# GEMM K-loops: s_setprio 0/1 toggle pair after every 8 MFMAs (was every 16) to give the loading partner more issue windows
# speedup vs baseline: 1.0048x; 1.0048x over previous
; #define PG8_STAGE(bufoff, gbase, voff) do { _Pragma("unroll") for (int _i = 0; _i < 2; ++_i) \
;         __builtin_amdgcn_global_load_lds((const unsigned*)((const char*)(gbase) + (voff)[_i]), (PG8_LAS unsigned*)(lds + (bufoff) + ldsw + _i * 8192), 16, 0, 0); } while (0)
; #define PG8_LDA(dst, b, h) do { _Pragma("unroll") for (int m = 0; m < 4; ++m) _Pragma("unroll") for (int k = 0; k < 2; ++k) dst[m][k] = *(const PG8_LAS bf16x8*)(lds + PG8_SA(b, h) + aoff + m * 2048 + k * 1024); } while (0)
; #define PG8_LDB(dst, b, h) do { _Pragma("unroll") for (int n = 0; n < 2; ++n) _Pragma("unroll") for (int k = 0; k < 2; ++k) dst[n][k] = *(const PG8_LAS bf16x8*)(lds + PG8_SB(b, h) + boff + n * 2048 + k * 1024); } while (0)
; #define PG8_MMA(ai, bj, At, Bt) do { __builtin_amdgcn_s_setprio(1); _Pragma("unroll") for (int m = 0; m < 4; ++m) _Pragma("unroll") for (int n = 0; n < 2; ++n) _Pragma("unroll") for (int k = 0; k < 2; ++k) \
;         acc[ai][bj][m][n] = __builtin_amdgcn_mfma_f32_16x16x32_bf16(Bt[n][k], At[m][k], acc[ai][bj][m][n], 0, 0, 0); __builtin_amdgcn_s_setprio(0); } while (0)
; #define PG8_WAIT_V(n) asm volatile("s_waitcnt vmcnt(" #n ")" ::: "memory")
; #define PG8_WAIT_L(n) asm volatile("s_waitcnt lgkmcnt(" #n ")" ::: "memory")
; template <class Epi, class Sched, bool ALIGN_EPI = false, bool SP2 = false>
; __device__ __forceinline__ void gemm_phase(PG8_LAS unsigned char* lds, const Gemm g, const Sched& S, const Epi& E) {
;     ...
;             const bool last = (t == nt - 2);
;             const char* a1 = cA + (size_t)(t + 1) * kstep;
;             const char* a2 = last ? nA : cA + (size_t)(t + 2) * kstep; const char* b2 = last ? nB : cB + (size_t)(t + 2) * kstep;
;             const char* a3 = a2 + kstep; const char* b3 = b2 + kstep;
;             if (last && has_next) S.a_ready(nxt);
;             if constexpr (SP2) {
;             PG8_LDB(B0, 0, 0); PG8_LDB(B1, 0, 1); PG8_SCHED; PG8_LDA(At, 0, 0); PG8_STAGE(PG8_SA(1, 1), a1 + hstep, voffA);
;             PG8_WAIT_V(8); PG8_WAIT_L(0); PG8_BAR; PG8_MMA(0, 0, At, B0); PG8_MMA(0, 1, At, B1); PG8_BAR; PG8_SCHED;
;             PG8_LDA(At, 0, 1); PG8_STAGE(PG8_SB(0, 0), b2, voffB); PG8_STAGE(PG8_SB(0, 1), b2 + hstep, voffB); PG8_STAGE(PG8_SA(0, 0), a2, voffA);
;             PG8_WAIT_V(8); PG8_WAIT_L(0); PG8_BAR; PG8_MMA(1, 0, At, B0); PG8_MMA(1, 1, At, B1); PG8_BAR; PG8_SCHED;
.LBB0_341:
	ds_read_b128 v[146:149], v159
	ds_read_b128 v[150:153], v159 offset:1024
	ds_read_b128 v[164:167], v159 offset:2048
	ds_read_b128 v[168:171], v159 offset:3072
	ds_read_b128 v[172:175], v160
	ds_read_b128 v[176:179], v160 offset:1024
	ds_read_b128 v[180:183], v160 offset:2048
	ds_read_b128 v[184:187], v160 offset:3072
	s_add_u32 s14, s10, 0xfff80080
	s_addc_u32 s15, s11, -1
	s_cmp_eq_u32 s48, 28
	s_cselect_b32 s87, s7, s15
	s_cselect_b32 s86, s9, s14
	s_cselect_b32 s15, s12, s47
	s_cselect_b32 s14, s45, s46
	v_lshl_add_u64 v[154:155], s[10:11], 0, v[136:137]
	s_add_i32 m0, s91, 0xc000
	ds_read_b128 v[188:191], v161
	ds_read_b128 v[192:195], v161 offset:1024
	ds_read_b128 v[196:199], v161 offset:2048
	ds_read_b128 v[200:203], v161 offset:3072
	ds_read_b128 v[204:207], v161 offset:4096
	ds_read_b128 v[208:211], v161 offset:5120
	ds_read_b128 v[212:215], v161 offset:6144
	ds_read_b128 v[216:219], v161 offset:7168
	global_load_lds_dwordx4 v[154:155], off
	v_lshl_add_u64 v[154:155], s[10:11], 0, v[138:139]
	s_add_i32 m0, s91, 0xe000
	s_nop 0
	global_load_lds_dwordx4 v[154:155], off
	s_waitcnt vmcnt(8)
	s_waitcnt lgkmcnt(0)
	s_barrier
	s_setprio 1
	s_waitcnt lgkmcnt(0)
	v_mfma_f32_16x16x32_bf16 v[124:127], v[146:149], v[188:191], v[124:127]
	v_mfma_f32_16x16x32_bf16 v[120:123], v[164:167], v[188:191], v[120:123]
	v_mfma_f32_16x16x32_bf16 v[108:111], v[146:149], v[196:199], v[108:111]
	v_mfma_f32_16x16x32_bf16 v[104:107], v[164:167], v[196:199], v[104:107]
	v_mfma_f32_16x16x32_bf16 v[92:95], v[146:149], v[204:207], v[92:95]
	v_mfma_f32_16x16x32_bf16 v[88:91], v[164:167], v[204:207], v[88:91]
	v_mfma_f32_16x16x32_bf16 v[76:79], v[146:149], v[212:215], v[76:79]
	v_mfma_f32_16x16x32_bf16 v[72:75], v[164:167], v[212:215], v[72:75]
	s_setprio 0
	s_setprio 1
	v_mfma_f32_16x16x32_bf16 v[124:127], v[150:153], v[192:195], v[124:127]
	v_mfma_f32_16x16x32_bf16 v[120:123], v[168:171], v[192:195], v[120:123]
	v_mfma_f32_16x16x32_bf16 v[108:111], v[150:153], v[200:203], v[108:111]
	v_mfma_f32_16x16x32_bf16 v[104:107], v[168:171], v[200:203], v[104:107]
	v_mfma_f32_16x16x32_bf16 v[92:95], v[150:153], v[208:211], v[92:95]
	v_mfma_f32_16x16x32_bf16 v[88:91], v[168:171], v[208:211], v[88:91]
	v_mfma_f32_16x16x32_bf16 v[76:79], v[150:153], v[216:219], v[76:79]
	v_mfma_f32_16x16x32_bf16 v[72:75], v[168:171], v[216:219], v[72:75]
	s_setprio 0
	s_setprio 1
	v_mfma_f32_16x16x32_bf16 v[116:119], v[172:175], v[188:191], v[116:119]
	v_mfma_f32_16x16x32_bf16 v[112:115], v[180:183], v[188:191], v[112:115]
	v_mfma_f32_16x16x32_bf16 v[100:103], v[172:175], v[196:199], v[100:103]
	v_mfma_f32_16x16x32_bf16 v[96:99], v[180:183], v[196:199], v[96:99]
	v_mfma_f32_16x16x32_bf16 v[84:87], v[172:175], v[204:207], v[84:87]
	v_mfma_f32_16x16x32_bf16 v[80:83], v[180:183], v[204:207], v[80:83]
	v_mfma_f32_16x16x32_bf16 v[68:71], v[172:175], v[212:215], v[68:71]
	v_mfma_f32_16x16x32_bf16 v[64:67], v[180:183], v[212:215], v[64:67]
	s_setprio 0
	s_setprio 1
	v_mfma_f32_16x16x32_bf16 v[116:119], v[176:179], v[192:195], v[116:119]
	v_mfma_f32_16x16x32_bf16 v[112:115], v[184:187], v[192:195], v[112:115]
	v_mfma_f32_16x16x32_bf16 v[100:103], v[176:179], v[200:203], v[100:103]
	v_mfma_f32_16x16x32_bf16 v[96:99], v[184:187], v[200:203], v[96:99]
	v_mfma_f32_16x16x32_bf16 v[84:87], v[176:179], v[208:211], v[84:87]
	v_mfma_f32_16x16x32_bf16 v[80:83], v[184:187], v[208:211], v[80:83]
	v_mfma_f32_16x16x32_bf16 v[68:71], v[176:179], v[216:219], v[68:71]
	v_mfma_f32_16x16x32_bf16 v[64:67], v[184:187], v[216:219], v[64:67]
	s_setprio 0
	s_barrier
	s_add_i32 s49, s42, s85
	v_lshl_add_u64 v[154:155], s[14:15], 0, v[130:131]
	s_mov_b32 m0, s49
	ds_read_b128 v[188:191], v161 offset:16384
	ds_read_b128 v[192:195], v161 offset:17408
	ds_read_b128 v[196:199], v161 offset:18432
	ds_read_b128 v[200:203], v161 offset:19456
	ds_read_b128 v[204:207], v161 offset:20480
	ds_read_b128 v[208:211], v161 offset:21504
	ds_read_b128 v[212:215], v161 offset:22528
	ds_read_b128 v[216:219], v161 offset:23552
	global_load_lds_dwordx4 v[154:155], off
	s_add_i32 m0, s49, 0x2000
	s_add_u32 s50, s14, 0x80000
	v_lshl_add_u64 v[220:221], s[14:15], 0, v[134:135]
	s_addc_u32 s51, s15, 0
	s_add_i32 s49, s43, s85
	global_load_lds_dwordx4 v[220:221], off
	v_lshl_add_u64 v[222:223], s[50:51], 0, v[130:131]
	s_mov_b32 m0, s49
	v_lshl_add_u64 v[224:225], s[86:87], 0, v[132:133]
	global_load_lds_dwordx4 v[222:223], off
	v_lshl_add_u64 v[222:223], s[50:51], 0, v[134:135]
	s_add_i32 m0, s49, 0x2000
	s_nop 0
	global_load_lds_dwordx4 v[222:223], off
	v_lshl_add_u64 v[222:223], s[86:87], 0, v[128:129]
	s_mov_b32 m0, s91
	s_nop 0
	global_load_lds_dwordx4 v[222:223], off
	s_mov_b32 m0, s93
	s_nop 0
	global_load_lds_dwordx4 v[224:225], off
	s_waitcnt vmcnt(8)
	s_waitcnt lgkmcnt(0)
	s_barrier
; #define PG8_STAGE(bufoff, gbase, voff) do { _Pragma("unroll") for (int _i = 0; _i < 2; ++_i) \
;         __builtin_amdgcn_global_load_lds((const unsigned*)((const char*)(gbase) + (voff)[_i]), (PG8_LAS unsigned*)(lds + (bufoff) + ldsw + _i * 8192), 16, 0, 0); } while (0)
; #define PG8_LDA(dst, b, h) do { _Pragma("unroll") for (int m = 0; m < 4; ++m) _Pragma("unroll") for (int k = 0; k < 2; ++k) dst[m][k] = *(const PG8_LAS bf16x8*)(lds + PG8_SA(b, h) + aoff + m * 2048 + k * 1024); } while (0)
; #define PG8_LDB(dst, b, h) do { _Pragma("unroll") for (int n = 0; n < 2; ++n) _Pragma("unroll") for (int k = 0; k < 2; ++k) dst[n][k] = *(const PG8_LAS bf16x8*)(lds + PG8_SB(b, h) + boff + n * 2048 + k * 1024); } while (0)
; #define PG8_MMA(ai, bj, At, Bt) do { __builtin_amdgcn_s_setprio(1); _Pragma("unroll") for (int m = 0; m < 4; ++m) _Pragma("unroll") for (int n = 0; n < 2; ++n) _Pragma("unroll") for (int k = 0; k < 2; ++k) \
;         acc[ai][bj][m][n] = __builtin_amdgcn_mfma_f32_16x16x32_bf16(Bt[n][k], At[m][k], acc[ai][bj][m][n], 0, 0, 0); __builtin_amdgcn_s_setprio(0); } while (0)
; #define PG8_WAIT_V(n) asm volatile("s_waitcnt vmcnt(" #n ")" ::: "memory")
; #define PG8_WAIT_L(n) asm volatile("s_waitcnt lgkmcnt(" #n ")" ::: "memory")
; #define PG8_BAR __builtin_amdgcn_s_barrier()
; #define PG8_SCHED __builtin_amdgcn_sched_barrier(0)
; template <class Epi, class Sched, bool ALIGN_EPI = false, bool SP2 = false>
; __device__ __forceinline__ void gemm_phase(PG8_LAS unsigned char* lds, const Gemm g, const Sched& S, const Epi& E) {
;     ...
;             PG8_WAIT_V(8); PG8_WAIT_L(0); PG8_BAR; PG8_MMA(1, 0, At, B0); PG8_MMA(1, 1, At, B1); PG8_BAR; PG8_SCHED;
;             PG8_LDB(B0, 1, 0); PG8_LDB(B1, 1, 1); PG8_SCHED; PG8_LDA(At, 1, 0); PG8_STAGE(PG8_SA(0, 1), a2 + hstep, voffA);
;             PG8_WAIT_V(8); PG8_WAIT_L(0); PG8_BAR; PG8_MMA(0, 0, At, B0); PG8_MMA(0, 1, At, B1); PG8_BAR; PG8_SCHED;
	s_setprio 1
	s_waitcnt lgkmcnt(0)
	v_mfma_f32_16x16x32_bf16 v[60:63], v[146:149], v[188:191], v[60:63]
	v_mfma_f32_16x16x32_bf16 v[56:59], v[164:167], v[188:191], v[56:59]
	v_mfma_f32_16x16x32_bf16 v[44:47], v[146:149], v[196:199], v[44:47]
	v_mfma_f32_16x16x32_bf16 v[40:43], v[164:167], v[196:199], v[40:43]
	v_mfma_f32_16x16x32_bf16 v[28:31], v[146:149], v[204:207], v[28:31]
	v_mfma_f32_16x16x32_bf16 v[24:27], v[164:167], v[204:207], v[24:27]
	v_mfma_f32_16x16x32_bf16 v[12:15], v[146:149], v[212:215], v[12:15]
	v_mfma_f32_16x16x32_bf16 v[8:11], v[164:167], v[212:215], v[8:11]
	s_setprio 0
	s_setprio 1
	v_mfma_f32_16x16x32_bf16 v[60:63], v[150:153], v[192:195], v[60:63]
	v_mfma_f32_16x16x32_bf16 v[56:59], v[168:171], v[192:195], v[56:59]
	v_mfma_f32_16x16x32_bf16 v[44:47], v[150:153], v[200:203], v[44:47]
	v_mfma_f32_16x16x32_bf16 v[40:43], v[168:171], v[200:203], v[40:43]
	v_mfma_f32_16x16x32_bf16 v[28:31], v[150:153], v[208:211], v[28:31]
	v_mfma_f32_16x16x32_bf16 v[24:27], v[168:171], v[208:211], v[24:27]
	v_mfma_f32_16x16x32_bf16 v[12:15], v[150:153], v[216:219], v[12:15]
	v_mfma_f32_16x16x32_bf16 v[8:11], v[168:171], v[216:219], v[8:11]
	s_setprio 0
	s_setprio 1
	v_mfma_f32_16x16x32_bf16 v[52:55], v[172:175], v[188:191], v[52:55]
	v_mfma_f32_16x16x32_bf16 v[48:51], v[180:183], v[188:191], v[48:51]
	v_mfma_f32_16x16x32_bf16 v[36:39], v[172:175], v[196:199], v[36:39]
	v_mfma_f32_16x16x32_bf16 v[32:35], v[180:183], v[196:199], v[32:35]
	v_mfma_f32_16x16x32_bf16 v[20:23], v[172:175], v[204:207], v[20:23]
	v_mfma_f32_16x16x32_bf16 v[16:19], v[180:183], v[204:207], v[16:19]
	v_mfma_f32_16x16x32_bf16 v[4:7], v[172:175], v[212:215], v[4:7]
	v_mfma_f32_16x16x32_bf16 v[0:3], v[180:183], v[212:215], v[0:3]
	s_setprio 0
	s_setprio 1
	v_mfma_f32_16x16x32_bf16 v[52:55], v[176:179], v[192:195], v[52:55]
	v_mfma_f32_16x16x32_bf16 v[48:51], v[184:187], v[192:195], v[48:51]
	v_mfma_f32_16x16x32_bf16 v[36:39], v[176:179], v[200:203], v[36:39]
	v_mfma_f32_16x16x32_bf16 v[32:35], v[184:187], v[200:203], v[32:35]
	v_mfma_f32_16x16x32_bf16 v[20:23], v[176:179], v[208:211], v[20:23]
	v_mfma_f32_16x16x32_bf16 v[16:19], v[184:187], v[208:211], v[16:19]
	v_mfma_f32_16x16x32_bf16 v[4:7], v[176:179], v[216:219], v[4:7]
	v_mfma_f32_16x16x32_bf16 v[0:3], v[184:187], v[216:219], v[0:3]
	s_setprio 0
	s_barrier
	s_add_i32 s49, 0, 0x18000
	v_add_u32_e32 v163, s49, v158
	s_add_i32 s69, 0, 0x1c000
	ds_read_b128 v[146:149], v163
	ds_read_b128 v[150:153], v163 offset:1024
	ds_read_b128 v[164:167], v163 offset:2048
	ds_read_b128 v[168:171], v163 offset:3072
	v_add_u32_e32 v163, s69, v158
	ds_read_b128 v[172:175], v163
	ds_read_b128 v[176:179], v163 offset:1024
	ds_read_b128 v[180:183], v163 offset:2048
	ds_read_b128 v[184:187], v163 offset:3072
	s_add_u32 s50, s86, 0x80000
	s_addc_u32 s51, s87, 0
	s_mov_b32 m0, s95
	v_lshl_add_u64 v[226:227], s[50:51], 0, v[128:129]
	ds_read_b128 v[188:191], v161 offset:32768
	ds_read_b128 v[192:195], v161 offset:33792
	ds_read_b128 v[196:199], v161 offset:34816
	ds_read_b128 v[200:203], v161 offset:35840
	ds_read_b128 v[204:207], v161 offset:36864
	ds_read_b128 v[208:211], v161 offset:37888
	ds_read_b128 v[212:215], v161 offset:38912
	ds_read_b128 v[216:219], v161 offset:39936
	global_load_lds_dwordx4 v[226:227], off
	v_lshl_add_u64 v[226:227], s[50:51], 0, v[132:133]
	s_mov_b32 m0, s97
	s_nop 0
	global_load_lds_dwordx4 v[226:227], off
	s_waitcnt vmcnt(8)
	s_waitcnt lgkmcnt(0)
	s_barrier
	s_setprio 1
	s_waitcnt lgkmcnt(0)
	v_mfma_f32_16x16x32_bf16 v[124:127], v[146:149], v[188:191], v[124:127]
	v_mfma_f32_16x16x32_bf16 v[120:123], v[164:167], v[188:191], v[120:123]
	v_mfma_f32_16x16x32_bf16 v[108:111], v[146:149], v[196:199], v[108:111]
	v_mfma_f32_16x16x32_bf16 v[104:107], v[164:167], v[196:199], v[104:107]
	v_mfma_f32_16x16x32_bf16 v[92:95], v[146:149], v[204:207], v[92:95]
	v_mfma_f32_16x16x32_bf16 v[88:91], v[164:167], v[204:207], v[88:91]
	v_mfma_f32_16x16x32_bf16 v[76:79], v[146:149], v[212:215], v[76:79]
	v_mfma_f32_16x16x32_bf16 v[72:75], v[164:167], v[212:215], v[72:75]
	s_setprio 0
	s_setprio 1
	v_mfma_f32_16x16x32_bf16 v[124:127], v[150:153], v[192:195], v[124:127]
	v_mfma_f32_16x16x32_bf16 v[120:123], v[168:171], v[192:195], v[120:123]
	v_mfma_f32_16x16x32_bf16 v[108:111], v[150:153], v[200:203], v[108:111]
	v_mfma_f32_16x16x32_bf16 v[104:107], v[168:171], v[200:203], v[104:107]
	v_mfma_f32_16x16x32_bf16 v[92:95], v[150:153], v[208:211], v[92:95]
	v_mfma_f32_16x16x32_bf16 v[88:91], v[168:171], v[208:211], v[88:91]
	v_mfma_f32_16x16x32_bf16 v[76:79], v[150:153], v[216:219], v[76:79]
	v_mfma_f32_16x16x32_bf16 v[72:75], v[168:171], v[216:219], v[72:75]
	s_setprio 0
	s_setprio 1
	v_mfma_f32_16x16x32_bf16 v[116:119], v[172:175], v[188:191], v[116:119]
	v_mfma_f32_16x16x32_bf16 v[112:115], v[180:183], v[188:191], v[112:115]
	v_mfma_f32_16x16x32_bf16 v[100:103], v[172:175], v[196:199], v[100:103]
	v_mfma_f32_16x16x32_bf16 v[96:99], v[180:183], v[196:199], v[96:99]
	v_mfma_f32_16x16x32_bf16 v[84:87], v[172:175], v[204:207], v[84:87]
	v_mfma_f32_16x16x32_bf16 v[80:83], v[180:183], v[204:207], v[80:83]
	v_mfma_f32_16x16x32_bf16 v[68:71], v[172:175], v[212:215], v[68:71]
	v_mfma_f32_16x16x32_bf16 v[64:67], v[180:183], v[212:215], v[64:67]
	s_setprio 0
	s_setprio 1
	v_mfma_f32_16x16x32_bf16 v[116:119], v[176:179], v[192:195], v[116:119]
	v_mfma_f32_16x16x32_bf16 v[112:115], v[184:187], v[192:195], v[112:115]
	v_mfma_f32_16x16x32_bf16 v[100:103], v[176:179], v[200:203], v[100:103]
	v_mfma_f32_16x16x32_bf16 v[96:99], v[184:187], v[200:203], v[96:99]
	v_mfma_f32_16x16x32_bf16 v[84:87], v[176:179], v[208:211], v[84:87]
	v_mfma_f32_16x16x32_bf16 v[80:83], v[184:187], v[208:211], v[80:83]
	v_mfma_f32_16x16x32_bf16 v[68:71], v[176:179], v[216:219], v[68:71]
	v_mfma_f32_16x16x32_bf16 v[64:67], v[184:187], v[216:219], v[64:67]
	s_setprio 0
	s_barrier
; #define PG8_STAGE(bufoff, gbase, voff) do { _Pragma("unroll") for (int _i = 0; _i < 2; ++_i) \
;         __builtin_amdgcn_global_load_lds((const unsigned*)((const char*)(gbase) + (voff)[_i]), (PG8_LAS unsigned*)(lds + (bufoff) + ldsw + _i * 8192), 16, 0, 0); } while (0)
; #define PG8_LDA(dst, b, h) do { _Pragma("unroll") for (int m = 0; m < 4; ++m) _Pragma("unroll") for (int k = 0; k < 2; ++k) dst[m][k] = *(const PG8_LAS bf16x8*)(lds + PG8_SA(b, h) + aoff + m * 2048 + k * 1024); } while (0)
; #define PG8_MMA(ai, bj, At, Bt) do { __builtin_amdgcn_s_setprio(1); _Pragma("unroll") for (int m = 0; m < 4; ++m) _Pragma("unroll") for (int n = 0; n < 2; ++n) _Pragma("unroll") for (int k = 0; k < 2; ++k) \
;         acc[ai][bj][m][n] = __builtin_amdgcn_mfma_f32_16x16x32_bf16(Bt[n][k], At[m][k], acc[ai][bj][m][n], 0, 0, 0); __builtin_amdgcn_s_setprio(0); } while (0)
; #define PG8_WAIT_V(n) asm volatile("s_waitcnt vmcnt(" #n ")" ::: "memory")
; #define PG8_WAIT_L(n) asm volatile("s_waitcnt lgkmcnt(" #n ")" ::: "memory")
; #define PG8_BAR __builtin_amdgcn_s_barrier()
; #define PG8_SCHED __builtin_amdgcn_sched_barrier(0)
; template <class Epi, class Sched, bool ALIGN_EPI = false, bool SP2 = false>
; __device__ __forceinline__ void gemm_phase(PG8_LAS unsigned char* lds, const Gemm g, const Sched& S, const Epi& E) {
;     ...
;             PG8_LDA(At, 1, 1); PG8_STAGE(PG8_SB(1, 0), b3, voffB); PG8_STAGE(PG8_SB(1, 1), b3 + hstep, voffB); PG8_STAGE(PG8_SA(1, 0), a3, voffA);
;             PG8_WAIT_V(8); PG8_WAIT_L(0); PG8_BAR; PG8_MMA(1, 0, At, B0); PG8_MMA(1, 1, At, B1); PG8_BAR; PG8_SCHED;
;     ...
;         if constexpr (ALIGN_EPI) { if (wr == 0) PG8_BAR; }
	s_add_i32 s49, s49, s85
	v_lshl_add_u64 v[154:155], v[154:155], 0, s[82:83]
	s_mov_b32 m0, s49
	ds_read_b128 v[188:191], v161 offset:49152
	ds_read_b128 v[192:195], v161 offset:50176
	ds_read_b128 v[196:199], v161 offset:51200
	ds_read_b128 v[200:203], v161 offset:52224
	ds_read_b128 v[204:207], v161 offset:53248
	ds_read_b128 v[208:211], v161 offset:54272
	ds_read_b128 v[212:215], v161 offset:55296
	ds_read_b128 v[216:219], v161 offset:56320
	global_load_lds_dwordx4 v[154:155], off
	s_add_i32 m0, s49, 0x2000
	s_add_u32 s14, s14, 0x80080
	v_lshl_add_u64 v[154:155], v[220:221], 0, s[82:83]
	s_addc_u32 s15, s15, 0
	s_add_i32 s49, s69, s85
	global_load_lds_dwordx4 v[154:155], off
	v_lshl_add_u64 v[154:155], s[14:15], 0, v[130:131]
	s_mov_b32 m0, s49
	s_nop 0
	global_load_lds_dwordx4 v[154:155], off
	v_lshl_add_u64 v[154:155], s[14:15], 0, v[134:135]
	s_add_i32 m0, s49, 0x2000
	s_nop 0
	global_load_lds_dwordx4 v[154:155], off
	v_lshl_add_u64 v[154:155], v[222:223], 0, s[82:83]
	s_mov_b32 m0, s39
	s_nop 0
	global_load_lds_dwordx4 v[154:155], off
	v_lshl_add_u64 v[154:155], v[224:225], 0, s[82:83]
	s_mov_b32 m0, s40
	s_nop 0
	global_load_lds_dwordx4 v[154:155], off
	s_waitcnt vmcnt(8)
	s_waitcnt lgkmcnt(0)
	s_barrier
	s_setprio 1
	s_waitcnt lgkmcnt(0)
	v_mfma_f32_16x16x32_bf16 v[60:63], v[146:149], v[188:191], v[60:63]
	v_mfma_f32_16x16x32_bf16 v[56:59], v[164:167], v[188:191], v[56:59]
	v_mfma_f32_16x16x32_bf16 v[44:47], v[146:149], v[196:199], v[44:47]
	v_mfma_f32_16x16x32_bf16 v[40:43], v[164:167], v[196:199], v[40:43]
	v_mfma_f32_16x16x32_bf16 v[28:31], v[146:149], v[204:207], v[28:31]
	v_mfma_f32_16x16x32_bf16 v[24:27], v[164:167], v[204:207], v[24:27]
	v_mfma_f32_16x16x32_bf16 v[12:15], v[146:149], v[212:215], v[12:15]
	v_mfma_f32_16x16x32_bf16 v[8:11], v[164:167], v[212:215], v[8:11]
	s_setprio 0
	s_setprio 1
	v_mfma_f32_16x16x32_bf16 v[60:63], v[150:153], v[192:195], v[60:63]
	v_mfma_f32_16x16x32_bf16 v[56:59], v[168:171], v[192:195], v[56:59]
	v_mfma_f32_16x16x32_bf16 v[44:47], v[150:153], v[200:203], v[44:47]
	v_mfma_f32_16x16x32_bf16 v[40:43], v[168:171], v[200:203], v[40:43]
	v_mfma_f32_16x16x32_bf16 v[28:31], v[150:153], v[208:211], v[28:31]
	v_mfma_f32_16x16x32_bf16 v[24:27], v[168:171], v[208:211], v[24:27]
	v_mfma_f32_16x16x32_bf16 v[12:15], v[150:153], v[216:219], v[12:15]
	v_mfma_f32_16x16x32_bf16 v[8:11], v[168:171], v[216:219], v[8:11]
	s_setprio 0
	s_setprio 1
	v_mfma_f32_16x16x32_bf16 v[52:55], v[172:175], v[188:191], v[52:55]
	v_mfma_f32_16x16x32_bf16 v[48:51], v[180:183], v[188:191], v[48:51]
	v_mfma_f32_16x16x32_bf16 v[36:39], v[172:175], v[196:199], v[36:39]
	v_mfma_f32_16x16x32_bf16 v[32:35], v[180:183], v[196:199], v[32:35]
	v_mfma_f32_16x16x32_bf16 v[20:23], v[172:175], v[204:207], v[20:23]
	v_mfma_f32_16x16x32_bf16 v[16:19], v[180:183], v[204:207], v[16:19]
	v_mfma_f32_16x16x32_bf16 v[4:7], v[172:175], v[212:215], v[4:7]
	v_mfma_f32_16x16x32_bf16 v[0:3], v[180:183], v[212:215], v[0:3]
	s_setprio 0
	s_setprio 1
	v_mfma_f32_16x16x32_bf16 v[52:55], v[176:179], v[192:195], v[52:55]
	v_mfma_f32_16x16x32_bf16 v[48:51], v[184:187], v[192:195], v[48:51]
	v_mfma_f32_16x16x32_bf16 v[36:39], v[176:179], v[200:203], v[36:39]
	v_mfma_f32_16x16x32_bf16 v[32:35], v[184:187], v[200:203], v[32:35]
	v_mfma_f32_16x16x32_bf16 v[20:23], v[176:179], v[208:211], v[20:23]
	v_mfma_f32_16x16x32_bf16 v[16:19], v[184:187], v[208:211], v[16:19]
	v_mfma_f32_16x16x32_bf16 v[4:7], v[176:179], v[216:219], v[4:7]
	v_mfma_f32_16x16x32_bf16 v[0:3], v[184:187], v[216:219], v[0:3]
	s_setprio 0
	s_barrier
	s_add_i32 s48, s48, 2
	s_add_u32 s10, s10, 0x100
	s_addc_u32 s11, s11, 0
	s_add_u32 s46, s46, 0x100
	s_addc_u32 s47, s47, 0
	s_cmp_gt_u32 s48, 29
	s_cbranch_scc0 .LBB0_341
	s_and_b64 vcc, exec, s[88:89]
	s_cbranch_vccz .LBB0_344
	s_barrier

; #define PG8_STAGE(bufoff, gbase, voff) do { _Pragma("unroll") for (int _i = 0; _i < 2; ++_i) \
;         __builtin_amdgcn_global_load_lds((const unsigned*)((const char*)(gbase) + (voff)[_i]), (PG8_LAS unsigned*)(lds + (bufoff) + ldsw + _i * 8192), 16, 0, 0); } while (0)
; #define PG8_LDA(dst, b, h) do { _Pragma("unroll") for (int m = 0; m < 4; ++m) _Pragma("unroll") for (int k = 0; k < 2; ++k) dst[m][k] = *(const PG8_LAS bf16x8*)(lds + PG8_SA(b, h) + aoff + m * 2048 + k * 1024); } while (0)
; #define PG8_LDB(dst, b, h) do { _Pragma("unroll") for (int n = 0; n < 2; ++n) _Pragma("unroll") for (int k = 0; k < 2; ++k) dst[n][k] = *(const PG8_LAS bf16x8*)(lds + PG8_SB(b, h) + boff + n * 2048 + k * 1024); } while (0)
; #define PG8_MMA(ai, bj, At, Bt) do { __builtin_amdgcn_s_setprio(1); _Pragma("unroll") for (int m = 0; m < 4; ++m) _Pragma("unroll") for (int n = 0; n < 2; ++n) _Pragma("unroll") for (int k = 0; k < 2; ++k) \
;         acc[ai][bj][m][n] = __builtin_amdgcn_mfma_f32_16x16x32_bf16(Bt[n][k], At[m][k], acc[ai][bj][m][n], 0, 0, 0); __builtin_amdgcn_s_setprio(0); } while (0)
; #define PG8_WAIT_V(n) asm volatile("s_waitcnt vmcnt(" #n ")" ::: "memory")
; #define PG8_WAIT_L(n) asm volatile("s_waitcnt lgkmcnt(" #n ")" ::: "memory")
; template <class Epi, class Sched, bool ALIGN_EPI = false, bool SP2 = false>
; __device__ __forceinline__ void gemm_phase(PG8_LAS unsigned char* lds, const Gemm g, const Sched& S, const Epi& E) {
;     ...
;             const bool last = (t == nt - 2);
;             const char* a1 = cA + (size_t)(t + 1) * kstep;
;             const char* a2 = last ? nA : cA + (size_t)(t + 2) * kstep; const char* b2 = last ? nB : cB + (size_t)(t + 2) * kstep;
;             const char* a3 = a2 + kstep; const char* b3 = b2 + kstep;
;             if (last && has_next) S.a_ready(nxt);
;             if constexpr (SP2) {
;             PG8_LDB(B0, 0, 0); PG8_LDB(B1, 0, 1); PG8_SCHED; PG8_LDA(At, 0, 0); PG8_STAGE(PG8_SA(1, 1), a1 + hstep, voffA);
;             PG8_WAIT_V(8); PG8_WAIT_L(0); PG8_BAR; PG8_MMA(0, 0, At, B0); PG8_MMA(0, 1, At, B1); PG8_BAR; PG8_SCHED;
;             PG8_LDA(At, 0, 1); PG8_STAGE(PG8_SB(0, 0), b2, voffB); PG8_STAGE(PG8_SB(0, 1), b2 + hstep, voffB); PG8_STAGE(PG8_SA(0, 0), a2, voffA);
;             PG8_WAIT_V(8); PG8_WAIT_L(0); PG8_BAR; PG8_MMA(1, 0, At, B0); PG8_MMA(1, 1, At, B1); PG8_BAR; PG8_SCHED;
.LBB0_919:
	ds_read_b128 v[128:131], v187
	ds_read_b128 v[132:135], v187 offset:1024
	ds_read_b128 v[154:157], v187 offset:2048
	ds_read_b128 v[158:161], v187 offset:3072
	ds_read_b128 v[162:165], v188
	ds_read_b128 v[166:169], v188 offset:1024
	ds_read_b128 v[170:173], v188 offset:2048
	ds_read_b128 v[174:177], v188 offset:3072
	s_add_i32 s46, s6, 2
	s_add_u32 s47, s0, 0x80
	s_addc_u32 s7, s1, 0
	s_cmp_eq_u32 s93, s6
	s_cselect_b32 s6, s16, s47
	s_cselect_b32 s7, s17, s7
	s_cselect_b32 s49, s19, s45
	s_cselect_b32 s48, s18, s44
	v_lshl_add_u64 v[182:183], s[0:1], 0, v[146:147]
	s_add_i32 m0, s85, 0xc000
	ds_read_b128 v[178:181], v189
	ds_read_b128 v[192:195], v189 offset:1024
	ds_read_b128 v[196:199], v189 offset:2048
	ds_read_b128 v[200:203], v189 offset:3072
	ds_read_b128 v[204:207], v189 offset:4096
	ds_read_b128 v[208:211], v189 offset:5120
	ds_read_b128 v[212:215], v189 offset:6144
	ds_read_b128 v[216:219], v189 offset:7168
	global_load_lds_dwordx4 v[182:183], off
	v_lshl_add_u64 v[182:183], s[0:1], 0, v[148:149]
	s_add_i32 m0, s85, 0xe000
	s_nop 0
	global_load_lds_dwordx4 v[182:183], off
	s_waitcnt vmcnt(8)
	s_waitcnt lgkmcnt(0)
	s_barrier
	s_setprio 1
	s_waitcnt lgkmcnt(0)
	v_mfma_f32_16x16x32_bf16 v[120:123], v[128:131], v[178:181], v[120:123]
	v_mfma_f32_16x16x32_bf16 v[124:127], v[154:157], v[178:181], v[124:127]
	v_mfma_f32_16x16x32_bf16 v[108:111], v[128:131], v[196:199], v[108:111]
	v_mfma_f32_16x16x32_bf16 v[104:107], v[154:157], v[196:199], v[104:107]
	v_mfma_f32_16x16x32_bf16 v[92:95], v[128:131], v[204:207], v[92:95]
	v_mfma_f32_16x16x32_bf16 v[88:91], v[154:157], v[204:207], v[88:91]
	v_mfma_f32_16x16x32_bf16 v[76:79], v[128:131], v[212:215], v[76:79]
	v_mfma_f32_16x16x32_bf16 v[72:75], v[154:157], v[212:215], v[72:75]
	s_setprio 0
	s_setprio 1
	v_mfma_f32_16x16x32_bf16 v[120:123], v[132:135], v[192:195], v[120:123]
	v_mfma_f32_16x16x32_bf16 v[124:127], v[158:161], v[192:195], v[124:127]
	v_mfma_f32_16x16x32_bf16 v[108:111], v[132:135], v[200:203], v[108:111]
	v_mfma_f32_16x16x32_bf16 v[104:107], v[158:161], v[200:203], v[104:107]
	v_mfma_f32_16x16x32_bf16 v[92:95], v[132:135], v[208:211], v[92:95]
	v_mfma_f32_16x16x32_bf16 v[88:91], v[158:161], v[208:211], v[88:91]
	v_mfma_f32_16x16x32_bf16 v[76:79], v[132:135], v[216:219], v[76:79]
	v_mfma_f32_16x16x32_bf16 v[72:75], v[158:161], v[216:219], v[72:75]
	s_setprio 0
	s_setprio 1
	v_mfma_f32_16x16x32_bf16 v[116:119], v[162:165], v[178:181], v[116:119]
	v_mfma_f32_16x16x32_bf16 v[112:115], v[170:173], v[178:181], v[112:115]
	v_mfma_f32_16x16x32_bf16 v[100:103], v[162:165], v[196:199], v[100:103]
	v_mfma_f32_16x16x32_bf16 v[96:99], v[170:173], v[196:199], v[96:99]
	v_mfma_f32_16x16x32_bf16 v[84:87], v[162:165], v[204:207], v[84:87]
	v_mfma_f32_16x16x32_bf16 v[80:83], v[170:173], v[204:207], v[80:83]
	v_mfma_f32_16x16x32_bf16 v[68:71], v[162:165], v[212:215], v[68:71]
	v_mfma_f32_16x16x32_bf16 v[64:67], v[170:173], v[212:215], v[64:67]
	s_setprio 0
	s_setprio 1
	v_mfma_f32_16x16x32_bf16 v[116:119], v[166:169], v[192:195], v[116:119]
	v_mfma_f32_16x16x32_bf16 v[112:115], v[174:177], v[192:195], v[112:115]
	v_mfma_f32_16x16x32_bf16 v[100:103], v[166:169], v[200:203], v[100:103]
	v_mfma_f32_16x16x32_bf16 v[96:99], v[174:177], v[200:203], v[96:99]
	v_mfma_f32_16x16x32_bf16 v[84:87], v[166:169], v[208:211], v[84:87]
	v_mfma_f32_16x16x32_bf16 v[80:83], v[174:177], v[208:211], v[80:83]
	v_mfma_f32_16x16x32_bf16 v[68:71], v[166:169], v[216:219], v[68:71]
	v_mfma_f32_16x16x32_bf16 v[64:67], v[174:177], v[216:219], v[64:67]
	s_setprio 0
	s_barrier
	s_add_i32 s47, s3, s84
	v_lshl_add_u64 v[182:183], s[48:49], 0, v[138:139]
	s_mov_b32 m0, s47
	ds_read_b128 v[178:181], v189 offset:16384
	ds_read_b128 v[192:195], v189 offset:17408
	ds_read_b128 v[196:199], v189 offset:18432
	ds_read_b128 v[200:203], v189 offset:19456
	ds_read_b128 v[204:207], v189 offset:20480
	ds_read_b128 v[208:211], v189 offset:21504
	ds_read_b128 v[212:215], v189 offset:22528
	ds_read_b128 v[216:219], v189 offset:23552
	global_load_lds_dwordx4 v[182:183], off
	s_add_i32 m0, s47, 0x2000
	v_lshl_add_u64 v[220:221], s[48:49], 0, v[142:143]
	s_add_u32 s48, s48, s10
	s_addc_u32 s49, s49, s11
	s_add_i32 s47, s8, s84
	global_load_lds_dwordx4 v[220:221], off
	v_lshl_add_u64 v[222:223], s[48:49], 0, v[138:139]
	s_mov_b32 m0, s47
	v_lshl_add_u64 v[224:225], s[48:49], 0, v[142:143]
	global_load_lds_dwordx4 v[222:223], off
	s_add_i32 m0, s47, 0x2000
	v_lshl_add_u64 v[226:227], s[6:7], 0, v[136:137]
	global_load_lds_dwordx4 v[224:225], off
	s_mov_b32 m0, s85
	v_lshl_add_u64 v[228:229], s[6:7], 0, v[140:141]
	global_load_lds_dwordx4 v[226:227], off
	s_mov_b32 m0, s86
	s_nop 0
	global_load_lds_dwordx4 v[228:229], off
	s_waitcnt vmcnt(8)
	s_waitcnt lgkmcnt(0)
	s_barrier
; #define PG8_STAGE(bufoff, gbase, voff) do { _Pragma("unroll") for (int _i = 0; _i < 2; ++_i) \
;         __builtin_amdgcn_global_load_lds((const unsigned*)((const char*)(gbase) + (voff)[_i]), (PG8_LAS unsigned*)(lds + (bufoff) + ldsw + _i * 8192), 16, 0, 0); } while (0)
; #define PG8_LDA(dst, b, h) do { _Pragma("unroll") for (int m = 0; m < 4; ++m) _Pragma("unroll") for (int k = 0; k < 2; ++k) dst[m][k] = *(const PG8_LAS bf16x8*)(lds + PG8_SA(b, h) + aoff + m * 2048 + k * 1024); } while (0)
; #define PG8_LDB(dst, b, h) do { _Pragma("unroll") for (int n = 0; n < 2; ++n) _Pragma("unroll") for (int k = 0; k < 2; ++k) dst[n][k] = *(const PG8_LAS bf16x8*)(lds + PG8_SB(b, h) + boff + n * 2048 + k * 1024); } while (0)
; #define PG8_MMA(ai, bj, At, Bt) do { __builtin_amdgcn_s_setprio(1); _Pragma("unroll") for (int m = 0; m < 4; ++m) _Pragma("unroll") for (int n = 0; n < 2; ++n) _Pragma("unroll") for (int k = 0; k < 2; ++k) \
;         acc[ai][bj][m][n] = __builtin_amdgcn_mfma_f32_16x16x32_bf16(Bt[n][k], At[m][k], acc[ai][bj][m][n], 0, 0, 0); __builtin_amdgcn_s_setprio(0); } while (0)
; #define PG8_WAIT_V(n) asm volatile("s_waitcnt vmcnt(" #n ")" ::: "memory")
; #define PG8_WAIT_L(n) asm volatile("s_waitcnt lgkmcnt(" #n ")" ::: "memory")
; #define PG8_BAR __builtin_amdgcn_s_barrier()
; #define PG8_SCHED __builtin_amdgcn_sched_barrier(0)
; template <class Epi, class Sched, bool ALIGN_EPI = false, bool SP2 = false>
; __device__ __forceinline__ void gemm_phase(PG8_LAS unsigned char* lds, const Gemm g, const Sched& S, const Epi& E) {
;     ...
;             PG8_WAIT_V(8); PG8_WAIT_L(0); PG8_BAR; PG8_MMA(1, 0, At, B0); PG8_MMA(1, 1, At, B1); PG8_BAR; PG8_SCHED;
;             PG8_LDB(B0, 1, 0); PG8_LDB(B1, 1, 1); PG8_SCHED; PG8_LDA(At, 1, 0); PG8_STAGE(PG8_SA(0, 1), a2 + hstep, voffA);
;             PG8_WAIT_V(8); PG8_WAIT_L(0); PG8_BAR; PG8_MMA(0, 0, At, B0); PG8_MMA(0, 1, At, B1); PG8_BAR; PG8_SCHED;
	s_setprio 1
	s_waitcnt lgkmcnt(0)
	v_mfma_f32_16x16x32_bf16 v[60:63], v[128:131], v[178:181], v[60:63]
	v_mfma_f32_16x16x32_bf16 v[56:59], v[154:157], v[178:181], v[56:59]
	v_mfma_f32_16x16x32_bf16 v[44:47], v[128:131], v[196:199], v[44:47]
	v_mfma_f32_16x16x32_bf16 v[40:43], v[154:157], v[196:199], v[40:43]
	v_mfma_f32_16x16x32_bf16 v[28:31], v[128:131], v[204:207], v[28:31]
	v_mfma_f32_16x16x32_bf16 v[24:27], v[154:157], v[204:207], v[24:27]
	v_mfma_f32_16x16x32_bf16 v[12:15], v[128:131], v[212:215], v[12:15]
	v_mfma_f32_16x16x32_bf16 v[8:11], v[154:157], v[212:215], v[8:11]
	s_setprio 0
	s_setprio 1
	v_mfma_f32_16x16x32_bf16 v[60:63], v[132:135], v[192:195], v[60:63]
	v_mfma_f32_16x16x32_bf16 v[56:59], v[158:161], v[192:195], v[56:59]
	v_mfma_f32_16x16x32_bf16 v[44:47], v[132:135], v[200:203], v[44:47]
	v_mfma_f32_16x16x32_bf16 v[40:43], v[158:161], v[200:203], v[40:43]
	v_mfma_f32_16x16x32_bf16 v[28:31], v[132:135], v[208:211], v[28:31]
	v_mfma_f32_16x16x32_bf16 v[24:27], v[158:161], v[208:211], v[24:27]
	v_mfma_f32_16x16x32_bf16 v[12:15], v[132:135], v[216:219], v[12:15]
	v_mfma_f32_16x16x32_bf16 v[8:11], v[158:161], v[216:219], v[8:11]
	s_setprio 0
	s_setprio 1
	v_mfma_f32_16x16x32_bf16 v[52:55], v[162:165], v[178:181], v[52:55]
	v_mfma_f32_16x16x32_bf16 v[48:51], v[170:173], v[178:181], v[48:51]
	v_mfma_f32_16x16x32_bf16 v[36:39], v[162:165], v[196:199], v[36:39]
	v_mfma_f32_16x16x32_bf16 v[32:35], v[170:173], v[196:199], v[32:35]
	v_mfma_f32_16x16x32_bf16 v[20:23], v[162:165], v[204:207], v[20:23]
	v_mfma_f32_16x16x32_bf16 v[16:19], v[170:173], v[204:207], v[16:19]
	v_mfma_f32_16x16x32_bf16 v[4:7], v[162:165], v[212:215], v[4:7]
	v_mfma_f32_16x16x32_bf16 v[0:3], v[170:173], v[212:215], v[0:3]
	s_setprio 0
	s_setprio 1
	v_mfma_f32_16x16x32_bf16 v[52:55], v[166:169], v[192:195], v[52:55]
	v_mfma_f32_16x16x32_bf16 v[48:51], v[174:177], v[192:195], v[48:51]
	v_mfma_f32_16x16x32_bf16 v[36:39], v[166:169], v[200:203], v[36:39]
	v_mfma_f32_16x16x32_bf16 v[32:35], v[174:177], v[200:203], v[32:35]
	v_mfma_f32_16x16x32_bf16 v[20:23], v[166:169], v[208:211], v[20:23]
	v_mfma_f32_16x16x32_bf16 v[16:19], v[174:177], v[208:211], v[16:19]
	v_mfma_f32_16x16x32_bf16 v[4:7], v[166:169], v[216:219], v[4:7]
	v_mfma_f32_16x16x32_bf16 v[0:3], v[174:177], v[216:219], v[0:3]
	s_setprio 0
	s_barrier
	s_add_i32 s47, 0, 0x18000
	s_add_i32 s48, 0, 0x1c000
	v_add_u32_e32 v158, s47, v186
	v_add_u32_e32 v174, s48, v186
	ds_read_b128 v[128:131], v158
	ds_read_b128 v[132:135], v158 offset:1024
	ds_read_b128 v[154:157], v158 offset:2048
	ds_read_b128 v[158:161], v158 offset:3072
	ds_read_b128 v[162:165], v174
	ds_read_b128 v[166:169], v174 offset:1024
	ds_read_b128 v[170:173], v174 offset:2048
	ds_read_b128 v[174:177], v174 offset:3072
	s_add_u32 s6, s6, s10
	s_addc_u32 s7, s7, s11
	s_mov_b32 m0, s87
	v_lshl_add_u64 v[230:231], s[6:7], 0, v[136:137]
	ds_read_b128 v[178:181], v189 offset:32768
	ds_read_b128 v[192:195], v189 offset:33792
	ds_read_b128 v[196:199], v189 offset:34816
	ds_read_b128 v[200:203], v189 offset:35840
	ds_read_b128 v[204:207], v189 offset:36864
	ds_read_b128 v[208:211], v189 offset:37888
	ds_read_b128 v[212:215], v189 offset:38912
	ds_read_b128 v[216:219], v189 offset:39936
	global_load_lds_dwordx4 v[230:231], off
	v_lshl_add_u64 v[230:231], s[6:7], 0, v[140:141]
	s_mov_b32 m0, s88
	s_nop 0
	global_load_lds_dwordx4 v[230:231], off
	s_waitcnt vmcnt(8)
	s_waitcnt lgkmcnt(0)
	s_barrier
	s_setprio 1
	s_waitcnt lgkmcnt(0)
	v_mfma_f32_16x16x32_bf16 v[120:123], v[128:131], v[178:181], v[120:123]
	v_mfma_f32_16x16x32_bf16 v[124:127], v[154:157], v[178:181], v[124:127]
	v_mfma_f32_16x16x32_bf16 v[108:111], v[128:131], v[196:199], v[108:111]
	v_mfma_f32_16x16x32_bf16 v[104:107], v[154:157], v[196:199], v[104:107]
	v_mfma_f32_16x16x32_bf16 v[92:95], v[128:131], v[204:207], v[92:95]
	v_mfma_f32_16x16x32_bf16 v[88:91], v[154:157], v[204:207], v[88:91]
	v_mfma_f32_16x16x32_bf16 v[76:79], v[128:131], v[212:215], v[76:79]
	v_mfma_f32_16x16x32_bf16 v[72:75], v[154:157], v[212:215], v[72:75]
	s_setprio 0
	s_setprio 1
	v_mfma_f32_16x16x32_bf16 v[120:123], v[132:135], v[192:195], v[120:123]
	v_mfma_f32_16x16x32_bf16 v[124:127], v[158:161], v[192:195], v[124:127]
	v_mfma_f32_16x16x32_bf16 v[108:111], v[132:135], v[200:203], v[108:111]
	v_mfma_f32_16x16x32_bf16 v[104:107], v[158:161], v[200:203], v[104:107]
	v_mfma_f32_16x16x32_bf16 v[92:95], v[132:135], v[208:211], v[92:95]
	v_mfma_f32_16x16x32_bf16 v[88:91], v[158:161], v[208:211], v[88:91]
	v_mfma_f32_16x16x32_bf16 v[76:79], v[132:135], v[216:219], v[76:79]
	v_mfma_f32_16x16x32_bf16 v[72:75], v[158:161], v[216:219], v[72:75]
	s_setprio 0
	s_setprio 1
	v_mfma_f32_16x16x32_bf16 v[116:119], v[162:165], v[178:181], v[116:119]
	v_mfma_f32_16x16x32_bf16 v[112:115], v[170:173], v[178:181], v[112:115]
	v_mfma_f32_16x16x32_bf16 v[100:103], v[162:165], v[196:199], v[100:103]
	v_mfma_f32_16x16x32_bf16 v[96:99], v[170:173], v[196:199], v[96:99]
	v_mfma_f32_16x16x32_bf16 v[84:87], v[162:165], v[204:207], v[84:87]
	v_mfma_f32_16x16x32_bf16 v[80:83], v[170:173], v[204:207], v[80:83]
	v_mfma_f32_16x16x32_bf16 v[68:71], v[162:165], v[212:215], v[68:71]
	v_mfma_f32_16x16x32_bf16 v[64:67], v[170:173], v[212:215], v[64:67]
	s_setprio 0
	s_setprio 1
	v_mfma_f32_16x16x32_bf16 v[116:119], v[166:169], v[192:195], v[116:119]
	v_mfma_f32_16x16x32_bf16 v[112:115], v[174:177], v[192:195], v[112:115]
	v_mfma_f32_16x16x32_bf16 v[100:103], v[166:169], v[200:203], v[100:103]
	v_mfma_f32_16x16x32_bf16 v[96:99], v[174:177], v[200:203], v[96:99]
	v_mfma_f32_16x16x32_bf16 v[84:87], v[166:169], v[208:211], v[84:87]
	v_mfma_f32_16x16x32_bf16 v[80:83], v[174:177], v[208:211], v[80:83]
	v_mfma_f32_16x16x32_bf16 v[68:71], v[166:169], v[216:219], v[68:71]
	v_mfma_f32_16x16x32_bf16 v[64:67], v[174:177], v[216:219], v[64:67]
	s_setprio 0
	s_barrier
; #define PG8_STAGE(bufoff, gbase, voff) do { _Pragma("unroll") for (int _i = 0; _i < 2; ++_i) \
;         __builtin_amdgcn_global_load_lds((const unsigned*)((const char*)(gbase) + (voff)[_i]), (PG8_LAS unsigned*)(lds + (bufoff) + ldsw + _i * 8192), 16, 0, 0); } while (0)
; #define PG8_LDA(dst, b, h) do { _Pragma("unroll") for (int m = 0; m < 4; ++m) _Pragma("unroll") for (int k = 0; k < 2; ++k) dst[m][k] = *(const PG8_LAS bf16x8*)(lds + PG8_SA(b, h) + aoff + m * 2048 + k * 1024); } while (0)
; #define PG8_MMA(ai, bj, At, Bt) do { __builtin_amdgcn_s_setprio(1); _Pragma("unroll") for (int m = 0; m < 4; ++m) _Pragma("unroll") for (int n = 0; n < 2; ++n) _Pragma("unroll") for (int k = 0; k < 2; ++k) \
;         acc[ai][bj][m][n] = __builtin_amdgcn_mfma_f32_16x16x32_bf16(Bt[n][k], At[m][k], acc[ai][bj][m][n], 0, 0, 0); __builtin_amdgcn_s_setprio(0); } while (0)
; #define PG8_WAIT_V(n) asm volatile("s_waitcnt vmcnt(" #n ")" ::: "memory")
; #define PG8_WAIT_L(n) asm volatile("s_waitcnt lgkmcnt(" #n ")" ::: "memory")
; #define PG8_BAR __builtin_amdgcn_s_barrier()
; #define PG8_SCHED __builtin_amdgcn_sched_barrier(0)
; template <class Epi, class Sched, bool ALIGN_EPI = false, bool SP2 = false>
; __device__ __forceinline__ void gemm_phase(PG8_LAS unsigned char* lds, const Gemm g, const Sched& S, const Epi& E) {
;     ...
;             PG8_LDA(At, 1, 1); PG8_STAGE(PG8_SB(1, 0), b3, voffB); PG8_STAGE(PG8_SB(1, 1), b3 + hstep, voffB); PG8_STAGE(PG8_SA(1, 0), a3, voffA);
;             PG8_WAIT_V(8); PG8_WAIT_L(0); PG8_BAR; PG8_MMA(1, 0, At, B0); PG8_MMA(1, 1, At, B1); PG8_BAR; PG8_SCHED;
	s_add_i32 s6, s47, s84
	v_lshl_add_u64 v[182:183], v[182:183], 0, s[64:65]
	s_mov_b32 m0, s6
	ds_read_b128 v[178:181], v189 offset:49152
	ds_read_b128 v[192:195], v189 offset:50176
	ds_read_b128 v[196:199], v189 offset:51200
	ds_read_b128 v[200:203], v189 offset:52224
	ds_read_b128 v[204:207], v189 offset:53248
	ds_read_b128 v[208:211], v189 offset:54272
	ds_read_b128 v[212:215], v189 offset:55296
	ds_read_b128 v[216:219], v189 offset:56320
	global_load_lds_dwordx4 v[182:183], off
	v_lshl_add_u64 v[182:183], v[220:221], 0, s[64:65]
	s_add_i32 m0, s6, 0x2000
	s_add_i32 s6, s48, s84
	global_load_lds_dwordx4 v[182:183], off
	v_lshl_add_u64 v[182:183], v[222:223], 0, s[64:65]
	s_mov_b32 m0, s6
	s_nop 0
	global_load_lds_dwordx4 v[182:183], off
	v_lshl_add_u64 v[182:183], v[224:225], 0, s[64:65]
	s_add_i32 m0, s6, 0x2000
	s_nop 0
	global_load_lds_dwordx4 v[182:183], off
	v_lshl_add_u64 v[182:183], v[226:227], 0, s[64:65]
	s_mov_b32 m0, s96
	s_nop 0
	global_load_lds_dwordx4 v[182:183], off
	v_lshl_add_u64 v[182:183], v[228:229], 0, s[64:65]
	s_mov_b32 m0, s97
	s_nop 0
	global_load_lds_dwordx4 v[182:183], off
	s_waitcnt vmcnt(8)
	s_waitcnt lgkmcnt(0)
	s_barrier
	s_setprio 1
	s_waitcnt lgkmcnt(0)
	v_mfma_f32_16x16x32_bf16 v[60:63], v[128:131], v[178:181], v[60:63]
	v_mfma_f32_16x16x32_bf16 v[56:59], v[154:157], v[178:181], v[56:59]
	v_mfma_f32_16x16x32_bf16 v[44:47], v[128:131], v[196:199], v[44:47]
	v_mfma_f32_16x16x32_bf16 v[40:43], v[154:157], v[196:199], v[40:43]
	v_mfma_f32_16x16x32_bf16 v[28:31], v[128:131], v[204:207], v[28:31]
	v_mfma_f32_16x16x32_bf16 v[24:27], v[154:157], v[204:207], v[24:27]
	v_mfma_f32_16x16x32_bf16 v[12:15], v[128:131], v[212:215], v[12:15]
	v_mfma_f32_16x16x32_bf16 v[8:11], v[154:157], v[212:215], v[8:11]
	s_setprio 0
	s_setprio 1
	v_mfma_f32_16x16x32_bf16 v[60:63], v[132:135], v[192:195], v[60:63]
	v_mfma_f32_16x16x32_bf16 v[56:59], v[158:161], v[192:195], v[56:59]
	v_mfma_f32_16x16x32_bf16 v[44:47], v[132:135], v[200:203], v[44:47]
	v_mfma_f32_16x16x32_bf16 v[40:43], v[158:161], v[200:203], v[40:43]
	v_mfma_f32_16x16x32_bf16 v[28:31], v[132:135], v[208:211], v[28:31]
	v_mfma_f32_16x16x32_bf16 v[24:27], v[158:161], v[208:211], v[24:27]
	v_mfma_f32_16x16x32_bf16 v[12:15], v[132:135], v[216:219], v[12:15]
	v_mfma_f32_16x16x32_bf16 v[8:11], v[158:161], v[216:219], v[8:11]
	s_setprio 0
	s_setprio 1
	v_mfma_f32_16x16x32_bf16 v[52:55], v[162:165], v[178:181], v[52:55]
	v_mfma_f32_16x16x32_bf16 v[48:51], v[170:173], v[178:181], v[48:51]
	v_mfma_f32_16x16x32_bf16 v[36:39], v[162:165], v[196:199], v[36:39]
	v_mfma_f32_16x16x32_bf16 v[32:35], v[170:173], v[196:199], v[32:35]
	v_mfma_f32_16x16x32_bf16 v[20:23], v[162:165], v[204:207], v[20:23]
	v_mfma_f32_16x16x32_bf16 v[16:19], v[170:173], v[204:207], v[16:19]
	v_mfma_f32_16x16x32_bf16 v[4:7], v[162:165], v[212:215], v[4:7]
	v_mfma_f32_16x16x32_bf16 v[0:3], v[170:173], v[212:215], v[0:3]
	s_setprio 0
	s_setprio 1
	v_mfma_f32_16x16x32_bf16 v[52:55], v[166:169], v[192:195], v[52:55]
	v_mfma_f32_16x16x32_bf16 v[48:51], v[174:177], v[192:195], v[48:51]
	v_mfma_f32_16x16x32_bf16 v[36:39], v[166:169], v[200:203], v[36:39]
	v_mfma_f32_16x16x32_bf16 v[32:35], v[174:177], v[200:203], v[32:35]
	v_mfma_f32_16x16x32_bf16 v[20:23], v[166:169], v[208:211], v[20:23]
	v_mfma_f32_16x16x32_bf16 v[16:19], v[174:177], v[208:211], v[16:19]
	v_mfma_f32_16x16x32_bf16 v[4:7], v[166:169], v[216:219], v[4:7]
	v_mfma_f32_16x16x32_bf16 v[0:3], v[174:177], v[216:219], v[0:3]
	s_setprio 0
	s_barrier
	s_add_u32 s0, s0, 0x100
	s_addc_u32 s1, s1, 0
	s_add_u32 s44, s44, 0x100
	s_addc_u32 s45, s45, 0
	s_cmp_ge_i32 s46, s33
	s_mov_b32 s6, s46
	s_cbranch_scc0 .LBB0_919

; #define PG8_STAGE(bufoff, gbase, voff) do { _Pragma("unroll") for (int _i = 0; _i < 2; ++_i) \
;         __builtin_amdgcn_global_load_lds((const unsigned*)((const char*)(gbase) + (voff)[_i]), (PG8_LAS unsigned*)(lds + (bufoff) + ldsw + _i * 8192), 16, 0, 0); } while (0)
; #define PG8_LDA(dst, b, h) do { _Pragma("unroll") for (int m = 0; m < 4; ++m) _Pragma("unroll") for (int k = 0; k < 2; ++k) dst[m][k] = *(const PG8_LAS bf16x8*)(lds + PG8_SA(b, h) + aoff + m * 2048 + k * 1024); } while (0)
; #define PG8_LDB(dst, b, h) do { _Pragma("unroll") for (int n = 0; n < 2; ++n) _Pragma("unroll") for (int k = 0; k < 2; ++k) dst[n][k] = *(const PG8_LAS bf16x8*)(lds + PG8_SB(b, h) + boff + n * 2048 + k * 1024); } while (0)
; #define PG8_MMA(ai, bj, At, Bt) do { __builtin_amdgcn_s_setprio(1); _Pragma("unroll") for (int m = 0; m < 4; ++m) _Pragma("unroll") for (int n = 0; n < 2; ++n) _Pragma("unroll") for (int k = 0; k < 2; ++k) \
;         acc[ai][bj][m][n] = __builtin_amdgcn_mfma_f32_16x16x32_bf16(Bt[n][k], At[m][k], acc[ai][bj][m][n], 0, 0, 0); __builtin_amdgcn_s_setprio(0); } while (0)
; #define PG8_WAIT_V(n) asm volatile("s_waitcnt vmcnt(" #n ")" ::: "memory")
; #define PG8_WAIT_L(n) asm volatile("s_waitcnt lgkmcnt(" #n ")" ::: "memory")
; template <class Epi, class Sched, bool ALIGN_EPI = false, bool SP2 = false>
; __device__ __forceinline__ void gemm_phase(PG8_LAS unsigned char* lds, const Gemm g, const Sched& S, const Epi& E) {
;     ...
;             const bool last = (t == nt - 2);
;             const char* a1 = cA + (size_t)(t + 1) * kstep;
;             const char* a2 = last ? nA : cA + (size_t)(t + 2) * kstep; const char* b2 = last ? nB : cB + (size_t)(t + 2) * kstep;
;             const char* a3 = a2 + kstep; const char* b3 = b2 + kstep;
;             if (last && has_next) S.a_ready(nxt);
;             if constexpr (SP2) {
;             PG8_LDB(B0, 0, 0); PG8_LDB(B1, 0, 1); PG8_SCHED; PG8_LDA(At, 0, 0); PG8_STAGE(PG8_SA(1, 1), a1 + hstep, voffA);
;             PG8_WAIT_V(8); PG8_WAIT_L(0); PG8_BAR; PG8_MMA(0, 0, At, B0); PG8_MMA(0, 1, At, B1); PG8_BAR; PG8_SCHED;
;             PG8_LDA(At, 0, 1); PG8_STAGE(PG8_SB(0, 0), b2, voffB); PG8_STAGE(PG8_SB(0, 1), b2 + hstep, voffB); PG8_STAGE(PG8_SA(0, 0), a2, voffA);
;             PG8_WAIT_V(8); PG8_WAIT_L(0); PG8_BAR; PG8_MMA(1, 0, At, B0); PG8_MMA(1, 1, At, B1); PG8_BAR; PG8_SCHED;
.LBB0_1440:
	ds_read_b128 v[146:149], v164
	ds_read_b128 v[168:171], v164 offset:1024
	ds_read_b128 v[172:175], v164 offset:2048
	ds_read_b128 v[176:179], v164 offset:3072
	ds_read_b128 v[180:183], v165
	ds_read_b128 v[184:187], v165 offset:1024
	ds_read_b128 v[188:191], v165 offset:2048
	ds_read_b128 v[192:195], v165 offset:3072
	s_add_u32 s56, s54, 0xfff80080
	s_addc_u32 s57, s55, -1
	s_cmp_eq_u32 s87, 28
	s_cselect_b32 s59, s47, s57
	s_cselect_b32 s58, s83, s56
	s_cselect_b32 s57, s45, s86
	s_cselect_b32 s56, s84, s85
	v_lshl_add_u64 v[228:229], s[54:55], 0, v[136:137]
	s_add_i32 m0, s65, 0xc000
	ds_read_b128 v[196:199], v166
	ds_read_b128 v[200:203], v166 offset:1024
	ds_read_b128 v[204:207], v166 offset:2048
	ds_read_b128 v[208:211], v166 offset:3072
	ds_read_b128 v[212:215], v166 offset:4096
	ds_read_b128 v[216:219], v166 offset:5120
	ds_read_b128 v[220:223], v166 offset:6144
	ds_read_b128 v[224:227], v166 offset:7168
	global_load_lds_dwordx4 v[228:229], off
	v_lshl_add_u64 v[228:229], s[54:55], 0, v[138:139]
	s_add_i32 m0, s65, 0xe000
	s_nop 0
	global_load_lds_dwordx4 v[228:229], off
	s_waitcnt vmcnt(8)
	s_waitcnt lgkmcnt(0)
	s_barrier
	s_setprio 1
	s_waitcnt lgkmcnt(0)
	v_mfma_f32_16x16x32_bf16 v[124:127], v[146:149], v[196:199], v[124:127]
	v_mfma_f32_16x16x32_bf16 v[120:123], v[172:175], v[196:199], v[120:123]
	v_mfma_f32_16x16x32_bf16 v[108:111], v[146:149], v[204:207], v[108:111]
	v_mfma_f32_16x16x32_bf16 v[104:107], v[172:175], v[204:207], v[104:107]
	v_mfma_f32_16x16x32_bf16 v[92:95], v[146:149], v[212:215], v[92:95]
	v_mfma_f32_16x16x32_bf16 v[88:91], v[172:175], v[212:215], v[88:91]
	v_mfma_f32_16x16x32_bf16 v[76:79], v[146:149], v[220:223], v[76:79]
	v_mfma_f32_16x16x32_bf16 v[72:75], v[172:175], v[220:223], v[72:75]
	s_setprio 0
	s_setprio 1
	v_mfma_f32_16x16x32_bf16 v[124:127], v[168:171], v[200:203], v[124:127]
	v_mfma_f32_16x16x32_bf16 v[120:123], v[176:179], v[200:203], v[120:123]
	v_mfma_f32_16x16x32_bf16 v[108:111], v[168:171], v[208:211], v[108:111]
	v_mfma_f32_16x16x32_bf16 v[104:107], v[176:179], v[208:211], v[104:107]
	v_mfma_f32_16x16x32_bf16 v[92:95], v[168:171], v[216:219], v[92:95]
	v_mfma_f32_16x16x32_bf16 v[88:91], v[176:179], v[216:219], v[88:91]
	v_mfma_f32_16x16x32_bf16 v[76:79], v[168:171], v[224:227], v[76:79]
	v_mfma_f32_16x16x32_bf16 v[72:75], v[176:179], v[224:227], v[72:75]
	s_setprio 0
	s_setprio 1
	v_mfma_f32_16x16x32_bf16 v[116:119], v[180:183], v[196:199], v[116:119]
	v_mfma_f32_16x16x32_bf16 v[112:115], v[188:191], v[196:199], v[112:115]
	v_mfma_f32_16x16x32_bf16 v[100:103], v[180:183], v[204:207], v[100:103]
	v_mfma_f32_16x16x32_bf16 v[96:99], v[188:191], v[204:207], v[96:99]
	v_mfma_f32_16x16x32_bf16 v[84:87], v[180:183], v[212:215], v[84:87]
	v_mfma_f32_16x16x32_bf16 v[80:83], v[188:191], v[212:215], v[80:83]
	v_mfma_f32_16x16x32_bf16 v[68:71], v[180:183], v[220:223], v[68:71]
	v_mfma_f32_16x16x32_bf16 v[64:67], v[188:191], v[220:223], v[64:67]
	s_setprio 0
	s_setprio 1
	v_mfma_f32_16x16x32_bf16 v[116:119], v[184:187], v[200:203], v[116:119]
	v_mfma_f32_16x16x32_bf16 v[112:115], v[192:195], v[200:203], v[112:115]
	v_mfma_f32_16x16x32_bf16 v[100:103], v[184:187], v[208:211], v[100:103]
	v_mfma_f32_16x16x32_bf16 v[96:99], v[192:195], v[208:211], v[96:99]
	v_mfma_f32_16x16x32_bf16 v[84:87], v[184:187], v[216:219], v[84:87]
	v_mfma_f32_16x16x32_bf16 v[80:83], v[192:195], v[216:219], v[80:83]
	v_mfma_f32_16x16x32_bf16 v[68:71], v[184:187], v[224:227], v[68:71]
	v_mfma_f32_16x16x32_bf16 v[64:67], v[192:195], v[224:227], v[64:67]
	s_setprio 0
	s_barrier
	s_add_i32 s88, s74, s64
	v_lshl_add_u64 v[228:229], s[56:57], 0, v[130:131]
	s_mov_b32 m0, s88
	ds_read_b128 v[196:199], v166 offset:16384
	ds_read_b128 v[200:203], v166 offset:17408
	ds_read_b128 v[204:207], v166 offset:18432
	ds_read_b128 v[208:211], v166 offset:19456
	ds_read_b128 v[212:215], v166 offset:20480
	ds_read_b128 v[216:219], v166 offset:21504
	ds_read_b128 v[220:223], v166 offset:22528
	ds_read_b128 v[224:227], v166 offset:23552
	global_load_lds_dwordx4 v[228:229], off
	s_add_i32 m0, s88, 0x2000
	s_add_u32 s88, s56, 0x80000
	v_lshl_add_u64 v[230:231], s[56:57], 0, v[134:135]
	s_addc_u32 s89, s57, 0
	s_add_i32 s90, s75, s64
	global_load_lds_dwordx4 v[230:231], off
	v_lshl_add_u64 v[232:233], s[88:89], 0, v[130:131]
	s_mov_b32 m0, s90
	v_lshl_add_u64 v[234:235], s[58:59], 0, v[132:133]
	global_load_lds_dwordx4 v[232:233], off
	v_lshl_add_u64 v[232:233], s[88:89], 0, v[134:135]
	s_add_i32 m0, s90, 0x2000
	s_nop 0
	global_load_lds_dwordx4 v[232:233], off
	v_lshl_add_u64 v[232:233], s[58:59], 0, v[128:129]
	s_mov_b32 m0, s65
	s_nop 0
	global_load_lds_dwordx4 v[232:233], off
	s_mov_b32 m0, s66
	s_nop 0
	global_load_lds_dwordx4 v[234:235], off
	s_waitcnt vmcnt(8)
	s_waitcnt lgkmcnt(0)
	s_barrier
; #define PG8_STAGE(bufoff, gbase, voff) do { _Pragma("unroll") for (int _i = 0; _i < 2; ++_i) \
;         __builtin_amdgcn_global_load_lds((const unsigned*)((const char*)(gbase) + (voff)[_i]), (PG8_LAS unsigned*)(lds + (bufoff) + ldsw + _i * 8192), 16, 0, 0); } while (0)
; #define PG8_LDA(dst, b, h) do { _Pragma("unroll") for (int m = 0; m < 4; ++m) _Pragma("unroll") for (int k = 0; k < 2; ++k) dst[m][k] = *(const PG8_LAS bf16x8*)(lds + PG8_SA(b, h) + aoff + m * 2048 + k * 1024); } while (0)
; #define PG8_LDB(dst, b, h) do { _Pragma("unroll") for (int n = 0; n < 2; ++n) _Pragma("unroll") for (int k = 0; k < 2; ++k) dst[n][k] = *(const PG8_LAS bf16x8*)(lds + PG8_SB(b, h) + boff + n * 2048 + k * 1024); } while (0)
; #define PG8_MMA(ai, bj, At, Bt) do { __builtin_amdgcn_s_setprio(1); _Pragma("unroll") for (int m = 0; m < 4; ++m) _Pragma("unroll") for (int n = 0; n < 2; ++n) _Pragma("unroll") for (int k = 0; k < 2; ++k) \
;         acc[ai][bj][m][n] = __builtin_amdgcn_mfma_f32_16x16x32_bf16(Bt[n][k], At[m][k], acc[ai][bj][m][n], 0, 0, 0); __builtin_amdgcn_s_setprio(0); } while (0)
; #define PG8_WAIT_V(n) asm volatile("s_waitcnt vmcnt(" #n ")" ::: "memory")
; #define PG8_WAIT_L(n) asm volatile("s_waitcnt lgkmcnt(" #n ")" ::: "memory")
; #define PG8_BAR __builtin_amdgcn_s_barrier()
; #define PG8_SCHED __builtin_amdgcn_sched_barrier(0)
; template <class Epi, class Sched, bool ALIGN_EPI = false, bool SP2 = false>
; __device__ __forceinline__ void gemm_phase(PG8_LAS unsigned char* lds, const Gemm g, const Sched& S, const Epi& E) {
;     ...
;             PG8_WAIT_V(8); PG8_WAIT_L(0); PG8_BAR; PG8_MMA(1, 0, At, B0); PG8_MMA(1, 1, At, B1); PG8_BAR; PG8_SCHED;
;             PG8_LDB(B0, 1, 0); PG8_LDB(B1, 1, 1); PG8_SCHED; PG8_LDA(At, 1, 0); PG8_STAGE(PG8_SA(0, 1), a2 + hstep, voffA);
;             PG8_WAIT_V(8); PG8_WAIT_L(0); PG8_BAR; PG8_MMA(0, 0, At, B0); PG8_MMA(0, 1, At, B1); PG8_BAR; PG8_SCHED;
	s_setprio 1
	s_waitcnt lgkmcnt(0)
	v_mfma_f32_16x16x32_bf16 v[60:63], v[146:149], v[196:199], v[60:63]
	v_mfma_f32_16x16x32_bf16 v[56:59], v[172:175], v[196:199], v[56:59]
	v_mfma_f32_16x16x32_bf16 v[44:47], v[146:149], v[204:207], v[44:47]
	v_mfma_f32_16x16x32_bf16 v[40:43], v[172:175], v[204:207], v[40:43]
	v_mfma_f32_16x16x32_bf16 v[28:31], v[146:149], v[212:215], v[28:31]
	v_mfma_f32_16x16x32_bf16 v[24:27], v[172:175], v[212:215], v[24:27]
	v_mfma_f32_16x16x32_bf16 v[12:15], v[146:149], v[220:223], v[12:15]
	v_mfma_f32_16x16x32_bf16 v[8:11], v[172:175], v[220:223], v[8:11]
	s_setprio 0
	s_setprio 1
	v_mfma_f32_16x16x32_bf16 v[60:63], v[168:171], v[200:203], v[60:63]
	v_mfma_f32_16x16x32_bf16 v[56:59], v[176:179], v[200:203], v[56:59]
	v_mfma_f32_16x16x32_bf16 v[44:47], v[168:171], v[208:211], v[44:47]
	v_mfma_f32_16x16x32_bf16 v[40:43], v[176:179], v[208:211], v[40:43]
	v_mfma_f32_16x16x32_bf16 v[28:31], v[168:171], v[216:219], v[28:31]
	v_mfma_f32_16x16x32_bf16 v[24:27], v[176:179], v[216:219], v[24:27]
	v_mfma_f32_16x16x32_bf16 v[12:15], v[168:171], v[224:227], v[12:15]
	v_mfma_f32_16x16x32_bf16 v[8:11], v[176:179], v[224:227], v[8:11]
	s_setprio 0
	s_setprio 1
	v_mfma_f32_16x16x32_bf16 v[52:55], v[180:183], v[196:199], v[52:55]
	v_mfma_f32_16x16x32_bf16 v[48:51], v[188:191], v[196:199], v[48:51]
	v_mfma_f32_16x16x32_bf16 v[36:39], v[180:183], v[204:207], v[36:39]
	v_mfma_f32_16x16x32_bf16 v[32:35], v[188:191], v[204:207], v[32:35]
	v_mfma_f32_16x16x32_bf16 v[20:23], v[180:183], v[212:215], v[20:23]
	v_mfma_f32_16x16x32_bf16 v[16:19], v[188:191], v[212:215], v[16:19]
	v_mfma_f32_16x16x32_bf16 v[4:7], v[180:183], v[220:223], v[4:7]
	v_mfma_f32_16x16x32_bf16 v[0:3], v[188:191], v[220:223], v[0:3]
	s_setprio 0
	s_setprio 1
	v_mfma_f32_16x16x32_bf16 v[52:55], v[184:187], v[200:203], v[52:55]
	v_mfma_f32_16x16x32_bf16 v[48:51], v[192:195], v[200:203], v[48:51]
	v_mfma_f32_16x16x32_bf16 v[36:39], v[184:187], v[208:211], v[36:39]
	v_mfma_f32_16x16x32_bf16 v[32:35], v[192:195], v[208:211], v[32:35]
	v_mfma_f32_16x16x32_bf16 v[20:23], v[184:187], v[216:219], v[20:23]
	v_mfma_f32_16x16x32_bf16 v[16:19], v[192:195], v[216:219], v[16:19]
	v_mfma_f32_16x16x32_bf16 v[4:7], v[184:187], v[224:227], v[4:7]
	v_mfma_f32_16x16x32_bf16 v[0:3], v[192:195], v[224:227], v[0:3]
	s_setprio 0
	s_barrier
	s_add_i32 s88, 0, 0x18000
	v_add_u32_e32 v167, s88, v163
	s_add_i32 s89, 0, 0x1c000
	ds_read_b128 v[146:149], v167
	ds_read_b128 v[168:171], v167 offset:1024
	ds_read_b128 v[172:175], v167 offset:2048
	ds_read_b128 v[176:179], v167 offset:3072
	v_add_u32_e32 v167, s89, v163
	ds_read_b128 v[180:183], v167
	ds_read_b128 v[184:187], v167 offset:1024
	ds_read_b128 v[188:191], v167 offset:2048
	ds_read_b128 v[192:195], v167 offset:3072
	s_add_u32 s58, s58, 0x80000
	s_addc_u32 s59, s59, 0
	s_mov_b32 m0, s67
	v_lshl_add_u64 v[236:237], s[58:59], 0, v[128:129]
	ds_read_b128 v[196:199], v166 offset:32768
	ds_read_b128 v[200:203], v166 offset:33792
	ds_read_b128 v[204:207], v166 offset:34816
	ds_read_b128 v[208:211], v166 offset:35840
	ds_read_b128 v[212:215], v166 offset:36864
	ds_read_b128 v[216:219], v166 offset:37888
	ds_read_b128 v[220:223], v166 offset:38912
	ds_read_b128 v[224:227], v166 offset:39936
	global_load_lds_dwordx4 v[236:237], off
	v_lshl_add_u64 v[236:237], s[58:59], 0, v[132:133]
	s_mov_b32 m0, s68
	s_nop 0
	global_load_lds_dwordx4 v[236:237], off
	s_waitcnt vmcnt(8)
	s_waitcnt lgkmcnt(0)
	s_barrier
	s_setprio 1
	s_waitcnt lgkmcnt(0)
	v_mfma_f32_16x16x32_bf16 v[124:127], v[146:149], v[196:199], v[124:127]
	v_mfma_f32_16x16x32_bf16 v[120:123], v[172:175], v[196:199], v[120:123]
	v_mfma_f32_16x16x32_bf16 v[108:111], v[146:149], v[204:207], v[108:111]
	v_mfma_f32_16x16x32_bf16 v[104:107], v[172:175], v[204:207], v[104:107]
	v_mfma_f32_16x16x32_bf16 v[92:95], v[146:149], v[212:215], v[92:95]
	v_mfma_f32_16x16x32_bf16 v[88:91], v[172:175], v[212:215], v[88:91]
	v_mfma_f32_16x16x32_bf16 v[76:79], v[146:149], v[220:223], v[76:79]
	v_mfma_f32_16x16x32_bf16 v[72:75], v[172:175], v[220:223], v[72:75]
	s_setprio 0
	s_setprio 1
	v_mfma_f32_16x16x32_bf16 v[124:127], v[168:171], v[200:203], v[124:127]
	v_mfma_f32_16x16x32_bf16 v[120:123], v[176:179], v[200:203], v[120:123]
	v_mfma_f32_16x16x32_bf16 v[108:111], v[168:171], v[208:211], v[108:111]
	v_mfma_f32_16x16x32_bf16 v[104:107], v[176:179], v[208:211], v[104:107]
	v_mfma_f32_16x16x32_bf16 v[92:95], v[168:171], v[216:219], v[92:95]
	v_mfma_f32_16x16x32_bf16 v[88:91], v[176:179], v[216:219], v[88:91]
	v_mfma_f32_16x16x32_bf16 v[76:79], v[168:171], v[224:227], v[76:79]
	v_mfma_f32_16x16x32_bf16 v[72:75], v[176:179], v[224:227], v[72:75]
	s_setprio 0
	s_setprio 1
	v_mfma_f32_16x16x32_bf16 v[116:119], v[180:183], v[196:199], v[116:119]
	v_mfma_f32_16x16x32_bf16 v[112:115], v[188:191], v[196:199], v[112:115]
	v_mfma_f32_16x16x32_bf16 v[100:103], v[180:183], v[204:207], v[100:103]
	v_mfma_f32_16x16x32_bf16 v[96:99], v[188:191], v[204:207], v[96:99]
	v_mfma_f32_16x16x32_bf16 v[84:87], v[180:183], v[212:215], v[84:87]
	v_mfma_f32_16x16x32_bf16 v[80:83], v[188:191], v[212:215], v[80:83]
	v_mfma_f32_16x16x32_bf16 v[68:71], v[180:183], v[220:223], v[68:71]
	v_mfma_f32_16x16x32_bf16 v[64:67], v[188:191], v[220:223], v[64:67]
	s_setprio 0
	s_setprio 1
	v_mfma_f32_16x16x32_bf16 v[116:119], v[184:187], v[200:203], v[116:119]
	v_mfma_f32_16x16x32_bf16 v[112:115], v[192:195], v[200:203], v[112:115]
	v_mfma_f32_16x16x32_bf16 v[100:103], v[184:187], v[208:211], v[100:103]
	v_mfma_f32_16x16x32_bf16 v[96:99], v[192:195], v[208:211], v[96:99]
	v_mfma_f32_16x16x32_bf16 v[84:87], v[184:187], v[216:219], v[84:87]
	v_mfma_f32_16x16x32_bf16 v[80:83], v[192:195], v[216:219], v[80:83]
	v_mfma_f32_16x16x32_bf16 v[68:71], v[184:187], v[224:227], v[68:71]
	v_mfma_f32_16x16x32_bf16 v[64:67], v[192:195], v[224:227], v[64:67]
	s_setprio 0
	s_barrier
; #define PG8_STAGE(bufoff, gbase, voff) do { _Pragma("unroll") for (int _i = 0; _i < 2; ++_i) \
;         __builtin_amdgcn_global_load_lds((const unsigned*)((const char*)(gbase) + (voff)[_i]), (PG8_LAS unsigned*)(lds + (bufoff) + ldsw + _i * 8192), 16, 0, 0); } while (0)
; #define PG8_LDA(dst, b, h) do { _Pragma("unroll") for (int m = 0; m < 4; ++m) _Pragma("unroll") for (int k = 0; k < 2; ++k) dst[m][k] = *(const PG8_LAS bf16x8*)(lds + PG8_SA(b, h) + aoff + m * 2048 + k * 1024); } while (0)
; #define PG8_MMA(ai, bj, At, Bt) do { __builtin_amdgcn_s_setprio(1); _Pragma("unroll") for (int m = 0; m < 4; ++m) _Pragma("unroll") for (int n = 0; n < 2; ++n) _Pragma("unroll") for (int k = 0; k < 2; ++k) \
;         acc[ai][bj][m][n] = __builtin_amdgcn_mfma_f32_16x16x32_bf16(Bt[n][k], At[m][k], acc[ai][bj][m][n], 0, 0, 0); __builtin_amdgcn_s_setprio(0); } while (0)
; #define PG8_WAIT_V(n) asm volatile("s_waitcnt vmcnt(" #n ")" ::: "memory")
; #define PG8_WAIT_L(n) asm volatile("s_waitcnt lgkmcnt(" #n ")" ::: "memory")
; #define PG8_BAR __builtin_amdgcn_s_barrier()
; #define PG8_SCHED __builtin_amdgcn_sched_barrier(0)
; template <class Epi, class Sched, bool ALIGN_EPI = false, bool SP2 = false>
; __device__ __forceinline__ void gemm_phase(PG8_LAS unsigned char* lds, const Gemm g, const Sched& S, const Epi& E) {
;     ...
;             PG8_LDA(At, 1, 1); PG8_STAGE(PG8_SB(1, 0), b3, voffB); PG8_STAGE(PG8_SB(1, 1), b3 + hstep, voffB); PG8_STAGE(PG8_SA(1, 0), a3, voffA);
;             PG8_WAIT_V(8); PG8_WAIT_L(0); PG8_BAR; PG8_MMA(1, 0, At, B0); PG8_MMA(1, 1, At, B1); PG8_BAR; PG8_SCHED;
	s_add_i32 s58, s88, s64
	v_lshl_add_u64 v[228:229], v[228:229], 0, s[12:13]
	s_mov_b32 m0, s58
	ds_read_b128 v[196:199], v166 offset:49152
	ds_read_b128 v[200:203], v166 offset:50176
	ds_read_b128 v[204:207], v166 offset:51200
	ds_read_b128 v[208:211], v166 offset:52224
	ds_read_b128 v[212:215], v166 offset:53248
	ds_read_b128 v[216:219], v166 offset:54272
	ds_read_b128 v[220:223], v166 offset:55296
	ds_read_b128 v[224:227], v166 offset:56320
	global_load_lds_dwordx4 v[228:229], off
	s_add_i32 m0, s58, 0x2000
	s_add_u32 s56, s56, 0x80080
	v_lshl_add_u64 v[228:229], v[230:231], 0, s[12:13]
	s_addc_u32 s57, s57, 0
	s_add_i32 s58, s89, s64
	global_load_lds_dwordx4 v[228:229], off
	v_lshl_add_u64 v[228:229], s[56:57], 0, v[130:131]
	s_mov_b32 m0, s58
	s_nop 0
	global_load_lds_dwordx4 v[228:229], off
	v_lshl_add_u64 v[228:229], s[56:57], 0, v[134:135]
	s_add_i32 m0, s58, 0x2000
	s_nop 0
	global_load_lds_dwordx4 v[228:229], off
	v_lshl_add_u64 v[228:229], v[232:233], 0, s[12:13]
	s_mov_b32 m0, s71
	s_nop 0
	global_load_lds_dwordx4 v[228:229], off
	v_lshl_add_u64 v[228:229], v[234:235], 0, s[12:13]
	s_mov_b32 m0, s72
	s_nop 0
	global_load_lds_dwordx4 v[228:229], off
	s_waitcnt vmcnt(8)
	s_waitcnt lgkmcnt(0)
	s_barrier
	s_setprio 1
	s_waitcnt lgkmcnt(0)
	v_mfma_f32_16x16x32_bf16 v[60:63], v[146:149], v[196:199], v[60:63]
	v_mfma_f32_16x16x32_bf16 v[56:59], v[172:175], v[196:199], v[56:59]
	v_mfma_f32_16x16x32_bf16 v[44:47], v[146:149], v[204:207], v[44:47]
	v_mfma_f32_16x16x32_bf16 v[40:43], v[172:175], v[204:207], v[40:43]
	v_mfma_f32_16x16x32_bf16 v[28:31], v[146:149], v[212:215], v[28:31]
	v_mfma_f32_16x16x32_bf16 v[24:27], v[172:175], v[212:215], v[24:27]
	v_mfma_f32_16x16x32_bf16 v[12:15], v[146:149], v[220:223], v[12:15]
	v_mfma_f32_16x16x32_bf16 v[8:11], v[172:175], v[220:223], v[8:11]
	s_setprio 0
	s_setprio 1
	v_mfma_f32_16x16x32_bf16 v[60:63], v[168:171], v[200:203], v[60:63]
	v_mfma_f32_16x16x32_bf16 v[56:59], v[176:179], v[200:203], v[56:59]
	v_mfma_f32_16x16x32_bf16 v[44:47], v[168:171], v[208:211], v[44:47]
	v_mfma_f32_16x16x32_bf16 v[40:43], v[176:179], v[208:211], v[40:43]
	v_mfma_f32_16x16x32_bf16 v[28:31], v[168:171], v[216:219], v[28:31]
	v_mfma_f32_16x16x32_bf16 v[24:27], v[176:179], v[216:219], v[24:27]
	v_mfma_f32_16x16x32_bf16 v[12:15], v[168:171], v[224:227], v[12:15]
	v_mfma_f32_16x16x32_bf16 v[8:11], v[176:179], v[224:227], v[8:11]
	s_setprio 0
	s_setprio 1
	v_mfma_f32_16x16x32_bf16 v[52:55], v[180:183], v[196:199], v[52:55]
	v_mfma_f32_16x16x32_bf16 v[48:51], v[188:191], v[196:199], v[48:51]
	v_mfma_f32_16x16x32_bf16 v[36:39], v[180:183], v[204:207], v[36:39]
	v_mfma_f32_16x16x32_bf16 v[32:35], v[188:191], v[204:207], v[32:35]
	v_mfma_f32_16x16x32_bf16 v[20:23], v[180:183], v[212:215], v[20:23]
	v_mfma_f32_16x16x32_bf16 v[16:19], v[188:191], v[212:215], v[16:19]
	v_mfma_f32_16x16x32_bf16 v[4:7], v[180:183], v[220:223], v[4:7]
	v_mfma_f32_16x16x32_bf16 v[0:3], v[188:191], v[220:223], v[0:3]
	s_setprio 0
	s_setprio 1
	v_mfma_f32_16x16x32_bf16 v[52:55], v[184:187], v[200:203], v[52:55]
	v_mfma_f32_16x16x32_bf16 v[48:51], v[192:195], v[200:203], v[48:51]
	v_mfma_f32_16x16x32_bf16 v[36:39], v[184:187], v[208:211], v[36:39]
	v_mfma_f32_16x16x32_bf16 v[32:35], v[192:195], v[208:211], v[32:35]
	v_mfma_f32_16x16x32_bf16 v[20:23], v[184:187], v[216:219], v[20:23]
	v_mfma_f32_16x16x32_bf16 v[16:19], v[192:195], v[216:219], v[16:19]
	v_mfma_f32_16x16x32_bf16 v[4:7], v[184:187], v[224:227], v[4:7]
	v_mfma_f32_16x16x32_bf16 v[0:3], v[192:195], v[224:227], v[0:3]
	s_setprio 0
	s_barrier
	s_add_i32 s87, s87, 2
	s_add_u32 s54, s54, 0x100
	s_addc_u32 s55, s55, 0
	s_add_u32 s85, s85, 0x100
	s_addc_u32 s86, s86, 0
	s_cmp_gt_u32 s87, 29
	s_cbranch_scc0 .LBB0_1440
	s_and_b64 vcc, exec, s[14:15]
	s_cbranch_vccz .LBB0_1443
	s_barrier

; #define PG8_STAGE(bufoff, gbase, voff) do { _Pragma("unroll") for (int _i = 0; _i < 2; ++_i) \
;         __builtin_amdgcn_global_load_lds((const unsigned*)((const char*)(gbase) + (voff)[_i]), (PG8_LAS unsigned*)(lds + (bufoff) + ldsw + _i * 8192), 16, 0, 0); } while (0)
; #define PG8_LDA(dst, b, h) do { _Pragma("unroll") for (int m = 0; m < 4; ++m) _Pragma("unroll") for (int k = 0; k < 2; ++k) dst[m][k] = *(const PG8_LAS bf16x8*)(lds + PG8_SA(b, h) + aoff + m * 2048 + k * 1024); } while (0)
; #define PG8_LDB(dst, b, h) do { _Pragma("unroll") for (int n = 0; n < 2; ++n) _Pragma("unroll") for (int k = 0; k < 2; ++k) dst[n][k] = *(const PG8_LAS bf16x8*)(lds + PG8_SB(b, h) + boff + n * 2048 + k * 1024); } while (0)
; #define PG8_MMA(ai, bj, At, Bt) do { __builtin_amdgcn_s_setprio(1); _Pragma("unroll") for (int m = 0; m < 4; ++m) _Pragma("unroll") for (int n = 0; n < 2; ++n) _Pragma("unroll") for (int k = 0; k < 2; ++k) \
;         acc[ai][bj][m][n] = __builtin_amdgcn_mfma_f32_16x16x32_bf16(Bt[n][k], At[m][k], acc[ai][bj][m][n], 0, 0, 0); __builtin_amdgcn_s_setprio(0); } while (0)
; #define PG8_WAIT_V(n) asm volatile("s_waitcnt vmcnt(" #n ")" ::: "memory")
; #define PG8_WAIT_L(n) asm volatile("s_waitcnt lgkmcnt(" #n ")" ::: "memory")
; template <class Epi, class Sched, bool ALIGN_EPI = false, bool SP2 = false>
; __device__ __forceinline__ void gemm_phase(PG8_LAS unsigned char* lds, const Gemm g, const Sched& S, const Epi& E) {
;     ...
;             const bool last = (t == nt - 2);
;             const char* a1 = cA + (size_t)(t + 1) * kstep;
;             const char* a2 = last ? nA : cA + (size_t)(t + 2) * kstep; const char* b2 = last ? nB : cB + (size_t)(t + 2) * kstep;
;             const char* a3 = a2 + kstep; const char* b3 = b2 + kstep;
;             if (last && has_next) S.a_ready(nxt);
;             if constexpr (SP2) {
;             PG8_LDB(B0, 0, 0); PG8_LDB(B1, 0, 1); PG8_SCHED; PG8_LDA(At, 0, 0); PG8_STAGE(PG8_SA(1, 1), a1 + hstep, voffA);
;             PG8_WAIT_V(8); PG8_WAIT_L(0); PG8_BAR; PG8_MMA(0, 0, At, B0); PG8_MMA(0, 1, At, B1); PG8_BAR; PG8_SCHED;
;             PG8_LDA(At, 0, 1); PG8_STAGE(PG8_SB(0, 0), b2, voffB); PG8_STAGE(PG8_SB(0, 1), b2 + hstep, voffB); PG8_STAGE(PG8_SA(0, 0), a2, voffA);
;             PG8_WAIT_V(8); PG8_WAIT_L(0); PG8_BAR; PG8_MMA(1, 0, At, B0); PG8_MMA(1, 1, At, B1); PG8_BAR; PG8_SCHED;
.LBB0_1460:
	ds_read_b128 v[152:155], v147
	ds_read_b128 v[156:159], v147 offset:1024
	ds_read_b128 v[160:163], v147 offset:2048
	ds_read_b128 v[164:167], v147 offset:3072
	ds_read_b128 v[168:171], v148
	ds_read_b128 v[172:175], v148 offset:1024
	ds_read_b128 v[176:179], v148 offset:2048
	ds_read_b128 v[180:183], v148 offset:3072
	s_add_u32 s56, s54, 0xfffc0080
	s_addc_u32 s57, s55, -1
	s_cmp_eq_u32 s85, 12
	s_cselect_b32 s59, s47, s57
	s_cselect_b32 s58, s81, s56
	s_cselect_b32 s57, s45, s84
	s_cselect_b32 s56, s82, s83
	v_lshl_add_u64 v[216:217], s[54:55], 0, v[136:137]
	s_add_i32 m0, s43, 0xc000
	ds_read_b128 v[184:187], v149
	ds_read_b128 v[188:191], v149 offset:1024
	ds_read_b128 v[192:195], v149 offset:2048
	ds_read_b128 v[196:199], v149 offset:3072
	ds_read_b128 v[200:203], v149 offset:4096
	ds_read_b128 v[204:207], v149 offset:5120
	ds_read_b128 v[208:211], v149 offset:6144
	ds_read_b128 v[212:215], v149 offset:7168
	global_load_lds_dwordx4 v[216:217], off
	v_lshl_add_u64 v[216:217], s[54:55], 0, v[138:139]
	s_add_i32 m0, s43, 0xe000
	s_nop 0
	global_load_lds_dwordx4 v[216:217], off
	s_waitcnt vmcnt(8)
	s_waitcnt lgkmcnt(0)
	s_barrier
	s_setprio 1
	s_waitcnt lgkmcnt(0)
	v_mfma_f32_16x16x32_bf16 v[124:127], v[152:155], v[184:187], v[124:127]
	v_mfma_f32_16x16x32_bf16 v[120:123], v[160:163], v[184:187], v[120:123]
	v_mfma_f32_16x16x32_bf16 v[116:119], v[152:155], v[192:195], v[116:119]
	v_mfma_f32_16x16x32_bf16 v[112:115], v[160:163], v[192:195], v[112:115]
	v_mfma_f32_16x16x32_bf16 v[100:103], v[152:155], v[200:203], v[100:103]
	v_mfma_f32_16x16x32_bf16 v[96:99], v[160:163], v[200:203], v[96:99]
	v_mfma_f32_16x16x32_bf16 v[84:87], v[152:155], v[208:211], v[84:87]
	v_mfma_f32_16x16x32_bf16 v[80:83], v[160:163], v[208:211], v[80:83]
	s_setprio 0
	s_setprio 1
	v_mfma_f32_16x16x32_bf16 v[124:127], v[156:159], v[188:191], v[124:127]
	v_mfma_f32_16x16x32_bf16 v[120:123], v[164:167], v[188:191], v[120:123]
	v_mfma_f32_16x16x32_bf16 v[116:119], v[156:159], v[196:199], v[116:119]
	v_mfma_f32_16x16x32_bf16 v[112:115], v[164:167], v[196:199], v[112:115]
	v_mfma_f32_16x16x32_bf16 v[100:103], v[156:159], v[204:207], v[100:103]
	v_mfma_f32_16x16x32_bf16 v[96:99], v[164:167], v[204:207], v[96:99]
	v_mfma_f32_16x16x32_bf16 v[84:87], v[156:159], v[212:215], v[84:87]
	v_mfma_f32_16x16x32_bf16 v[80:83], v[164:167], v[212:215], v[80:83]
	s_setprio 0
	s_setprio 1
	v_mfma_f32_16x16x32_bf16 v[108:111], v[168:171], v[184:187], v[108:111]
	v_mfma_f32_16x16x32_bf16 v[104:107], v[176:179], v[184:187], v[104:107]
	v_mfma_f32_16x16x32_bf16 v[92:95], v[168:171], v[192:195], v[92:95]
	v_mfma_f32_16x16x32_bf16 v[88:91], v[176:179], v[192:195], v[88:91]
	v_mfma_f32_16x16x32_bf16 v[76:79], v[168:171], v[200:203], v[76:79]
	v_mfma_f32_16x16x32_bf16 v[72:75], v[176:179], v[200:203], v[72:75]
	v_mfma_f32_16x16x32_bf16 v[68:71], v[168:171], v[208:211], v[68:71]
	v_mfma_f32_16x16x32_bf16 v[64:67], v[176:179], v[208:211], v[64:67]
	s_setprio 0
	s_setprio 1
	v_mfma_f32_16x16x32_bf16 v[108:111], v[172:175], v[188:191], v[108:111]
	v_mfma_f32_16x16x32_bf16 v[104:107], v[180:183], v[188:191], v[104:107]
	v_mfma_f32_16x16x32_bf16 v[92:95], v[172:175], v[196:199], v[92:95]
	v_mfma_f32_16x16x32_bf16 v[88:91], v[180:183], v[196:199], v[88:91]
	v_mfma_f32_16x16x32_bf16 v[76:79], v[172:175], v[204:207], v[76:79]
	v_mfma_f32_16x16x32_bf16 v[72:75], v[180:183], v[204:207], v[72:75]
	v_mfma_f32_16x16x32_bf16 v[68:71], v[172:175], v[212:215], v[68:71]
	v_mfma_f32_16x16x32_bf16 v[64:67], v[180:183], v[212:215], v[64:67]
	s_setprio 0
	s_barrier
	s_add_i32 s86, s72, s60
	v_lshl_add_u64 v[216:217], s[56:57], 0, v[130:131]
	s_mov_b32 m0, s86
	ds_read_b128 v[184:187], v149 offset:16384
	ds_read_b128 v[188:191], v149 offset:17408
	ds_read_b128 v[192:195], v149 offset:18432
	ds_read_b128 v[196:199], v149 offset:19456
	ds_read_b128 v[200:203], v149 offset:20480
	ds_read_b128 v[204:207], v149 offset:21504
	ds_read_b128 v[208:211], v149 offset:22528
	ds_read_b128 v[212:215], v149 offset:23552
	global_load_lds_dwordx4 v[216:217], off
	s_add_i32 m0, s86, 0x2000
	s_add_u32 s86, s56, 0x40000
	v_lshl_add_u64 v[218:219], s[56:57], 0, v[134:135]
	s_addc_u32 s87, s57, 0
	s_add_i32 s88, s73, s60
	global_load_lds_dwordx4 v[218:219], off
	v_lshl_add_u64 v[220:221], s[86:87], 0, v[130:131]
	s_mov_b32 m0, s88
	v_lshl_add_u64 v[222:223], s[58:59], 0, v[132:133]
	global_load_lds_dwordx4 v[220:221], off
	v_lshl_add_u64 v[220:221], s[86:87], 0, v[134:135]
	s_add_i32 m0, s88, 0x2000
	s_nop 0
	global_load_lds_dwordx4 v[220:221], off
	v_lshl_add_u64 v[220:221], s[58:59], 0, v[128:129]
	s_mov_b32 m0, s43
	s_nop 0
	global_load_lds_dwordx4 v[220:221], off
	s_mov_b32 m0, s50
	s_nop 0
	global_load_lds_dwordx4 v[222:223], off
	s_waitcnt vmcnt(8)
	s_waitcnt lgkmcnt(0)
	s_barrier
; #define PG8_STAGE(bufoff, gbase, voff) do { _Pragma("unroll") for (int _i = 0; _i < 2; ++_i) \
;         __builtin_amdgcn_global_load_lds((const unsigned*)((const char*)(gbase) + (voff)[_i]), (PG8_LAS unsigned*)(lds + (bufoff) + ldsw + _i * 8192), 16, 0, 0); } while (0)
; #define PG8_LDA(dst, b, h) do { _Pragma("unroll") for (int m = 0; m < 4; ++m) _Pragma("unroll") for (int k = 0; k < 2; ++k) dst[m][k] = *(const PG8_LAS bf16x8*)(lds + PG8_SA(b, h) + aoff + m * 2048 + k * 1024); } while (0)
; #define PG8_LDB(dst, b, h) do { _Pragma("unroll") for (int n = 0; n < 2; ++n) _Pragma("unroll") for (int k = 0; k < 2; ++k) dst[n][k] = *(const PG8_LAS bf16x8*)(lds + PG8_SB(b, h) + boff + n * 2048 + k * 1024); } while (0)
; #define PG8_MMA(ai, bj, At, Bt) do { __builtin_amdgcn_s_setprio(1); _Pragma("unroll") for (int m = 0; m < 4; ++m) _Pragma("unroll") for (int n = 0; n < 2; ++n) _Pragma("unroll") for (int k = 0; k < 2; ++k) \
;         acc[ai][bj][m][n] = __builtin_amdgcn_mfma_f32_16x16x32_bf16(Bt[n][k], At[m][k], acc[ai][bj][m][n], 0, 0, 0); __builtin_amdgcn_s_setprio(0); } while (0)
; #define PG8_WAIT_V(n) asm volatile("s_waitcnt vmcnt(" #n ")" ::: "memory")
; #define PG8_WAIT_L(n) asm volatile("s_waitcnt lgkmcnt(" #n ")" ::: "memory")
; #define PG8_BAR __builtin_amdgcn_s_barrier()
; #define PG8_SCHED __builtin_amdgcn_sched_barrier(0)
; template <class Epi, class Sched, bool ALIGN_EPI = false, bool SP2 = false>
; __device__ __forceinline__ void gemm_phase(PG8_LAS unsigned char* lds, const Gemm g, const Sched& S, const Epi& E) {
;     ...
;             PG8_WAIT_V(8); PG8_WAIT_L(0); PG8_BAR; PG8_MMA(1, 0, At, B0); PG8_MMA(1, 1, At, B1); PG8_BAR; PG8_SCHED;
;             PG8_LDB(B0, 1, 0); PG8_LDB(B1, 1, 1); PG8_SCHED; PG8_LDA(At, 1, 0); PG8_STAGE(PG8_SA(0, 1), a2 + hstep, voffA);
;             PG8_WAIT_V(8); PG8_WAIT_L(0); PG8_BAR; PG8_MMA(0, 0, At, B0); PG8_MMA(0, 1, At, B1); PG8_BAR; PG8_SCHED;
	s_setprio 1
	s_waitcnt lgkmcnt(0)
	v_mfma_f32_16x16x32_bf16 v[60:63], v[152:155], v[184:187], v[60:63]
	v_mfma_f32_16x16x32_bf16 v[56:59], v[160:163], v[184:187], v[56:59]
	v_mfma_f32_16x16x32_bf16 v[52:55], v[152:155], v[192:195], v[52:55]
	v_mfma_f32_16x16x32_bf16 v[48:51], v[160:163], v[192:195], v[48:51]
	v_mfma_f32_16x16x32_bf16 v[36:39], v[152:155], v[200:203], v[36:39]
	v_mfma_f32_16x16x32_bf16 v[32:35], v[160:163], v[200:203], v[32:35]
	v_mfma_f32_16x16x32_bf16 v[20:23], v[152:155], v[208:211], v[20:23]
	v_mfma_f32_16x16x32_bf16 v[16:19], v[160:163], v[208:211], v[16:19]
	s_setprio 0
	s_setprio 1
	v_mfma_f32_16x16x32_bf16 v[60:63], v[156:159], v[188:191], v[60:63]
	v_mfma_f32_16x16x32_bf16 v[56:59], v[164:167], v[188:191], v[56:59]
	v_mfma_f32_16x16x32_bf16 v[52:55], v[156:159], v[196:199], v[52:55]
	v_mfma_f32_16x16x32_bf16 v[48:51], v[164:167], v[196:199], v[48:51]
	v_mfma_f32_16x16x32_bf16 v[36:39], v[156:159], v[204:207], v[36:39]
	v_mfma_f32_16x16x32_bf16 v[32:35], v[164:167], v[204:207], v[32:35]
	v_mfma_f32_16x16x32_bf16 v[20:23], v[156:159], v[212:215], v[20:23]
	v_mfma_f32_16x16x32_bf16 v[16:19], v[164:167], v[212:215], v[16:19]
	s_setprio 0
	s_setprio 1
	v_mfma_f32_16x16x32_bf16 v[44:47], v[168:171], v[184:187], v[44:47]
	v_mfma_f32_16x16x32_bf16 v[40:43], v[176:179], v[184:187], v[40:43]
	v_mfma_f32_16x16x32_bf16 v[28:31], v[168:171], v[192:195], v[28:31]
	v_mfma_f32_16x16x32_bf16 v[24:27], v[176:179], v[192:195], v[24:27]
	v_mfma_f32_16x16x32_bf16 v[12:15], v[168:171], v[200:203], v[12:15]
	v_mfma_f32_16x16x32_bf16 v[8:11], v[176:179], v[200:203], v[8:11]
	v_mfma_f32_16x16x32_bf16 v[4:7], v[168:171], v[208:211], v[4:7]
	v_mfma_f32_16x16x32_bf16 v[0:3], v[176:179], v[208:211], v[0:3]
	s_setprio 0
	s_setprio 1
	v_mfma_f32_16x16x32_bf16 v[44:47], v[172:175], v[188:191], v[44:47]
	v_mfma_f32_16x16x32_bf16 v[40:43], v[180:183], v[188:191], v[40:43]
	v_mfma_f32_16x16x32_bf16 v[28:31], v[172:175], v[196:199], v[28:31]
	v_mfma_f32_16x16x32_bf16 v[24:27], v[180:183], v[196:199], v[24:27]
	v_mfma_f32_16x16x32_bf16 v[12:15], v[172:175], v[204:207], v[12:15]
	v_mfma_f32_16x16x32_bf16 v[8:11], v[180:183], v[204:207], v[8:11]
	v_mfma_f32_16x16x32_bf16 v[4:7], v[172:175], v[212:215], v[4:7]
	v_mfma_f32_16x16x32_bf16 v[0:3], v[180:183], v[212:215], v[0:3]
	s_setprio 0
	s_barrier
	s_add_i32 s86, 0, 0x18000
	s_add_i32 s87, 0, 0x1c000
	v_add_u32_e32 v164, s86, v146
	v_add_u32_e32 v180, s87, v146
	ds_read_b128 v[152:155], v164
	ds_read_b128 v[156:159], v164 offset:1024
	ds_read_b128 v[160:163], v164 offset:2048
	ds_read_b128 v[164:167], v164 offset:3072
	ds_read_b128 v[168:171], v180
	ds_read_b128 v[172:175], v180 offset:1024
	ds_read_b128 v[176:179], v180 offset:2048
	ds_read_b128 v[180:183], v180 offset:3072
	s_add_u32 s58, s58, 0x40000
	s_addc_u32 s59, s59, 0
	s_mov_b32 m0, s51
	v_lshl_add_u64 v[224:225], s[58:59], 0, v[128:129]
	ds_read_b128 v[184:187], v149 offset:32768
	ds_read_b128 v[188:191], v149 offset:33792
	ds_read_b128 v[192:195], v149 offset:34816
	ds_read_b128 v[196:199], v149 offset:35840
	ds_read_b128 v[200:203], v149 offset:36864
	ds_read_b128 v[204:207], v149 offset:37888
	ds_read_b128 v[208:211], v149 offset:38912
	ds_read_b128 v[212:215], v149 offset:39936
	global_load_lds_dwordx4 v[224:225], off
	v_lshl_add_u64 v[224:225], s[58:59], 0, v[132:133]
	s_mov_b32 m0, s65
	s_nop 0
	global_load_lds_dwordx4 v[224:225], off
	s_waitcnt vmcnt(8)
	s_waitcnt lgkmcnt(0)
	s_barrier
	s_setprio 1
	s_waitcnt lgkmcnt(0)
	v_mfma_f32_16x16x32_bf16 v[124:127], v[152:155], v[184:187], v[124:127]
	v_mfma_f32_16x16x32_bf16 v[120:123], v[160:163], v[184:187], v[120:123]
	v_mfma_f32_16x16x32_bf16 v[116:119], v[152:155], v[192:195], v[116:119]
	v_mfma_f32_16x16x32_bf16 v[112:115], v[160:163], v[192:195], v[112:115]
	v_mfma_f32_16x16x32_bf16 v[100:103], v[152:155], v[200:203], v[100:103]
	v_mfma_f32_16x16x32_bf16 v[96:99], v[160:163], v[200:203], v[96:99]
	v_mfma_f32_16x16x32_bf16 v[84:87], v[152:155], v[208:211], v[84:87]
	v_mfma_f32_16x16x32_bf16 v[80:83], v[160:163], v[208:211], v[80:83]
	s_setprio 0
	s_setprio 1
	v_mfma_f32_16x16x32_bf16 v[124:127], v[156:159], v[188:191], v[124:127]
	v_mfma_f32_16x16x32_bf16 v[120:123], v[164:167], v[188:191], v[120:123]
	v_mfma_f32_16x16x32_bf16 v[116:119], v[156:159], v[196:199], v[116:119]
	v_mfma_f32_16x16x32_bf16 v[112:115], v[164:167], v[196:199], v[112:115]
	v_mfma_f32_16x16x32_bf16 v[100:103], v[156:159], v[204:207], v[100:103]
	v_mfma_f32_16x16x32_bf16 v[96:99], v[164:167], v[204:207], v[96:99]
	v_mfma_f32_16x16x32_bf16 v[84:87], v[156:159], v[212:215], v[84:87]
	v_mfma_f32_16x16x32_bf16 v[80:83], v[164:167], v[212:215], v[80:83]
	s_setprio 0
	s_setprio 1
	v_mfma_f32_16x16x32_bf16 v[108:111], v[168:171], v[184:187], v[108:111]
	v_mfma_f32_16x16x32_bf16 v[104:107], v[176:179], v[184:187], v[104:107]
	v_mfma_f32_16x16x32_bf16 v[92:95], v[168:171], v[192:195], v[92:95]
	v_mfma_f32_16x16x32_bf16 v[88:91], v[176:179], v[192:195], v[88:91]
	v_mfma_f32_16x16x32_bf16 v[76:79], v[168:171], v[200:203], v[76:79]
	v_mfma_f32_16x16x32_bf16 v[72:75], v[176:179], v[200:203], v[72:75]
	v_mfma_f32_16x16x32_bf16 v[68:71], v[168:171], v[208:211], v[68:71]
	v_mfma_f32_16x16x32_bf16 v[64:67], v[176:179], v[208:211], v[64:67]
	s_setprio 0
	s_setprio 1
	v_mfma_f32_16x16x32_bf16 v[108:111], v[172:175], v[188:191], v[108:111]
	v_mfma_f32_16x16x32_bf16 v[104:107], v[180:183], v[188:191], v[104:107]
	v_mfma_f32_16x16x32_bf16 v[92:95], v[172:175], v[196:199], v[92:95]
	v_mfma_f32_16x16x32_bf16 v[88:91], v[180:183], v[196:199], v[88:91]
	v_mfma_f32_16x16x32_bf16 v[76:79], v[172:175], v[204:207], v[76:79]
	v_mfma_f32_16x16x32_bf16 v[72:75], v[180:183], v[204:207], v[72:75]
	v_mfma_f32_16x16x32_bf16 v[68:71], v[172:175], v[212:215], v[68:71]
	v_mfma_f32_16x16x32_bf16 v[64:67], v[180:183], v[212:215], v[64:67]
	s_setprio 0
	s_barrier
; #define PG8_STAGE(bufoff, gbase, voff) do { _Pragma("unroll") for (int _i = 0; _i < 2; ++_i) \
;         __builtin_amdgcn_global_load_lds((const unsigned*)((const char*)(gbase) + (voff)[_i]), (PG8_LAS unsigned*)(lds + (bufoff) + ldsw + _i * 8192), 16, 0, 0); } while (0)
; #define PG8_LDA(dst, b, h) do { _Pragma("unroll") for (int m = 0; m < 4; ++m) _Pragma("unroll") for (int k = 0; k < 2; ++k) dst[m][k] = *(const PG8_LAS bf16x8*)(lds + PG8_SA(b, h) + aoff + m * 2048 + k * 1024); } while (0)
; #define PG8_MMA(ai, bj, At, Bt) do { __builtin_amdgcn_s_setprio(1); _Pragma("unroll") for (int m = 0; m < 4; ++m) _Pragma("unroll") for (int n = 0; n < 2; ++n) _Pragma("unroll") for (int k = 0; k < 2; ++k) \
;         acc[ai][bj][m][n] = __builtin_amdgcn_mfma_f32_16x16x32_bf16(Bt[n][k], At[m][k], acc[ai][bj][m][n], 0, 0, 0); __builtin_amdgcn_s_setprio(0); } while (0)
; #define PG8_WAIT_V(n) asm volatile("s_waitcnt vmcnt(" #n ")" ::: "memory")
; #define PG8_WAIT_L(n) asm volatile("s_waitcnt lgkmcnt(" #n ")" ::: "memory")
; #define PG8_BAR __builtin_amdgcn_s_barrier()
; #define PG8_SCHED __builtin_amdgcn_sched_barrier(0)
; template <class Epi, class Sched, bool ALIGN_EPI = false, bool SP2 = false>
; __device__ __forceinline__ void gemm_phase(PG8_LAS unsigned char* lds, const Gemm g, const Sched& S, const Epi& E) {
;     ...
;             PG8_LDA(At, 1, 1); PG8_STAGE(PG8_SB(1, 0), b3, voffB); PG8_STAGE(PG8_SB(1, 1), b3 + hstep, voffB); PG8_STAGE(PG8_SA(1, 0), a3, voffA);
;             PG8_WAIT_V(8); PG8_WAIT_L(0); PG8_BAR; PG8_MMA(1, 0, At, B0); PG8_MMA(1, 1, At, B1); PG8_BAR; PG8_SCHED;
	s_add_i32 s58, s86, s60
	v_lshl_add_u64 v[216:217], v[216:217], 0, s[10:11]
	s_mov_b32 m0, s58
	ds_read_b128 v[184:187], v149 offset:49152
	ds_read_b128 v[188:191], v149 offset:50176
	ds_read_b128 v[192:195], v149 offset:51200
	ds_read_b128 v[196:199], v149 offset:52224
	ds_read_b128 v[200:203], v149 offset:53248
	ds_read_b128 v[204:207], v149 offset:54272
	ds_read_b128 v[208:211], v149 offset:55296
	ds_read_b128 v[212:215], v149 offset:56320
	global_load_lds_dwordx4 v[216:217], off
	s_add_i32 m0, s58, 0x2000
	s_add_u32 s56, s56, 0x40080
	v_lshl_add_u64 v[216:217], v[218:219], 0, s[10:11]
	s_addc_u32 s57, s57, 0
	s_add_i32 s58, s87, s60
	global_load_lds_dwordx4 v[216:217], off
	v_lshl_add_u64 v[216:217], s[56:57], 0, v[130:131]
	s_mov_b32 m0, s58
	s_nop 0
	global_load_lds_dwordx4 v[216:217], off
	v_lshl_add_u64 v[216:217], s[56:57], 0, v[134:135]
	s_add_i32 m0, s58, 0x2000
	s_nop 0
	global_load_lds_dwordx4 v[216:217], off
	v_lshl_add_u64 v[216:217], v[220:221], 0, s[10:11]
	s_mov_b32 m0, s70
	s_nop 0
	global_load_lds_dwordx4 v[216:217], off
	v_lshl_add_u64 v[216:217], v[222:223], 0, s[10:11]
	s_mov_b32 m0, s71
	s_nop 0
	global_load_lds_dwordx4 v[216:217], off
	s_waitcnt vmcnt(8)
	s_waitcnt lgkmcnt(0)
	s_barrier
	s_setprio 1
	s_waitcnt lgkmcnt(0)
	v_mfma_f32_16x16x32_bf16 v[60:63], v[152:155], v[184:187], v[60:63]
	v_mfma_f32_16x16x32_bf16 v[56:59], v[160:163], v[184:187], v[56:59]
	v_mfma_f32_16x16x32_bf16 v[52:55], v[152:155], v[192:195], v[52:55]
	v_mfma_f32_16x16x32_bf16 v[48:51], v[160:163], v[192:195], v[48:51]
	v_mfma_f32_16x16x32_bf16 v[36:39], v[152:155], v[200:203], v[36:39]
	v_mfma_f32_16x16x32_bf16 v[32:35], v[160:163], v[200:203], v[32:35]
	v_mfma_f32_16x16x32_bf16 v[20:23], v[152:155], v[208:211], v[20:23]
	v_mfma_f32_16x16x32_bf16 v[16:19], v[160:163], v[208:211], v[16:19]
	s_setprio 0
	s_setprio 1
	v_mfma_f32_16x16x32_bf16 v[60:63], v[156:159], v[188:191], v[60:63]
	v_mfma_f32_16x16x32_bf16 v[56:59], v[164:167], v[188:191], v[56:59]
	v_mfma_f32_16x16x32_bf16 v[52:55], v[156:159], v[196:199], v[52:55]
	v_mfma_f32_16x16x32_bf16 v[48:51], v[164:167], v[196:199], v[48:51]
	v_mfma_f32_16x16x32_bf16 v[36:39], v[156:159], v[204:207], v[36:39]
	v_mfma_f32_16x16x32_bf16 v[32:35], v[164:167], v[204:207], v[32:35]
	v_mfma_f32_16x16x32_bf16 v[20:23], v[156:159], v[212:215], v[20:23]
	v_mfma_f32_16x16x32_bf16 v[16:19], v[164:167], v[212:215], v[16:19]
	s_setprio 0
	s_setprio 1
	v_mfma_f32_16x16x32_bf16 v[44:47], v[168:171], v[184:187], v[44:47]
	v_mfma_f32_16x16x32_bf16 v[40:43], v[176:179], v[184:187], v[40:43]
	v_mfma_f32_16x16x32_bf16 v[28:31], v[168:171], v[192:195], v[28:31]
	v_mfma_f32_16x16x32_bf16 v[24:27], v[176:179], v[192:195], v[24:27]
	v_mfma_f32_16x16x32_bf16 v[12:15], v[168:171], v[200:203], v[12:15]
	v_mfma_f32_16x16x32_bf16 v[8:11], v[176:179], v[200:203], v[8:11]
	v_mfma_f32_16x16x32_bf16 v[4:7], v[168:171], v[208:211], v[4:7]
	v_mfma_f32_16x16x32_bf16 v[0:3], v[176:179], v[208:211], v[0:3]
	s_setprio 0
	s_setprio 1
	v_mfma_f32_16x16x32_bf16 v[44:47], v[172:175], v[188:191], v[44:47]
	v_mfma_f32_16x16x32_bf16 v[40:43], v[180:183], v[188:191], v[40:43]
	v_mfma_f32_16x16x32_bf16 v[28:31], v[172:175], v[196:199], v[28:31]
	v_mfma_f32_16x16x32_bf16 v[24:27], v[180:183], v[196:199], v[24:27]
	v_mfma_f32_16x16x32_bf16 v[12:15], v[172:175], v[204:207], v[12:15]
	v_mfma_f32_16x16x32_bf16 v[8:11], v[180:183], v[204:207], v[8:11]
	v_mfma_f32_16x16x32_bf16 v[4:7], v[172:175], v[212:215], v[4:7]
	v_mfma_f32_16x16x32_bf16 v[0:3], v[180:183], v[212:215], v[0:3]
	s_setprio 0
	s_barrier
	s_add_i32 s85, s85, 2
	s_add_u32 s54, s54, 0x100
	s_addc_u32 s55, s55, 0
	s_add_u32 s83, s83, 0x100
	s_addc_u32 s84, s84, 0
	s_cmp_gt_u32 s85, 13
	s_cbranch_scc0 .LBB0_1460
	s_and_b64 vcc, exec, s[12:13]
	s_cbranch_vccz .LBB0_1463
	s_barrier

; #define PG8_STAGE(bufoff, gbase, voff) do { _Pragma("unroll") for (int _i = 0; _i < 2; ++_i) \
;         __builtin_amdgcn_global_load_lds((const unsigned*)((const char*)(gbase) + (voff)[_i]), (PG8_LAS unsigned*)(lds + (bufoff) + ldsw + _i * 8192), 16, 0, 0); } while (0)
; #define PG8_LDA(dst, b, h) do { _Pragma("unroll") for (int m = 0; m < 4; ++m) _Pragma("unroll") for (int k = 0; k < 2; ++k) dst[m][k] = *(const PG8_LAS bf16x8*)(lds + PG8_SA(b, h) + aoff + m * 2048 + k * 1024); } while (0)
; #define PG8_LDB(dst, b, h) do { _Pragma("unroll") for (int n = 0; n < 2; ++n) _Pragma("unroll") for (int k = 0; k < 2; ++k) dst[n][k] = *(const PG8_LAS bf16x8*)(lds + PG8_SB(b, h) + boff + n * 2048 + k * 1024); } while (0)
; #define PG8_MMA(ai, bj, At, Bt) do { __builtin_amdgcn_s_setprio(1); _Pragma("unroll") for (int m = 0; m < 4; ++m) _Pragma("unroll") for (int n = 0; n < 2; ++n) _Pragma("unroll") for (int k = 0; k < 2; ++k) \
;         acc[ai][bj][m][n] = __builtin_amdgcn_mfma_f32_16x16x32_bf16(Bt[n][k], At[m][k], acc[ai][bj][m][n], 0, 0, 0); __builtin_amdgcn_s_setprio(0); } while (0)
; #define PG8_WAIT_V(n) asm volatile("s_waitcnt vmcnt(" #n ")" ::: "memory")
; #define PG8_WAIT_L(n) asm volatile("s_waitcnt lgkmcnt(" #n ")" ::: "memory")
; template <class Epi, class Sched, bool ALIGN_EPI = false, bool SP2 = false>
; __device__ __forceinline__ void gemm_phase(PG8_LAS unsigned char* lds, const Gemm g, const Sched& S, const Epi& E) {
;     ...
;             const bool last = (t == nt - 2);
;             const char* a1 = cA + (size_t)(t + 1) * kstep;
;             const char* a2 = last ? nA : cA + (size_t)(t + 2) * kstep; const char* b2 = last ? nB : cB + (size_t)(t + 2) * kstep;
;             const char* a3 = a2 + kstep; const char* b3 = b2 + kstep;
;             if (last && has_next) S.a_ready(nxt);
;             if constexpr (SP2) {
;             PG8_LDB(B0, 0, 0); PG8_LDB(B1, 0, 1); PG8_SCHED; PG8_LDA(At, 0, 0); PG8_STAGE(PG8_SA(1, 1), a1 + hstep, voffA);
;             PG8_WAIT_V(8); PG8_WAIT_L(0); PG8_BAR; PG8_MMA(0, 0, At, B0); PG8_MMA(0, 1, At, B1); PG8_BAR; PG8_SCHED;
;             PG8_LDA(At, 0, 1); PG8_STAGE(PG8_SB(0, 0), b2, voffB); PG8_STAGE(PG8_SB(0, 1), b2 + hstep, voffB); PG8_STAGE(PG8_SA(0, 0), a2, voffA);
;             PG8_WAIT_V(8); PG8_WAIT_L(0); PG8_BAR; PG8_MMA(1, 0, At, B0); PG8_MMA(1, 1, At, B1); PG8_BAR; PG8_SCHED;
.LBB0_1535:
	ds_read_b128 v[146:149], v153
	ds_read_b128 v[156:159], v153 offset:1024
	ds_read_b128 v[160:163], v153 offset:2048
	ds_read_b128 v[164:167], v153 offset:3072
	ds_read_b128 v[168:171], v154
	ds_read_b128 v[172:175], v154 offset:1024
	ds_read_b128 v[176:179], v154 offset:2048
	ds_read_b128 v[180:183], v154 offset:3072
	s_add_u32 s44, s42, 0xfffc0080
	s_addc_u32 s45, s43, -1
	s_cmp_eq_u32 s70, 12
	s_cselect_b32 s47, s23, s45
	s_cselect_b32 s46, s66, s44
	s_cselect_b32 s45, s19, s69
	s_cselect_b32 s44, s67, s68
	v_lshl_add_u64 v[216:217], s[42:43], 0, v[136:137]
	s_add_i32 m0, s41, 0xc000
	ds_read_b128 v[184:187], v155
	ds_read_b128 v[188:191], v155 offset:1024
	ds_read_b128 v[192:195], v155 offset:2048
	ds_read_b128 v[196:199], v155 offset:3072
	ds_read_b128 v[200:203], v155 offset:4096
	ds_read_b128 v[204:207], v155 offset:5120
	ds_read_b128 v[208:211], v155 offset:6144
	ds_read_b128 v[212:215], v155 offset:7168
	global_load_lds_dwordx4 v[216:217], off
	v_lshl_add_u64 v[216:217], s[42:43], 0, v[138:139]
	s_add_i32 m0, s41, 0xe000
	s_nop 0
	global_load_lds_dwordx4 v[216:217], off
	s_waitcnt vmcnt(8)
	s_waitcnt lgkmcnt(0)
	s_barrier
	s_setprio 1
	s_waitcnt lgkmcnt(0)
	v_mfma_f32_16x16x32_bf16 v[124:127], v[146:149], v[184:187], v[124:127]
	v_mfma_f32_16x16x32_bf16 v[120:123], v[160:163], v[184:187], v[120:123]
	v_mfma_f32_16x16x32_bf16 v[108:111], v[146:149], v[192:195], v[108:111]
	v_mfma_f32_16x16x32_bf16 v[104:107], v[160:163], v[192:195], v[104:107]
	v_mfma_f32_16x16x32_bf16 v[92:95], v[146:149], v[200:203], v[92:95]
	v_mfma_f32_16x16x32_bf16 v[88:91], v[160:163], v[200:203], v[88:91]
	v_mfma_f32_16x16x32_bf16 v[76:79], v[146:149], v[208:211], v[76:79]
	v_mfma_f32_16x16x32_bf16 v[72:75], v[160:163], v[208:211], v[72:75]
	s_setprio 0
	s_setprio 1
	v_mfma_f32_16x16x32_bf16 v[124:127], v[156:159], v[188:191], v[124:127]
	v_mfma_f32_16x16x32_bf16 v[120:123], v[164:167], v[188:191], v[120:123]
	v_mfma_f32_16x16x32_bf16 v[108:111], v[156:159], v[196:199], v[108:111]
	v_mfma_f32_16x16x32_bf16 v[104:107], v[164:167], v[196:199], v[104:107]
	v_mfma_f32_16x16x32_bf16 v[92:95], v[156:159], v[204:207], v[92:95]
	v_mfma_f32_16x16x32_bf16 v[88:91], v[164:167], v[204:207], v[88:91]
	v_mfma_f32_16x16x32_bf16 v[76:79], v[156:159], v[212:215], v[76:79]
	v_mfma_f32_16x16x32_bf16 v[72:75], v[164:167], v[212:215], v[72:75]
	s_setprio 0
	s_setprio 1
	v_mfma_f32_16x16x32_bf16 v[116:119], v[168:171], v[184:187], v[116:119]
	v_mfma_f32_16x16x32_bf16 v[112:115], v[176:179], v[184:187], v[112:115]
	v_mfma_f32_16x16x32_bf16 v[100:103], v[168:171], v[192:195], v[100:103]
	v_mfma_f32_16x16x32_bf16 v[96:99], v[176:179], v[192:195], v[96:99]
	v_mfma_f32_16x16x32_bf16 v[84:87], v[168:171], v[200:203], v[84:87]
	v_mfma_f32_16x16x32_bf16 v[80:83], v[176:179], v[200:203], v[80:83]
	v_mfma_f32_16x16x32_bf16 v[68:71], v[168:171], v[208:211], v[68:71]
	v_mfma_f32_16x16x32_bf16 v[64:67], v[176:179], v[208:211], v[64:67]
	s_setprio 0
	s_setprio 1
	v_mfma_f32_16x16x32_bf16 v[116:119], v[172:175], v[188:191], v[116:119]
	v_mfma_f32_16x16x32_bf16 v[112:115], v[180:183], v[188:191], v[112:115]
	v_mfma_f32_16x16x32_bf16 v[100:103], v[172:175], v[196:199], v[100:103]
	v_mfma_f32_16x16x32_bf16 v[96:99], v[180:183], v[196:199], v[96:99]
	v_mfma_f32_16x16x32_bf16 v[84:87], v[172:175], v[204:207], v[84:87]
	v_mfma_f32_16x16x32_bf16 v[80:83], v[180:183], v[204:207], v[80:83]
	v_mfma_f32_16x16x32_bf16 v[68:71], v[172:175], v[212:215], v[68:71]
	v_mfma_f32_16x16x32_bf16 v[64:67], v[180:183], v[212:215], v[64:67]
	s_setprio 0
	s_barrier
	s_add_i32 s71, s62, s50
	v_lshl_add_u64 v[216:217], s[44:45], 0, v[130:131]
	s_mov_b32 m0, s71
	ds_read_b128 v[184:187], v155 offset:16384
	ds_read_b128 v[188:191], v155 offset:17408
	ds_read_b128 v[192:195], v155 offset:18432
	ds_read_b128 v[196:199], v155 offset:19456
	ds_read_b128 v[200:203], v155 offset:20480
	ds_read_b128 v[204:207], v155 offset:21504
	ds_read_b128 v[208:211], v155 offset:22528
	ds_read_b128 v[212:215], v155 offset:23552
	global_load_lds_dwordx4 v[216:217], off
	s_add_i32 m0, s71, 0x2000
	s_add_u32 s72, s44, 0x40000
	v_lshl_add_u64 v[218:219], s[44:45], 0, v[134:135]
	s_addc_u32 s73, s45, 0
	s_add_i32 s71, s63, s50
	global_load_lds_dwordx4 v[218:219], off
	v_lshl_add_u64 v[220:221], s[72:73], 0, v[130:131]
	s_mov_b32 m0, s71
	v_lshl_add_u64 v[222:223], s[46:47], 0, v[132:133]
	global_load_lds_dwordx4 v[220:221], off
	v_lshl_add_u64 v[220:221], s[72:73], 0, v[134:135]
	s_add_i32 m0, s71, 0x2000
	s_nop 0
	global_load_lds_dwordx4 v[220:221], off
	v_lshl_add_u64 v[220:221], s[46:47], 0, v[128:129]
	s_mov_b32 m0, s41
	s_nop 0
	global_load_lds_dwordx4 v[220:221], off
	s_mov_b32 m0, s52
	s_nop 0
	global_load_lds_dwordx4 v[222:223], off
	s_waitcnt vmcnt(8)
	s_waitcnt lgkmcnt(0)
	s_barrier
; #define PG8_STAGE(bufoff, gbase, voff) do { _Pragma("unroll") for (int _i = 0; _i < 2; ++_i) \
;         __builtin_amdgcn_global_load_lds((const unsigned*)((const char*)(gbase) + (voff)[_i]), (PG8_LAS unsigned*)(lds + (bufoff) + ldsw + _i * 8192), 16, 0, 0); } while (0)
; #define PG8_LDA(dst, b, h) do { _Pragma("unroll") for (int m = 0; m < 4; ++m) _Pragma("unroll") for (int k = 0; k < 2; ++k) dst[m][k] = *(const PG8_LAS bf16x8*)(lds + PG8_SA(b, h) + aoff + m * 2048 + k * 1024); } while (0)
; #define PG8_LDB(dst, b, h) do { _Pragma("unroll") for (int n = 0; n < 2; ++n) _Pragma("unroll") for (int k = 0; k < 2; ++k) dst[n][k] = *(const PG8_LAS bf16x8*)(lds + PG8_SB(b, h) + boff + n * 2048 + k * 1024); } while (0)
; #define PG8_MMA(ai, bj, At, Bt) do { __builtin_amdgcn_s_setprio(1); _Pragma("unroll") for (int m = 0; m < 4; ++m) _Pragma("unroll") for (int n = 0; n < 2; ++n) _Pragma("unroll") for (int k = 0; k < 2; ++k) \
;         acc[ai][bj][m][n] = __builtin_amdgcn_mfma_f32_16x16x32_bf16(Bt[n][k], At[m][k], acc[ai][bj][m][n], 0, 0, 0); __builtin_amdgcn_s_setprio(0); } while (0)
; #define PG8_WAIT_V(n) asm volatile("s_waitcnt vmcnt(" #n ")" ::: "memory")
; #define PG8_WAIT_L(n) asm volatile("s_waitcnt lgkmcnt(" #n ")" ::: "memory")
; #define PG8_BAR __builtin_amdgcn_s_barrier()
; #define PG8_SCHED __builtin_amdgcn_sched_barrier(0)
; template <class Epi, class Sched, bool ALIGN_EPI = false, bool SP2 = false>
; __device__ __forceinline__ void gemm_phase(PG8_LAS unsigned char* lds, const Gemm g, const Sched& S, const Epi& E) {
;     ...
;             PG8_WAIT_V(8); PG8_WAIT_L(0); PG8_BAR; PG8_MMA(1, 0, At, B0); PG8_MMA(1, 1, At, B1); PG8_BAR; PG8_SCHED;
;             PG8_LDB(B0, 1, 0); PG8_LDB(B1, 1, 1); PG8_SCHED; PG8_LDA(At, 1, 0); PG8_STAGE(PG8_SA(0, 1), a2 + hstep, voffA);
;             PG8_WAIT_V(8); PG8_WAIT_L(0); PG8_BAR; PG8_MMA(0, 0, At, B0); PG8_MMA(0, 1, At, B1); PG8_BAR; PG8_SCHED;
	s_setprio 1
	s_waitcnt lgkmcnt(0)
	v_mfma_f32_16x16x32_bf16 v[60:63], v[146:149], v[184:187], v[60:63]
	v_mfma_f32_16x16x32_bf16 v[56:59], v[160:163], v[184:187], v[56:59]
	v_mfma_f32_16x16x32_bf16 v[44:47], v[146:149], v[192:195], v[44:47]
	v_mfma_f32_16x16x32_bf16 v[40:43], v[160:163], v[192:195], v[40:43]
	v_mfma_f32_16x16x32_bf16 v[28:31], v[146:149], v[200:203], v[28:31]
	v_mfma_f32_16x16x32_bf16 v[24:27], v[160:163], v[200:203], v[24:27]
	v_mfma_f32_16x16x32_bf16 v[12:15], v[146:149], v[208:211], v[12:15]
	v_mfma_f32_16x16x32_bf16 v[8:11], v[160:163], v[208:211], v[8:11]
	s_setprio 0
	s_setprio 1
	v_mfma_f32_16x16x32_bf16 v[60:63], v[156:159], v[188:191], v[60:63]
	v_mfma_f32_16x16x32_bf16 v[56:59], v[164:167], v[188:191], v[56:59]
	v_mfma_f32_16x16x32_bf16 v[44:47], v[156:159], v[196:199], v[44:47]
	v_mfma_f32_16x16x32_bf16 v[40:43], v[164:167], v[196:199], v[40:43]
	v_mfma_f32_16x16x32_bf16 v[28:31], v[156:159], v[204:207], v[28:31]
	v_mfma_f32_16x16x32_bf16 v[24:27], v[164:167], v[204:207], v[24:27]
	v_mfma_f32_16x16x32_bf16 v[12:15], v[156:159], v[212:215], v[12:15]
	v_mfma_f32_16x16x32_bf16 v[8:11], v[164:167], v[212:215], v[8:11]
	s_setprio 0
	s_setprio 1
	v_mfma_f32_16x16x32_bf16 v[52:55], v[168:171], v[184:187], v[52:55]
	v_mfma_f32_16x16x32_bf16 v[48:51], v[176:179], v[184:187], v[48:51]
	v_mfma_f32_16x16x32_bf16 v[36:39], v[168:171], v[192:195], v[36:39]
	v_mfma_f32_16x16x32_bf16 v[32:35], v[176:179], v[192:195], v[32:35]
	v_mfma_f32_16x16x32_bf16 v[20:23], v[168:171], v[200:203], v[20:23]
	v_mfma_f32_16x16x32_bf16 v[16:19], v[176:179], v[200:203], v[16:19]
	v_mfma_f32_16x16x32_bf16 v[4:7], v[168:171], v[208:211], v[4:7]
	v_mfma_f32_16x16x32_bf16 v[0:3], v[176:179], v[208:211], v[0:3]
	s_setprio 0
	s_setprio 1
	v_mfma_f32_16x16x32_bf16 v[52:55], v[172:175], v[188:191], v[52:55]
	v_mfma_f32_16x16x32_bf16 v[48:51], v[180:183], v[188:191], v[48:51]
	v_mfma_f32_16x16x32_bf16 v[36:39], v[172:175], v[196:199], v[36:39]
	v_mfma_f32_16x16x32_bf16 v[32:35], v[180:183], v[196:199], v[32:35]
	v_mfma_f32_16x16x32_bf16 v[20:23], v[172:175], v[204:207], v[20:23]
	v_mfma_f32_16x16x32_bf16 v[16:19], v[180:183], v[204:207], v[16:19]
	v_mfma_f32_16x16x32_bf16 v[4:7], v[172:175], v[212:215], v[4:7]
	v_mfma_f32_16x16x32_bf16 v[0:3], v[180:183], v[212:215], v[0:3]
	s_setprio 0
	s_barrier
	s_add_i32 s71, 0, 0x18000
	s_add_i32 s72, 0, 0x1c000
	v_add_u32_e32 v164, s71, v152
	v_add_u32_e32 v180, s72, v152
	ds_read_b128 v[146:149], v164
	ds_read_b128 v[156:159], v164 offset:1024
	ds_read_b128 v[160:163], v164 offset:2048
	ds_read_b128 v[164:167], v164 offset:3072
	ds_read_b128 v[168:171], v180
	ds_read_b128 v[172:175], v180 offset:1024
	ds_read_b128 v[176:179], v180 offset:2048
	ds_read_b128 v[180:183], v180 offset:3072
	s_add_u32 s46, s46, 0x40000
	s_addc_u32 s47, s47, 0
	s_mov_b32 m0, s53
	v_lshl_add_u64 v[224:225], s[46:47], 0, v[128:129]
	ds_read_b128 v[184:187], v155 offset:32768
	ds_read_b128 v[188:191], v155 offset:33792
	ds_read_b128 v[192:195], v155 offset:34816
	ds_read_b128 v[196:199], v155 offset:35840
	ds_read_b128 v[200:203], v155 offset:36864
	ds_read_b128 v[204:207], v155 offset:37888
	ds_read_b128 v[208:211], v155 offset:38912
	ds_read_b128 v[212:215], v155 offset:39936
	global_load_lds_dwordx4 v[224:225], off
	v_lshl_add_u64 v[224:225], s[46:47], 0, v[132:133]
	s_mov_b32 m0, s54
	s_nop 0
	global_load_lds_dwordx4 v[224:225], off
	s_waitcnt vmcnt(8)
	s_waitcnt lgkmcnt(0)
	s_barrier
	s_setprio 1
	s_waitcnt lgkmcnt(0)
	v_mfma_f32_16x16x32_bf16 v[124:127], v[146:149], v[184:187], v[124:127]
	v_mfma_f32_16x16x32_bf16 v[120:123], v[160:163], v[184:187], v[120:123]
	v_mfma_f32_16x16x32_bf16 v[108:111], v[146:149], v[192:195], v[108:111]
	v_mfma_f32_16x16x32_bf16 v[104:107], v[160:163], v[192:195], v[104:107]
	v_mfma_f32_16x16x32_bf16 v[92:95], v[146:149], v[200:203], v[92:95]
	v_mfma_f32_16x16x32_bf16 v[88:91], v[160:163], v[200:203], v[88:91]
	v_mfma_f32_16x16x32_bf16 v[76:79], v[146:149], v[208:211], v[76:79]
	v_mfma_f32_16x16x32_bf16 v[72:75], v[160:163], v[208:211], v[72:75]
	s_setprio 0
	s_setprio 1
	v_mfma_f32_16x16x32_bf16 v[124:127], v[156:159], v[188:191], v[124:127]
	v_mfma_f32_16x16x32_bf16 v[120:123], v[164:167], v[188:191], v[120:123]
	v_mfma_f32_16x16x32_bf16 v[108:111], v[156:159], v[196:199], v[108:111]
	v_mfma_f32_16x16x32_bf16 v[104:107], v[164:167], v[196:199], v[104:107]
	v_mfma_f32_16x16x32_bf16 v[92:95], v[156:159], v[204:207], v[92:95]
	v_mfma_f32_16x16x32_bf16 v[88:91], v[164:167], v[204:207], v[88:91]
	v_mfma_f32_16x16x32_bf16 v[76:79], v[156:159], v[212:215], v[76:79]
	v_mfma_f32_16x16x32_bf16 v[72:75], v[164:167], v[212:215], v[72:75]
	s_setprio 0
	s_setprio 1
	v_mfma_f32_16x16x32_bf16 v[116:119], v[168:171], v[184:187], v[116:119]
	v_mfma_f32_16x16x32_bf16 v[112:115], v[176:179], v[184:187], v[112:115]
	v_mfma_f32_16x16x32_bf16 v[100:103], v[168:171], v[192:195], v[100:103]
	v_mfma_f32_16x16x32_bf16 v[96:99], v[176:179], v[192:195], v[96:99]
	v_mfma_f32_16x16x32_bf16 v[84:87], v[168:171], v[200:203], v[84:87]
	v_mfma_f32_16x16x32_bf16 v[80:83], v[176:179], v[200:203], v[80:83]
	v_mfma_f32_16x16x32_bf16 v[68:71], v[168:171], v[208:211], v[68:71]
	v_mfma_f32_16x16x32_bf16 v[64:67], v[176:179], v[208:211], v[64:67]
	s_setprio 0
	s_setprio 1
	v_mfma_f32_16x16x32_bf16 v[116:119], v[172:175], v[188:191], v[116:119]
	v_mfma_f32_16x16x32_bf16 v[112:115], v[180:183], v[188:191], v[112:115]
	v_mfma_f32_16x16x32_bf16 v[100:103], v[172:175], v[196:199], v[100:103]
	v_mfma_f32_16x16x32_bf16 v[96:99], v[180:183], v[196:199], v[96:99]
	v_mfma_f32_16x16x32_bf16 v[84:87], v[172:175], v[204:207], v[84:87]
	v_mfma_f32_16x16x32_bf16 v[80:83], v[180:183], v[204:207], v[80:83]
	v_mfma_f32_16x16x32_bf16 v[68:71], v[172:175], v[212:215], v[68:71]
	v_mfma_f32_16x16x32_bf16 v[64:67], v[180:183], v[212:215], v[64:67]
	s_setprio 0
	s_barrier
; #define PG8_STAGE(bufoff, gbase, voff) do { _Pragma("unroll") for (int _i = 0; _i < 2; ++_i) \
;         __builtin_amdgcn_global_load_lds((const unsigned*)((const char*)(gbase) + (voff)[_i]), (PG8_LAS unsigned*)(lds + (bufoff) + ldsw + _i * 8192), 16, 0, 0); } while (0)
; #define PG8_LDA(dst, b, h) do { _Pragma("unroll") for (int m = 0; m < 4; ++m) _Pragma("unroll") for (int k = 0; k < 2; ++k) dst[m][k] = *(const PG8_LAS bf16x8*)(lds + PG8_SA(b, h) + aoff + m * 2048 + k * 1024); } while (0)
; #define PG8_MMA(ai, bj, At, Bt) do { __builtin_amdgcn_s_setprio(1); _Pragma("unroll") for (int m = 0; m < 4; ++m) _Pragma("unroll") for (int n = 0; n < 2; ++n) _Pragma("unroll") for (int k = 0; k < 2; ++k) \
;         acc[ai][bj][m][n] = __builtin_amdgcn_mfma_f32_16x16x32_bf16(Bt[n][k], At[m][k], acc[ai][bj][m][n], 0, 0, 0); __builtin_amdgcn_s_setprio(0); } while (0)
; #define PG8_WAIT_V(n) asm volatile("s_waitcnt vmcnt(" #n ")" ::: "memory")
; #define PG8_WAIT_L(n) asm volatile("s_waitcnt lgkmcnt(" #n ")" ::: "memory")
; #define PG8_BAR __builtin_amdgcn_s_barrier()
; #define PG8_SCHED __builtin_amdgcn_sched_barrier(0)
; template <class Epi, class Sched, bool ALIGN_EPI = false, bool SP2 = false>
; __device__ __forceinline__ void gemm_phase(PG8_LAS unsigned char* lds, const Gemm g, const Sched& S, const Epi& E) {
;     ...
;             PG8_LDA(At, 1, 1); PG8_STAGE(PG8_SB(1, 0), b3, voffB); PG8_STAGE(PG8_SB(1, 1), b3 + hstep, voffB); PG8_STAGE(PG8_SA(1, 0), a3, voffA);
;             PG8_WAIT_V(8); PG8_WAIT_L(0); PG8_BAR; PG8_MMA(1, 0, At, B0); PG8_MMA(1, 1, At, B1); PG8_BAR; PG8_SCHED;
	s_add_i32 s46, s71, s50
	v_lshl_add_u64 v[216:217], v[216:217], 0, s[12:13]
	s_mov_b32 m0, s46
	ds_read_b128 v[184:187], v155 offset:49152
	ds_read_b128 v[188:191], v155 offset:50176
	ds_read_b128 v[192:195], v155 offset:51200
	ds_read_b128 v[196:199], v155 offset:52224
	ds_read_b128 v[200:203], v155 offset:53248
	ds_read_b128 v[204:207], v155 offset:54272
	ds_read_b128 v[208:211], v155 offset:55296
	ds_read_b128 v[212:215], v155 offset:56320
	global_load_lds_dwordx4 v[216:217], off
	s_add_i32 m0, s46, 0x2000
	s_add_u32 s44, s44, 0x40080
	v_lshl_add_u64 v[216:217], v[218:219], 0, s[12:13]
	s_addc_u32 s45, s45, 0
	s_add_i32 s46, s72, s50
	global_load_lds_dwordx4 v[216:217], off
	v_lshl_add_u64 v[216:217], s[44:45], 0, v[130:131]
	s_mov_b32 m0, s46
	s_nop 0
	global_load_lds_dwordx4 v[216:217], off
	v_lshl_add_u64 v[216:217], s[44:45], 0, v[134:135]
	s_add_i32 m0, s46, 0x2000
	s_nop 0
	global_load_lds_dwordx4 v[216:217], off
	v_lshl_add_u64 v[216:217], v[220:221], 0, s[12:13]
	s_mov_b32 m0, s59
	s_nop 0
	global_load_lds_dwordx4 v[216:217], off
	v_lshl_add_u64 v[216:217], v[222:223], 0, s[12:13]
	s_mov_b32 m0, s60
	s_nop 0
	global_load_lds_dwordx4 v[216:217], off
	s_waitcnt vmcnt(8)
	s_waitcnt lgkmcnt(0)
	s_barrier
	s_setprio 1
	s_waitcnt lgkmcnt(0)
	v_mfma_f32_16x16x32_bf16 v[60:63], v[146:149], v[184:187], v[60:63]
	v_mfma_f32_16x16x32_bf16 v[56:59], v[160:163], v[184:187], v[56:59]
	v_mfma_f32_16x16x32_bf16 v[44:47], v[146:149], v[192:195], v[44:47]
	v_mfma_f32_16x16x32_bf16 v[40:43], v[160:163], v[192:195], v[40:43]
	v_mfma_f32_16x16x32_bf16 v[28:31], v[146:149], v[200:203], v[28:31]
	v_mfma_f32_16x16x32_bf16 v[24:27], v[160:163], v[200:203], v[24:27]
	v_mfma_f32_16x16x32_bf16 v[12:15], v[146:149], v[208:211], v[12:15]
	v_mfma_f32_16x16x32_bf16 v[8:11], v[160:163], v[208:211], v[8:11]
	s_setprio 0
	s_setprio 1
	v_mfma_f32_16x16x32_bf16 v[60:63], v[156:159], v[188:191], v[60:63]
	v_mfma_f32_16x16x32_bf16 v[56:59], v[164:167], v[188:191], v[56:59]
	v_mfma_f32_16x16x32_bf16 v[44:47], v[156:159], v[196:199], v[44:47]
	v_mfma_f32_16x16x32_bf16 v[40:43], v[164:167], v[196:199], v[40:43]
	v_mfma_f32_16x16x32_bf16 v[28:31], v[156:159], v[204:207], v[28:31]
	v_mfma_f32_16x16x32_bf16 v[24:27], v[164:167], v[204:207], v[24:27]
	v_mfma_f32_16x16x32_bf16 v[12:15], v[156:159], v[212:215], v[12:15]
	v_mfma_f32_16x16x32_bf16 v[8:11], v[164:167], v[212:215], v[8:11]
	s_setprio 0
	s_setprio 1
	v_mfma_f32_16x16x32_bf16 v[52:55], v[168:171], v[184:187], v[52:55]
	v_mfma_f32_16x16x32_bf16 v[48:51], v[176:179], v[184:187], v[48:51]
	v_mfma_f32_16x16x32_bf16 v[36:39], v[168:171], v[192:195], v[36:39]
	v_mfma_f32_16x16x32_bf16 v[32:35], v[176:179], v[192:195], v[32:35]
	v_mfma_f32_16x16x32_bf16 v[20:23], v[168:171], v[200:203], v[20:23]
	v_mfma_f32_16x16x32_bf16 v[16:19], v[176:179], v[200:203], v[16:19]
	v_mfma_f32_16x16x32_bf16 v[4:7], v[168:171], v[208:211], v[4:7]
	v_mfma_f32_16x16x32_bf16 v[0:3], v[176:179], v[208:211], v[0:3]
	s_setprio 0
	s_setprio 1
	v_mfma_f32_16x16x32_bf16 v[52:55], v[172:175], v[188:191], v[52:55]
	v_mfma_f32_16x16x32_bf16 v[48:51], v[180:183], v[188:191], v[48:51]
	v_mfma_f32_16x16x32_bf16 v[36:39], v[172:175], v[196:199], v[36:39]
	v_mfma_f32_16x16x32_bf16 v[32:35], v[180:183], v[196:199], v[32:35]
	v_mfma_f32_16x16x32_bf16 v[20:23], v[172:175], v[204:207], v[20:23]
	v_mfma_f32_16x16x32_bf16 v[16:19], v[180:183], v[204:207], v[16:19]
	v_mfma_f32_16x16x32_bf16 v[4:7], v[172:175], v[212:215], v[4:7]
	v_mfma_f32_16x16x32_bf16 v[0:3], v[180:183], v[212:215], v[0:3]
	s_setprio 0
	s_barrier
	s_add_i32 s70, s70, 2
	s_add_u32 s42, s42, 0x100
	s_addc_u32 s43, s43, 0
	s_add_u32 s68, s68, 0x100
	s_addc_u32 s69, s69, 0
	s_cmp_gt_u32 s70, 13
	s_cbranch_scc0 .LBB0_1535
	s_and_b64 vcc, exec, s[14:15]
	s_cbranch_vccz .LBB0_1538
	s_barrier

; #define PG8_STAGE(bufoff, gbase, voff) do { _Pragma("unroll") for (int _i = 0; _i < 2; ++_i) \
;         __builtin_amdgcn_global_load_lds((const unsigned*)((const char*)(gbase) + (voff)[_i]), (PG8_LAS unsigned*)(lds + (bufoff) + ldsw + _i * 8192), 16, 0, 0); } while (0)
; #define PG8_LDA(dst, b, h) do { _Pragma("unroll") for (int m = 0; m < 4; ++m) _Pragma("unroll") for (int k = 0; k < 2; ++k) dst[m][k] = *(const PG8_LAS bf16x8*)(lds + PG8_SA(b, h) + aoff + m * 2048 + k * 1024); } while (0)
; #define PG8_LDB(dst, b, h) do { _Pragma("unroll") for (int n = 0; n < 2; ++n) _Pragma("unroll") for (int k = 0; k < 2; ++k) dst[n][k] = *(const PG8_LAS bf16x8*)(lds + PG8_SB(b, h) + boff + n * 2048 + k * 1024); } while (0)
; #define PG8_MMA(ai, bj, At, Bt) do { __builtin_amdgcn_s_setprio(1); _Pragma("unroll") for (int m = 0; m < 4; ++m) _Pragma("unroll") for (int n = 0; n < 2; ++n) _Pragma("unroll") for (int k = 0; k < 2; ++k) \
;         acc[ai][bj][m][n] = __builtin_amdgcn_mfma_f32_16x16x32_bf16(Bt[n][k], At[m][k], acc[ai][bj][m][n], 0, 0, 0); __builtin_amdgcn_s_setprio(0); } while (0)
; #define PG8_WAIT_V(n) asm volatile("s_waitcnt vmcnt(" #n ")" ::: "memory")
; #define PG8_WAIT_L(n) asm volatile("s_waitcnt lgkmcnt(" #n ")" ::: "memory")
; template <class Epi, class Sched, bool ALIGN_EPI = false, bool SP2 = false>
; __device__ __forceinline__ void gemm_phase(PG8_LAS unsigned char* lds, const Gemm g, const Sched& S, const Epi& E) {
;     ...
;             const bool last = (t == nt - 2);
;             const char* a1 = cA + (size_t)(t + 1) * kstep;
;             const char* a2 = last ? nA : cA + (size_t)(t + 2) * kstep; const char* b2 = last ? nB : cB + (size_t)(t + 2) * kstep;
;             const char* a3 = a2 + kstep; const char* b3 = b2 + kstep;
;             if (last && has_next) S.a_ready(nxt);
;             if constexpr (SP2) {
;             PG8_LDB(B0, 0, 0); PG8_LDB(B1, 0, 1); PG8_SCHED; PG8_LDA(At, 0, 0); PG8_STAGE(PG8_SA(1, 1), a1 + hstep, voffA);
;             PG8_WAIT_V(8); PG8_WAIT_L(0); PG8_BAR; PG8_MMA(0, 0, At, B0); PG8_MMA(0, 1, At, B1); PG8_BAR; PG8_SCHED;
;             PG8_LDA(At, 0, 1); PG8_STAGE(PG8_SB(0, 0), b2, voffB); PG8_STAGE(PG8_SB(0, 1), b2 + hstep, voffB); PG8_STAGE(PG8_SA(0, 0), a2, voffA);
;             PG8_WAIT_V(8); PG8_WAIT_L(0); PG8_BAR; PG8_MMA(1, 0, At, B0); PG8_MMA(1, 1, At, B1); PG8_BAR; PG8_SCHED;
.LBB0_1612:
	ds_read_b128 v[146:149], v153
	ds_read_b128 v[158:161], v153 offset:1024
	ds_read_b128 v[162:165], v153 offset:2048
	ds_read_b128 v[166:169], v153 offset:3072
	ds_read_b128 v[170:173], v154
	ds_read_b128 v[174:177], v154 offset:1024
	ds_read_b128 v[178:181], v154 offset:2048
	ds_read_b128 v[182:185], v154 offset:3072
	s_add_u32 s44, s42, 0xfff80080
	s_addc_u32 s45, s43, -1
	s_cmp_eq_u32 s69, 28
	s_cselect_b32 s47, s23, s45
	s_cselect_b32 s46, s41, s44
	s_cselect_b32 s45, s19, s68
	s_cselect_b32 s44, s66, s67
	v_lshl_add_u64 v[218:219], s[42:43], 0, v[136:137]
	s_add_i32 m0, s51, 0xc000
	ds_read_b128 v[186:189], v155
	ds_read_b128 v[190:193], v155 offset:1024
	ds_read_b128 v[194:197], v155 offset:2048
	ds_read_b128 v[198:201], v155 offset:3072
	ds_read_b128 v[202:205], v155 offset:4096
	ds_read_b128 v[206:209], v155 offset:5120
	ds_read_b128 v[210:213], v155 offset:6144
	ds_read_b128 v[214:217], v155 offset:7168
	global_load_lds_dwordx4 v[218:219], off
	v_lshl_add_u64 v[218:219], s[42:43], 0, v[138:139]
	s_add_i32 m0, s51, 0xe000
	s_nop 0
	global_load_lds_dwordx4 v[218:219], off
	s_waitcnt vmcnt(8)
	s_waitcnt lgkmcnt(0)
	s_barrier
	s_setprio 1
	s_waitcnt lgkmcnt(0)
	v_mfma_f32_16x16x32_bf16 v[124:127], v[146:149], v[186:189], v[124:127]
	v_mfma_f32_16x16x32_bf16 v[120:123], v[162:165], v[186:189], v[120:123]
	v_mfma_f32_16x16x32_bf16 v[108:111], v[146:149], v[194:197], v[108:111]
	v_mfma_f32_16x16x32_bf16 v[104:107], v[162:165], v[194:197], v[104:107]
	v_mfma_f32_16x16x32_bf16 v[92:95], v[146:149], v[202:205], v[92:95]
	v_mfma_f32_16x16x32_bf16 v[88:91], v[162:165], v[202:205], v[88:91]
	v_mfma_f32_16x16x32_bf16 v[76:79], v[146:149], v[210:213], v[76:79]
	v_mfma_f32_16x16x32_bf16 v[72:75], v[162:165], v[210:213], v[72:75]
	s_setprio 0
	s_setprio 1
	v_mfma_f32_16x16x32_bf16 v[124:127], v[158:161], v[190:193], v[124:127]
	v_mfma_f32_16x16x32_bf16 v[120:123], v[166:169], v[190:193], v[120:123]
	v_mfma_f32_16x16x32_bf16 v[108:111], v[158:161], v[198:201], v[108:111]
	v_mfma_f32_16x16x32_bf16 v[104:107], v[166:169], v[198:201], v[104:107]
	v_mfma_f32_16x16x32_bf16 v[92:95], v[158:161], v[206:209], v[92:95]
	v_mfma_f32_16x16x32_bf16 v[88:91], v[166:169], v[206:209], v[88:91]
	v_mfma_f32_16x16x32_bf16 v[76:79], v[158:161], v[214:217], v[76:79]
	v_mfma_f32_16x16x32_bf16 v[72:75], v[166:169], v[214:217], v[72:75]
	s_setprio 0
	s_setprio 1
	v_mfma_f32_16x16x32_bf16 v[116:119], v[170:173], v[186:189], v[116:119]
	v_mfma_f32_16x16x32_bf16 v[112:115], v[178:181], v[186:189], v[112:115]
	v_mfma_f32_16x16x32_bf16 v[100:103], v[170:173], v[194:197], v[100:103]
	v_mfma_f32_16x16x32_bf16 v[96:99], v[178:181], v[194:197], v[96:99]
	v_mfma_f32_16x16x32_bf16 v[84:87], v[170:173], v[202:205], v[84:87]
	v_mfma_f32_16x16x32_bf16 v[80:83], v[178:181], v[202:205], v[80:83]
	v_mfma_f32_16x16x32_bf16 v[68:71], v[170:173], v[210:213], v[68:71]
	v_mfma_f32_16x16x32_bf16 v[64:67], v[178:181], v[210:213], v[64:67]
	s_setprio 0
	s_setprio 1
	v_mfma_f32_16x16x32_bf16 v[116:119], v[174:177], v[190:193], v[116:119]
	v_mfma_f32_16x16x32_bf16 v[112:115], v[182:185], v[190:193], v[112:115]
	v_mfma_f32_16x16x32_bf16 v[100:103], v[174:177], v[198:201], v[100:103]
	v_mfma_f32_16x16x32_bf16 v[96:99], v[182:185], v[198:201], v[96:99]
	v_mfma_f32_16x16x32_bf16 v[84:87], v[174:177], v[206:209], v[84:87]
	v_mfma_f32_16x16x32_bf16 v[80:83], v[182:185], v[206:209], v[80:83]
	v_mfma_f32_16x16x32_bf16 v[68:71], v[174:177], v[214:217], v[68:71]
	v_mfma_f32_16x16x32_bf16 v[64:67], v[182:185], v[214:217], v[64:67]
	s_setprio 0
	s_barrier
	s_add_i32 s70, s63, s50
	v_lshl_add_u64 v[218:219], s[44:45], 0, v[130:131]
	s_mov_b32 m0, s70
	ds_read_b128 v[186:189], v155 offset:16384
	ds_read_b128 v[190:193], v155 offset:17408
	ds_read_b128 v[194:197], v155 offset:18432
	ds_read_b128 v[198:201], v155 offset:19456
	ds_read_b128 v[202:205], v155 offset:20480
	ds_read_b128 v[206:209], v155 offset:21504
	ds_read_b128 v[210:213], v155 offset:22528
	ds_read_b128 v[214:217], v155 offset:23552
	global_load_lds_dwordx4 v[218:219], off
	s_add_i32 m0, s70, 0x2000
	s_add_u32 s70, s44, 0x80000
	v_lshl_add_u64 v[220:221], s[44:45], 0, v[134:135]
	s_addc_u32 s71, s45, 0
	s_add_i32 s72, s64, s50
	global_load_lds_dwordx4 v[220:221], off
	v_lshl_add_u64 v[222:223], s[70:71], 0, v[130:131]
	s_mov_b32 m0, s72
	v_lshl_add_u64 v[224:225], s[46:47], 0, v[132:133]
	global_load_lds_dwordx4 v[222:223], off
	v_lshl_add_u64 v[222:223], s[70:71], 0, v[134:135]
	s_add_i32 m0, s72, 0x2000
	s_nop 0
	global_load_lds_dwordx4 v[222:223], off
	v_lshl_add_u64 v[222:223], s[46:47], 0, v[128:129]
	s_mov_b32 m0, s51
	s_nop 0
	global_load_lds_dwordx4 v[222:223], off
	s_mov_b32 m0, s52
	s_nop 0
	global_load_lds_dwordx4 v[224:225], off
	s_waitcnt vmcnt(8)
	s_waitcnt lgkmcnt(0)
	s_barrier
; #define PG8_STAGE(bufoff, gbase, voff) do { _Pragma("unroll") for (int _i = 0; _i < 2; ++_i) \
;         __builtin_amdgcn_global_load_lds((const unsigned*)((const char*)(gbase) + (voff)[_i]), (PG8_LAS unsigned*)(lds + (bufoff) + ldsw + _i * 8192), 16, 0, 0); } while (0)
; #define PG8_LDA(dst, b, h) do { _Pragma("unroll") for (int m = 0; m < 4; ++m) _Pragma("unroll") for (int k = 0; k < 2; ++k) dst[m][k] = *(const PG8_LAS bf16x8*)(lds + PG8_SA(b, h) + aoff + m * 2048 + k * 1024); } while (0)
; #define PG8_LDB(dst, b, h) do { _Pragma("unroll") for (int n = 0; n < 2; ++n) _Pragma("unroll") for (int k = 0; k < 2; ++k) dst[n][k] = *(const PG8_LAS bf16x8*)(lds + PG8_SB(b, h) + boff + n * 2048 + k * 1024); } while (0)
; #define PG8_MMA(ai, bj, At, Bt) do { __builtin_amdgcn_s_setprio(1); _Pragma("unroll") for (int m = 0; m < 4; ++m) _Pragma("unroll") for (int n = 0; n < 2; ++n) _Pragma("unroll") for (int k = 0; k < 2; ++k) \
;         acc[ai][bj][m][n] = __builtin_amdgcn_mfma_f32_16x16x32_bf16(Bt[n][k], At[m][k], acc[ai][bj][m][n], 0, 0, 0); __builtin_amdgcn_s_setprio(0); } while (0)
; #define PG8_WAIT_V(n) asm volatile("s_waitcnt vmcnt(" #n ")" ::: "memory")
; #define PG8_WAIT_L(n) asm volatile("s_waitcnt lgkmcnt(" #n ")" ::: "memory")
; #define PG8_BAR __builtin_amdgcn_s_barrier()
; #define PG8_SCHED __builtin_amdgcn_sched_barrier(0)
; template <class Epi, class Sched, bool ALIGN_EPI = false, bool SP2 = false>
; __device__ __forceinline__ void gemm_phase(PG8_LAS unsigned char* lds, const Gemm g, const Sched& S, const Epi& E) {
;     ...
;             PG8_WAIT_V(8); PG8_WAIT_L(0); PG8_BAR; PG8_MMA(1, 0, At, B0); PG8_MMA(1, 1, At, B1); PG8_BAR; PG8_SCHED;
;             PG8_LDB(B0, 1, 0); PG8_LDB(B1, 1, 1); PG8_SCHED; PG8_LDA(At, 1, 0); PG8_STAGE(PG8_SA(0, 1), a2 + hstep, voffA);
;             PG8_WAIT_V(8); PG8_WAIT_L(0); PG8_BAR; PG8_MMA(0, 0, At, B0); PG8_MMA(0, 1, At, B1); PG8_BAR; PG8_SCHED;
	s_setprio 1
	s_waitcnt lgkmcnt(0)
	v_mfma_f32_16x16x32_bf16 v[60:63], v[146:149], v[186:189], v[60:63]
	v_mfma_f32_16x16x32_bf16 v[56:59], v[162:165], v[186:189], v[56:59]
	v_mfma_f32_16x16x32_bf16 v[44:47], v[146:149], v[194:197], v[44:47]
	v_mfma_f32_16x16x32_bf16 v[40:43], v[162:165], v[194:197], v[40:43]
	v_mfma_f32_16x16x32_bf16 v[28:31], v[146:149], v[202:205], v[28:31]
	v_mfma_f32_16x16x32_bf16 v[24:27], v[162:165], v[202:205], v[24:27]
	v_mfma_f32_16x16x32_bf16 v[12:15], v[146:149], v[210:213], v[12:15]
	v_mfma_f32_16x16x32_bf16 v[8:11], v[162:165], v[210:213], v[8:11]
	s_setprio 0
	s_setprio 1
	v_mfma_f32_16x16x32_bf16 v[60:63], v[158:161], v[190:193], v[60:63]
	v_mfma_f32_16x16x32_bf16 v[56:59], v[166:169], v[190:193], v[56:59]
	v_mfma_f32_16x16x32_bf16 v[44:47], v[158:161], v[198:201], v[44:47]
	v_mfma_f32_16x16x32_bf16 v[40:43], v[166:169], v[198:201], v[40:43]
	v_mfma_f32_16x16x32_bf16 v[28:31], v[158:161], v[206:209], v[28:31]
	v_mfma_f32_16x16x32_bf16 v[24:27], v[166:169], v[206:209], v[24:27]
	v_mfma_f32_16x16x32_bf16 v[12:15], v[158:161], v[214:217], v[12:15]
	v_mfma_f32_16x16x32_bf16 v[8:11], v[166:169], v[214:217], v[8:11]
	s_setprio 0
	s_setprio 1
	v_mfma_f32_16x16x32_bf16 v[52:55], v[170:173], v[186:189], v[52:55]
	v_mfma_f32_16x16x32_bf16 v[48:51], v[178:181], v[186:189], v[48:51]
	v_mfma_f32_16x16x32_bf16 v[36:39], v[170:173], v[194:197], v[36:39]
	v_mfma_f32_16x16x32_bf16 v[32:35], v[178:181], v[194:197], v[32:35]
	v_mfma_f32_16x16x32_bf16 v[20:23], v[170:173], v[202:205], v[20:23]
	v_mfma_f32_16x16x32_bf16 v[16:19], v[178:181], v[202:205], v[16:19]
	v_mfma_f32_16x16x32_bf16 v[4:7], v[170:173], v[210:213], v[4:7]
	v_mfma_f32_16x16x32_bf16 v[0:3], v[178:181], v[210:213], v[0:3]
	s_setprio 0
	s_setprio 1
	v_mfma_f32_16x16x32_bf16 v[52:55], v[174:177], v[190:193], v[52:55]
	v_mfma_f32_16x16x32_bf16 v[48:51], v[182:185], v[190:193], v[48:51]
	v_mfma_f32_16x16x32_bf16 v[36:39], v[174:177], v[198:201], v[36:39]
	v_mfma_f32_16x16x32_bf16 v[32:35], v[182:185], v[198:201], v[32:35]
	v_mfma_f32_16x16x32_bf16 v[20:23], v[174:177], v[206:209], v[20:23]
	v_mfma_f32_16x16x32_bf16 v[16:19], v[182:185], v[206:209], v[16:19]
	v_mfma_f32_16x16x32_bf16 v[4:7], v[174:177], v[214:217], v[4:7]
	v_mfma_f32_16x16x32_bf16 v[0:3], v[182:185], v[214:217], v[0:3]
	s_setprio 0
	s_barrier
	s_add_i32 s70, 0, 0x18000
	v_add_u32_e32 v157, s70, v152
	s_add_i32 s71, 0, 0x1c000
	ds_read_b128 v[146:149], v157
	ds_read_b128 v[158:161], v157 offset:1024
	ds_read_b128 v[162:165], v157 offset:2048
	ds_read_b128 v[166:169], v157 offset:3072
	v_add_u32_e32 v157, s71, v152
	ds_read_b128 v[170:173], v157
	ds_read_b128 v[174:177], v157 offset:1024
	ds_read_b128 v[178:181], v157 offset:2048
	ds_read_b128 v[182:185], v157 offset:3072
	s_add_u32 s46, s46, 0x80000
	s_addc_u32 s47, s47, 0
	s_mov_b32 m0, s53
	v_lshl_add_u64 v[226:227], s[46:47], 0, v[128:129]
	ds_read_b128 v[186:189], v155 offset:32768
	ds_read_b128 v[190:193], v155 offset:33792
	ds_read_b128 v[194:197], v155 offset:34816
	ds_read_b128 v[198:201], v155 offset:35840
	ds_read_b128 v[202:205], v155 offset:36864
	ds_read_b128 v[206:209], v155 offset:37888
	ds_read_b128 v[210:213], v155 offset:38912
	ds_read_b128 v[214:217], v155 offset:39936
	global_load_lds_dwordx4 v[226:227], off
	v_lshl_add_u64 v[226:227], s[46:47], 0, v[132:133]
	s_mov_b32 m0, s54
	s_nop 0
	global_load_lds_dwordx4 v[226:227], off
	s_waitcnt vmcnt(8)
	s_waitcnt lgkmcnt(0)
	s_barrier
	s_setprio 1
	s_waitcnt lgkmcnt(0)
	v_mfma_f32_16x16x32_bf16 v[124:127], v[146:149], v[186:189], v[124:127]
	v_mfma_f32_16x16x32_bf16 v[120:123], v[162:165], v[186:189], v[120:123]
	v_mfma_f32_16x16x32_bf16 v[108:111], v[146:149], v[194:197], v[108:111]
	v_mfma_f32_16x16x32_bf16 v[104:107], v[162:165], v[194:197], v[104:107]
	v_mfma_f32_16x16x32_bf16 v[92:95], v[146:149], v[202:205], v[92:95]
	v_mfma_f32_16x16x32_bf16 v[88:91], v[162:165], v[202:205], v[88:91]
	v_mfma_f32_16x16x32_bf16 v[76:79], v[146:149], v[210:213], v[76:79]
	v_mfma_f32_16x16x32_bf16 v[72:75], v[162:165], v[210:213], v[72:75]
	s_setprio 0
	s_setprio 1
	v_mfma_f32_16x16x32_bf16 v[124:127], v[158:161], v[190:193], v[124:127]
	v_mfma_f32_16x16x32_bf16 v[120:123], v[166:169], v[190:193], v[120:123]
	v_mfma_f32_16x16x32_bf16 v[108:111], v[158:161], v[198:201], v[108:111]
	v_mfma_f32_16x16x32_bf16 v[104:107], v[166:169], v[198:201], v[104:107]
	v_mfma_f32_16x16x32_bf16 v[92:95], v[158:161], v[206:209], v[92:95]
	v_mfma_f32_16x16x32_bf16 v[88:91], v[166:169], v[206:209], v[88:91]
	v_mfma_f32_16x16x32_bf16 v[76:79], v[158:161], v[214:217], v[76:79]
	v_mfma_f32_16x16x32_bf16 v[72:75], v[166:169], v[214:217], v[72:75]
	s_setprio 0
	s_setprio 1
	v_mfma_f32_16x16x32_bf16 v[116:119], v[170:173], v[186:189], v[116:119]
	v_mfma_f32_16x16x32_bf16 v[112:115], v[178:181], v[186:189], v[112:115]
	v_mfma_f32_16x16x32_bf16 v[100:103], v[170:173], v[194:197], v[100:103]
	v_mfma_f32_16x16x32_bf16 v[96:99], v[178:181], v[194:197], v[96:99]
	v_mfma_f32_16x16x32_bf16 v[84:87], v[170:173], v[202:205], v[84:87]
	v_mfma_f32_16x16x32_bf16 v[80:83], v[178:181], v[202:205], v[80:83]
	v_mfma_f32_16x16x32_bf16 v[68:71], v[170:173], v[210:213], v[68:71]
	v_mfma_f32_16x16x32_bf16 v[64:67], v[178:181], v[210:213], v[64:67]
	s_setprio 0
	s_setprio 1
	v_mfma_f32_16x16x32_bf16 v[116:119], v[174:177], v[190:193], v[116:119]
	v_mfma_f32_16x16x32_bf16 v[112:115], v[182:185], v[190:193], v[112:115]
	v_mfma_f32_16x16x32_bf16 v[100:103], v[174:177], v[198:201], v[100:103]
	v_mfma_f32_16x16x32_bf16 v[96:99], v[182:185], v[198:201], v[96:99]
	v_mfma_f32_16x16x32_bf16 v[84:87], v[174:177], v[206:209], v[84:87]
	v_mfma_f32_16x16x32_bf16 v[80:83], v[182:185], v[206:209], v[80:83]
	v_mfma_f32_16x16x32_bf16 v[68:71], v[174:177], v[214:217], v[68:71]
	v_mfma_f32_16x16x32_bf16 v[64:67], v[182:185], v[214:217], v[64:67]
	s_setprio 0
	s_barrier
; #define PG8_STAGE(bufoff, gbase, voff) do { _Pragma("unroll") for (int _i = 0; _i < 2; ++_i) \
;         __builtin_amdgcn_global_load_lds((const unsigned*)((const char*)(gbase) + (voff)[_i]), (PG8_LAS unsigned*)(lds + (bufoff) + ldsw + _i * 8192), 16, 0, 0); } while (0)
; #define PG8_LDA(dst, b, h) do { _Pragma("unroll") for (int m = 0; m < 4; ++m) _Pragma("unroll") for (int k = 0; k < 2; ++k) dst[m][k] = *(const PG8_LAS bf16x8*)(lds + PG8_SA(b, h) + aoff + m * 2048 + k * 1024); } while (0)
; #define PG8_MMA(ai, bj, At, Bt) do { __builtin_amdgcn_s_setprio(1); _Pragma("unroll") for (int m = 0; m < 4; ++m) _Pragma("unroll") for (int n = 0; n < 2; ++n) _Pragma("unroll") for (int k = 0; k < 2; ++k) \
;         acc[ai][bj][m][n] = __builtin_amdgcn_mfma_f32_16x16x32_bf16(Bt[n][k], At[m][k], acc[ai][bj][m][n], 0, 0, 0); __builtin_amdgcn_s_setprio(0); } while (0)
; #define PG8_WAIT_V(n) asm volatile("s_waitcnt vmcnt(" #n ")" ::: "memory")
; #define PG8_WAIT_L(n) asm volatile("s_waitcnt lgkmcnt(" #n ")" ::: "memory")
; #define PG8_BAR __builtin_amdgcn_s_barrier()
; #define PG8_SCHED __builtin_amdgcn_sched_barrier(0)
; template <class Epi, class Sched, bool ALIGN_EPI = false, bool SP2 = false>
; __device__ __forceinline__ void gemm_phase(PG8_LAS unsigned char* lds, const Gemm g, const Sched& S, const Epi& E) {
;     ...
;             PG8_LDA(At, 1, 1); PG8_STAGE(PG8_SB(1, 0), b3, voffB); PG8_STAGE(PG8_SB(1, 1), b3 + hstep, voffB); PG8_STAGE(PG8_SA(1, 0), a3, voffA);
;             PG8_WAIT_V(8); PG8_WAIT_L(0); PG8_BAR; PG8_MMA(1, 0, At, B0); PG8_MMA(1, 1, At, B1); PG8_BAR; PG8_SCHED;
	s_add_i32 s46, s70, s50
	v_lshl_add_u64 v[218:219], v[218:219], 0, s[14:15]
	s_mov_b32 m0, s46
	ds_read_b128 v[186:189], v155 offset:49152
	ds_read_b128 v[190:193], v155 offset:50176
	ds_read_b128 v[194:197], v155 offset:51200
	ds_read_b128 v[198:201], v155 offset:52224
	ds_read_b128 v[202:205], v155 offset:53248
	ds_read_b128 v[206:209], v155 offset:54272
	ds_read_b128 v[210:213], v155 offset:55296
	ds_read_b128 v[214:217], v155 offset:56320
	global_load_lds_dwordx4 v[218:219], off
	s_add_i32 m0, s46, 0x2000
	s_add_u32 s44, s44, 0x80080
	v_lshl_add_u64 v[218:219], v[220:221], 0, s[14:15]
	s_addc_u32 s45, s45, 0
	s_add_i32 s46, s71, s50
	global_load_lds_dwordx4 v[218:219], off
	v_lshl_add_u64 v[218:219], s[44:45], 0, v[130:131]
	s_mov_b32 m0, s46
	s_nop 0
	global_load_lds_dwordx4 v[218:219], off
	v_lshl_add_u64 v[218:219], s[44:45], 0, v[134:135]
	s_add_i32 m0, s46, 0x2000
	s_nop 0
	global_load_lds_dwordx4 v[218:219], off
	v_lshl_add_u64 v[218:219], v[222:223], 0, s[14:15]
	s_mov_b32 m0, s60
	s_nop 0
	global_load_lds_dwordx4 v[218:219], off
	v_lshl_add_u64 v[218:219], v[224:225], 0, s[14:15]
	s_mov_b32 m0, s61
	s_nop 0
	global_load_lds_dwordx4 v[218:219], off
	s_waitcnt vmcnt(8)
	s_waitcnt lgkmcnt(0)
	s_barrier
	s_setprio 1
	s_waitcnt lgkmcnt(0)
	v_mfma_f32_16x16x32_bf16 v[60:63], v[146:149], v[186:189], v[60:63]
	v_mfma_f32_16x16x32_bf16 v[56:59], v[162:165], v[186:189], v[56:59]
	v_mfma_f32_16x16x32_bf16 v[44:47], v[146:149], v[194:197], v[44:47]
	v_mfma_f32_16x16x32_bf16 v[40:43], v[162:165], v[194:197], v[40:43]
	v_mfma_f32_16x16x32_bf16 v[28:31], v[146:149], v[202:205], v[28:31]
	v_mfma_f32_16x16x32_bf16 v[24:27], v[162:165], v[202:205], v[24:27]
	v_mfma_f32_16x16x32_bf16 v[12:15], v[146:149], v[210:213], v[12:15]
	v_mfma_f32_16x16x32_bf16 v[8:11], v[162:165], v[210:213], v[8:11]
	s_setprio 0
	s_setprio 1
	v_mfma_f32_16x16x32_bf16 v[60:63], v[158:161], v[190:193], v[60:63]
	v_mfma_f32_16x16x32_bf16 v[56:59], v[166:169], v[190:193], v[56:59]
	v_mfma_f32_16x16x32_bf16 v[44:47], v[158:161], v[198:201], v[44:47]
	v_mfma_f32_16x16x32_bf16 v[40:43], v[166:169], v[198:201], v[40:43]
	v_mfma_f32_16x16x32_bf16 v[28:31], v[158:161], v[206:209], v[28:31]
	v_mfma_f32_16x16x32_bf16 v[24:27], v[166:169], v[206:209], v[24:27]
	v_mfma_f32_16x16x32_bf16 v[12:15], v[158:161], v[214:217], v[12:15]
	v_mfma_f32_16x16x32_bf16 v[8:11], v[166:169], v[214:217], v[8:11]
	s_setprio 0
	s_setprio 1
	v_mfma_f32_16x16x32_bf16 v[52:55], v[170:173], v[186:189], v[52:55]
	v_mfma_f32_16x16x32_bf16 v[48:51], v[178:181], v[186:189], v[48:51]
	v_mfma_f32_16x16x32_bf16 v[36:39], v[170:173], v[194:197], v[36:39]
	v_mfma_f32_16x16x32_bf16 v[32:35], v[178:181], v[194:197], v[32:35]
	v_mfma_f32_16x16x32_bf16 v[20:23], v[170:173], v[202:205], v[20:23]
	v_mfma_f32_16x16x32_bf16 v[16:19], v[178:181], v[202:205], v[16:19]
	v_mfma_f32_16x16x32_bf16 v[4:7], v[170:173], v[210:213], v[4:7]
	v_mfma_f32_16x16x32_bf16 v[0:3], v[178:181], v[210:213], v[0:3]
	s_setprio 0
	s_setprio 1
	v_mfma_f32_16x16x32_bf16 v[52:55], v[174:177], v[190:193], v[52:55]
	v_mfma_f32_16x16x32_bf16 v[48:51], v[182:185], v[190:193], v[48:51]
	v_mfma_f32_16x16x32_bf16 v[36:39], v[174:177], v[198:201], v[36:39]
	v_mfma_f32_16x16x32_bf16 v[32:35], v[182:185], v[198:201], v[32:35]
	v_mfma_f32_16x16x32_bf16 v[20:23], v[174:177], v[206:209], v[20:23]
	v_mfma_f32_16x16x32_bf16 v[16:19], v[182:185], v[206:209], v[16:19]
	v_mfma_f32_16x16x32_bf16 v[4:7], v[174:177], v[214:217], v[4:7]
	v_mfma_f32_16x16x32_bf16 v[0:3], v[182:185], v[214:217], v[0:3]
	s_setprio 0
	s_barrier
	s_add_i32 s69, s69, 2
	s_add_u32 s42, s42, 0x100
	s_addc_u32 s43, s43, 0
	s_add_u32 s67, s67, 0x100
	s_addc_u32 s68, s68, 0
	s_cmp_gt_u32 s69, 29
	s_cbranch_scc0 .LBB0_1612
	s_and_b64 vcc, exec, s[16:17]
	s_cbranch_vccz .LBB0_1615
	s_barrier

; #define PG8_STAGE(bufoff, gbase, voff) do { _Pragma("unroll") for (int _i = 0; _i < 2; ++_i) \
;         __builtin_amdgcn_global_load_lds((const unsigned*)((const char*)(gbase) + (voff)[_i]), (PG8_LAS unsigned*)(lds + (bufoff) + ldsw + _i * 8192), 16, 0, 0); } while (0)
; #define PG8_LDA(dst, b, h) do { _Pragma("unroll") for (int m = 0; m < 4; ++m) _Pragma("unroll") for (int k = 0; k < 2; ++k) dst[m][k] = *(const PG8_LAS bf16x8*)(lds + PG8_SA(b, h) + aoff + m * 2048 + k * 1024); } while (0)
; #define PG8_LDB(dst, b, h) do { _Pragma("unroll") for (int n = 0; n < 2; ++n) _Pragma("unroll") for (int k = 0; k < 2; ++k) dst[n][k] = *(const PG8_LAS bf16x8*)(lds + PG8_SB(b, h) + boff + n * 2048 + k * 1024); } while (0)
; #define PG8_MMA(ai, bj, At, Bt) do { __builtin_amdgcn_s_setprio(1); _Pragma("unroll") for (int m = 0; m < 4; ++m) _Pragma("unroll") for (int n = 0; n < 2; ++n) _Pragma("unroll") for (int k = 0; k < 2; ++k) \
;         acc[ai][bj][m][n] = __builtin_amdgcn_mfma_f32_16x16x32_bf16(Bt[n][k], At[m][k], acc[ai][bj][m][n], 0, 0, 0); __builtin_amdgcn_s_setprio(0); } while (0)
; #define PG8_WAIT_V(n) asm volatile("s_waitcnt vmcnt(" #n ")" ::: "memory")
; #define PG8_WAIT_L(n) asm volatile("s_waitcnt lgkmcnt(" #n ")" ::: "memory")
; template <class Epi, class Sched, bool ALIGN_EPI = false, bool SP2 = false>
; __device__ __forceinline__ void gemm_phase(PG8_LAS unsigned char* lds, const Gemm g, const Sched& S, const Epi& E) {
;     ...
;             const bool last = (t == nt - 2);
;             const char* a1 = cA + (size_t)(t + 1) * kstep;
;             const char* a2 = last ? nA : cA + (size_t)(t + 2) * kstep; const char* b2 = last ? nB : cB + (size_t)(t + 2) * kstep;
;             const char* a3 = a2 + kstep; const char* b3 = b2 + kstep;
;             if (last && has_next) S.a_ready(nxt);
;             if constexpr (SP2) {
;             PG8_LDB(B0, 0, 0); PG8_LDB(B1, 0, 1); PG8_SCHED; PG8_LDA(At, 0, 0); PG8_STAGE(PG8_SA(1, 1), a1 + hstep, voffA);
;             PG8_WAIT_V(8); PG8_WAIT_L(0); PG8_BAR; PG8_MMA(0, 0, At, B0); PG8_MMA(0, 1, At, B1); PG8_BAR; PG8_SCHED;
;             PG8_LDA(At, 0, 1); PG8_STAGE(PG8_SB(0, 0), b2, voffB); PG8_STAGE(PG8_SB(0, 1), b2 + hstep, voffB); PG8_STAGE(PG8_SA(0, 0), a2, voffA);
;             PG8_WAIT_V(8); PG8_WAIT_L(0); PG8_BAR; PG8_MMA(1, 0, At, B0); PG8_MMA(1, 1, At, B1); PG8_BAR; PG8_SCHED;
.LBB0_1701:
	ds_read_b128 v[128:131], v220
	ds_read_b128 v[132:135], v220 offset:1024
	ds_read_b128 v[136:139], v220 offset:2048
	ds_read_b128 v[140:143], v220 offset:3072
	ds_read_b128 v[164:167], v221
	ds_read_b128 v[168:171], v221 offset:1024
	ds_read_b128 v[172:175], v221 offset:2048
	ds_read_b128 v[176:179], v221 offset:3072
	s_add_u32 s8, s0, 0xfff80080
	s_addc_u32 s9, s1, -1
	s_cmp_eq_u32 s73, 28
	s_cselect_b32 s11, s7, s9
	s_cselect_b32 s10, s12, s8
	s_cselect_b32 s9, s13, s71
	s_cselect_b32 s8, s16, s37
	v_lshl_add_u64 v[212:213], s[0:1], 0, v[156:157]
	s_add_i32 m0, s61, 0xc000
	ds_read_b128 v[180:183], v222
	ds_read_b128 v[184:187], v222 offset:1024
	ds_read_b128 v[188:191], v222 offset:2048
	ds_read_b128 v[192:195], v222 offset:3072
	ds_read_b128 v[196:199], v222 offset:4096
	ds_read_b128 v[200:203], v222 offset:5120
	ds_read_b128 v[204:207], v222 offset:6144
	ds_read_b128 v[208:211], v222 offset:7168
	global_load_lds_dwordx4 v[212:213], off
	v_lshl_add_u64 v[212:213], s[0:1], 0, v[158:159]
	s_add_i32 m0, s61, 0xe000
	s_nop 0
	global_load_lds_dwordx4 v[212:213], off
	s_waitcnt vmcnt(8)
	s_waitcnt lgkmcnt(0)
	s_barrier
	s_setprio 1
	s_waitcnt lgkmcnt(0)
	v_mfma_f32_16x16x32_bf16 v[124:127], v[128:131], v[180:183], v[124:127]
	v_mfma_f32_16x16x32_bf16 v[116:119], v[136:139], v[180:183], v[116:119]
	v_mfma_f32_16x16x32_bf16 v[120:123], v[128:131], v[188:191], v[120:123]
	v_mfma_f32_16x16x32_bf16 v[112:115], v[136:139], v[188:191], v[112:115]
	v_mfma_f32_16x16x32_bf16 v[104:107], v[128:131], v[196:199], v[104:107]
	v_mfma_f32_16x16x32_bf16 v[108:111], v[136:139], v[196:199], v[108:111]
	v_mfma_f32_16x16x32_bf16 v[80:83], v[128:131], v[204:207], v[80:83]
	v_mfma_f32_16x16x32_bf16 v[92:95], v[136:139], v[204:207], v[92:95]
	s_setprio 0
	s_setprio 1
	v_mfma_f32_16x16x32_bf16 v[124:127], v[132:135], v[184:187], v[124:127]
	v_mfma_f32_16x16x32_bf16 v[116:119], v[140:143], v[184:187], v[116:119]
	v_mfma_f32_16x16x32_bf16 v[120:123], v[132:135], v[192:195], v[120:123]
	v_mfma_f32_16x16x32_bf16 v[112:115], v[140:143], v[192:195], v[112:115]
	v_mfma_f32_16x16x32_bf16 v[104:107], v[132:135], v[200:203], v[104:107]
	v_mfma_f32_16x16x32_bf16 v[108:111], v[140:143], v[200:203], v[108:111]
	v_mfma_f32_16x16x32_bf16 v[80:83], v[132:135], v[208:211], v[80:83]
	v_mfma_f32_16x16x32_bf16 v[92:95], v[140:143], v[208:211], v[92:95]
	s_setprio 0
	s_setprio 1
	v_mfma_f32_16x16x32_bf16 v[100:103], v[164:167], v[180:183], v[100:103]
	v_mfma_f32_16x16x32_bf16 v[76:79], v[172:175], v[180:183], v[76:79]
	v_mfma_f32_16x16x32_bf16 v[96:99], v[164:167], v[188:191], v[96:99]
	v_mfma_f32_16x16x32_bf16 v[72:75], v[172:175], v[188:191], v[72:75]
	v_mfma_f32_16x16x32_bf16 v[88:91], v[164:167], v[196:199], v[88:91]
	v_mfma_f32_16x16x32_bf16 v[68:71], v[172:175], v[196:199], v[68:71]
	v_mfma_f32_16x16x32_bf16 v[84:87], v[164:167], v[204:207], v[84:87]
	v_mfma_f32_16x16x32_bf16 v[64:67], v[172:175], v[204:207], v[64:67]
	s_setprio 0
	s_setprio 1
	v_mfma_f32_16x16x32_bf16 v[100:103], v[168:171], v[184:187], v[100:103]
	v_mfma_f32_16x16x32_bf16 v[76:79], v[176:179], v[184:187], v[76:79]
	v_mfma_f32_16x16x32_bf16 v[96:99], v[168:171], v[192:195], v[96:99]
	v_mfma_f32_16x16x32_bf16 v[72:75], v[176:179], v[192:195], v[72:75]
	v_mfma_f32_16x16x32_bf16 v[88:91], v[168:171], v[200:203], v[88:91]
	v_mfma_f32_16x16x32_bf16 v[68:71], v[176:179], v[200:203], v[68:71]
	v_mfma_f32_16x16x32_bf16 v[84:87], v[168:171], v[208:211], v[84:87]
	v_mfma_f32_16x16x32_bf16 v[64:67], v[176:179], v[208:211], v[64:67]
	s_setprio 0
	s_barrier
	s_add_i32 s79, s15, s59
	v_lshl_add_u64 v[212:213], s[8:9], 0, v[148:149]
	s_mov_b32 m0, s79
	ds_read_b128 v[180:183], v222 offset:16384
	ds_read_b128 v[184:187], v222 offset:17408
	ds_read_b128 v[188:191], v222 offset:18432
	ds_read_b128 v[192:195], v222 offset:19456
	ds_read_b128 v[196:199], v222 offset:20480
	ds_read_b128 v[200:203], v222 offset:21504
	ds_read_b128 v[204:207], v222 offset:22528
	ds_read_b128 v[208:211], v222 offset:23552
	global_load_lds_dwordx4 v[212:213], off
	s_add_i32 m0, s79, 0x2000
	s_add_u32 vcc_lo, s8, 0x80000
	v_lshl_add_u64 v[214:215], s[8:9], 0, v[152:153]
	s_addc_u32 vcc_hi, s9, 0
	s_add_i32 s79, s87, s59
	global_load_lds_dwordx4 v[214:215], off
	v_lshl_add_u64 v[226:227], vcc, 0, v[148:149]
	s_mov_b32 m0, s79
	v_lshl_add_u64 v[228:229], s[10:11], 0, v[150:151]
	global_load_lds_dwordx4 v[226:227], off
	v_lshl_add_u64 v[226:227], vcc, 0, v[152:153]
	s_add_i32 m0, s79, 0x2000
	s_nop 0
	global_load_lds_dwordx4 v[226:227], off
	v_lshl_add_u64 v[226:227], s[10:11], 0, v[146:147]
	s_mov_b32 m0, s61
	s_nop 0
	global_load_lds_dwordx4 v[226:227], off
	s_mov_b32 m0, s63
	s_nop 0
	global_load_lds_dwordx4 v[228:229], off
	s_waitcnt vmcnt(8)
	s_waitcnt lgkmcnt(0)
	s_barrier
; #define PG8_STAGE(bufoff, gbase, voff) do { _Pragma("unroll") for (int _i = 0; _i < 2; ++_i) \
;         __builtin_amdgcn_global_load_lds((const unsigned*)((const char*)(gbase) + (voff)[_i]), (PG8_LAS unsigned*)(lds + (bufoff) + ldsw + _i * 8192), 16, 0, 0); } while (0)
; #define PG8_LDA(dst, b, h) do { _Pragma("unroll") for (int m = 0; m < 4; ++m) _Pragma("unroll") for (int k = 0; k < 2; ++k) dst[m][k] = *(const PG8_LAS bf16x8*)(lds + PG8_SA(b, h) + aoff + m * 2048 + k * 1024); } while (0)
; #define PG8_LDB(dst, b, h) do { _Pragma("unroll") for (int n = 0; n < 2; ++n) _Pragma("unroll") for (int k = 0; k < 2; ++k) dst[n][k] = *(const PG8_LAS bf16x8*)(lds + PG8_SB(b, h) + boff + n * 2048 + k * 1024); } while (0)
; #define PG8_MMA(ai, bj, At, Bt) do { __builtin_amdgcn_s_setprio(1); _Pragma("unroll") for (int m = 0; m < 4; ++m) _Pragma("unroll") for (int n = 0; n < 2; ++n) _Pragma("unroll") for (int k = 0; k < 2; ++k) \
;         acc[ai][bj][m][n] = __builtin_amdgcn_mfma_f32_16x16x32_bf16(Bt[n][k], At[m][k], acc[ai][bj][m][n], 0, 0, 0); __builtin_amdgcn_s_setprio(0); } while (0)
; #define PG8_WAIT_V(n) asm volatile("s_waitcnt vmcnt(" #n ")" ::: "memory")
; #define PG8_WAIT_L(n) asm volatile("s_waitcnt lgkmcnt(" #n ")" ::: "memory")
; #define PG8_BAR __builtin_amdgcn_s_barrier()
; #define PG8_SCHED __builtin_amdgcn_sched_barrier(0)
; template <class Epi, class Sched, bool ALIGN_EPI = false, bool SP2 = false>
; __device__ __forceinline__ void gemm_phase(PG8_LAS unsigned char* lds, const Gemm g, const Sched& S, const Epi& E) {
;     ...
;             PG8_WAIT_V(8); PG8_WAIT_L(0); PG8_BAR; PG8_MMA(1, 0, At, B0); PG8_MMA(1, 1, At, B1); PG8_BAR; PG8_SCHED;
;             PG8_LDB(B0, 1, 0); PG8_LDB(B1, 1, 1); PG8_SCHED; PG8_LDA(At, 1, 0); PG8_STAGE(PG8_SA(0, 1), a2 + hstep, voffA);
;             PG8_WAIT_V(8); PG8_WAIT_L(0); PG8_BAR; PG8_MMA(0, 0, At, B0); PG8_MMA(0, 1, At, B1); PG8_BAR; PG8_SCHED;
	s_setprio 1
	s_waitcnt lgkmcnt(0)
	v_mfma_f32_16x16x32_bf16 v[60:63], v[128:131], v[180:183], v[60:63]
	v_mfma_f32_16x16x32_bf16 v[44:47], v[136:139], v[180:183], v[44:47]
	v_mfma_f32_16x16x32_bf16 v[56:59], v[128:131], v[188:191], v[56:59]
	v_mfma_f32_16x16x32_bf16 v[40:43], v[136:139], v[188:191], v[40:43]
	v_mfma_f32_16x16x32_bf16 v[52:55], v[128:131], v[196:199], v[52:55]
	v_mfma_f32_16x16x32_bf16 v[36:39], v[136:139], v[196:199], v[36:39]
	v_mfma_f32_16x16x32_bf16 v[48:51], v[128:131], v[204:207], v[48:51]
	v_mfma_f32_16x16x32_bf16 v[32:35], v[136:139], v[204:207], v[32:35]
	s_setprio 0
	s_setprio 1
	v_mfma_f32_16x16x32_bf16 v[60:63], v[132:135], v[184:187], v[60:63]
	v_mfma_f32_16x16x32_bf16 v[44:47], v[140:143], v[184:187], v[44:47]
	v_mfma_f32_16x16x32_bf16 v[56:59], v[132:135], v[192:195], v[56:59]
	v_mfma_f32_16x16x32_bf16 v[40:43], v[140:143], v[192:195], v[40:43]
	v_mfma_f32_16x16x32_bf16 v[52:55], v[132:135], v[200:203], v[52:55]
	v_mfma_f32_16x16x32_bf16 v[36:39], v[140:143], v[200:203], v[36:39]
	v_mfma_f32_16x16x32_bf16 v[48:51], v[132:135], v[208:211], v[48:51]
	v_mfma_f32_16x16x32_bf16 v[32:35], v[140:143], v[208:211], v[32:35]
	s_setprio 0
	s_setprio 1
	v_mfma_f32_16x16x32_bf16 v[28:31], v[164:167], v[180:183], v[28:31]
	v_mfma_f32_16x16x32_bf16 v[12:15], v[172:175], v[180:183], v[12:15]
	v_mfma_f32_16x16x32_bf16 v[24:27], v[164:167], v[188:191], v[24:27]
	v_mfma_f32_16x16x32_bf16 v[8:11], v[172:175], v[188:191], v[8:11]
	v_mfma_f32_16x16x32_bf16 v[20:23], v[164:167], v[196:199], v[20:23]
	v_mfma_f32_16x16x32_bf16 v[4:7], v[172:175], v[196:199], v[4:7]
	v_mfma_f32_16x16x32_bf16 v[16:19], v[164:167], v[204:207], v[16:19]
	v_mfma_f32_16x16x32_bf16 v[0:3], v[172:175], v[204:207], v[0:3]
	s_setprio 0
	s_setprio 1
	v_mfma_f32_16x16x32_bf16 v[28:31], v[168:171], v[184:187], v[28:31]
	v_mfma_f32_16x16x32_bf16 v[12:15], v[176:179], v[184:187], v[12:15]
	v_mfma_f32_16x16x32_bf16 v[24:27], v[168:171], v[192:195], v[24:27]
	v_mfma_f32_16x16x32_bf16 v[8:11], v[176:179], v[192:195], v[8:11]
	v_mfma_f32_16x16x32_bf16 v[20:23], v[168:171], v[200:203], v[20:23]
	v_mfma_f32_16x16x32_bf16 v[4:7], v[176:179], v[200:203], v[4:7]
	v_mfma_f32_16x16x32_bf16 v[16:19], v[168:171], v[208:211], v[16:19]
	v_mfma_f32_16x16x32_bf16 v[0:3], v[176:179], v[208:211], v[0:3]
	s_setprio 0
	s_barrier
	s_add_i32 s79, 0, 0x18000
	s_add_i32 vcc_lo, 0, 0x1c000
	v_add_u32_e32 v140, s79, v219
	v_add_u32_e32 v154, vcc_lo, v219
	ds_read_b128 v[128:131], v140
	ds_read_b128 v[132:135], v140 offset:1024
	ds_read_b128 v[136:139], v140 offset:2048
	ds_read_b128 v[140:143], v140 offset:3072
	ds_read_b128 v[164:167], v154
	ds_read_b128 v[168:171], v154 offset:1024
	ds_read_b128 v[172:175], v154 offset:2048
	ds_read_b128 v[176:179], v154 offset:3072
	s_add_u32 s10, s10, 0x80000
	s_addc_u32 s11, s11, 0
	s_mov_b32 m0, s65
	v_lshl_add_u64 v[230:231], s[10:11], 0, v[146:147]
	ds_read_b128 v[180:183], v222 offset:32768
	ds_read_b128 v[184:187], v222 offset:33792
	ds_read_b128 v[188:191], v222 offset:34816
	ds_read_b128 v[192:195], v222 offset:35840
	ds_read_b128 v[196:199], v222 offset:36864
	ds_read_b128 v[200:203], v222 offset:37888
	ds_read_b128 v[204:207], v222 offset:38912
	ds_read_b128 v[208:211], v222 offset:39936
	global_load_lds_dwordx4 v[230:231], off
	v_lshl_add_u64 v[230:231], s[10:11], 0, v[150:151]
	s_mov_b32 m0, s67
	s_nop 0
	global_load_lds_dwordx4 v[230:231], off
	s_waitcnt vmcnt(8)
	s_waitcnt lgkmcnt(0)
	s_barrier
	s_setprio 1
	s_waitcnt lgkmcnt(0)
	v_mfma_f32_16x16x32_bf16 v[124:127], v[128:131], v[180:183], v[124:127]
	v_mfma_f32_16x16x32_bf16 v[116:119], v[136:139], v[180:183], v[116:119]
	v_mfma_f32_16x16x32_bf16 v[120:123], v[128:131], v[188:191], v[120:123]
	v_mfma_f32_16x16x32_bf16 v[112:115], v[136:139], v[188:191], v[112:115]
	v_mfma_f32_16x16x32_bf16 v[104:107], v[128:131], v[196:199], v[104:107]
	v_mfma_f32_16x16x32_bf16 v[108:111], v[136:139], v[196:199], v[108:111]
	v_mfma_f32_16x16x32_bf16 v[80:83], v[128:131], v[204:207], v[80:83]
	v_mfma_f32_16x16x32_bf16 v[92:95], v[136:139], v[204:207], v[92:95]
	s_setprio 0
	s_setprio 1
	v_mfma_f32_16x16x32_bf16 v[124:127], v[132:135], v[184:187], v[124:127]
	v_mfma_f32_16x16x32_bf16 v[116:119], v[140:143], v[184:187], v[116:119]
	v_mfma_f32_16x16x32_bf16 v[120:123], v[132:135], v[192:195], v[120:123]
	v_mfma_f32_16x16x32_bf16 v[112:115], v[140:143], v[192:195], v[112:115]
	v_mfma_f32_16x16x32_bf16 v[104:107], v[132:135], v[200:203], v[104:107]
	v_mfma_f32_16x16x32_bf16 v[108:111], v[140:143], v[200:203], v[108:111]
	v_mfma_f32_16x16x32_bf16 v[80:83], v[132:135], v[208:211], v[80:83]
	v_mfma_f32_16x16x32_bf16 v[92:95], v[140:143], v[208:211], v[92:95]
	s_setprio 0
	s_setprio 1
	v_mfma_f32_16x16x32_bf16 v[100:103], v[164:167], v[180:183], v[100:103]
	v_mfma_f32_16x16x32_bf16 v[76:79], v[172:175], v[180:183], v[76:79]
	v_mfma_f32_16x16x32_bf16 v[96:99], v[164:167], v[188:191], v[96:99]
	v_mfma_f32_16x16x32_bf16 v[72:75], v[172:175], v[188:191], v[72:75]
	v_mfma_f32_16x16x32_bf16 v[88:91], v[164:167], v[196:199], v[88:91]
	v_mfma_f32_16x16x32_bf16 v[68:71], v[172:175], v[196:199], v[68:71]
	v_mfma_f32_16x16x32_bf16 v[84:87], v[164:167], v[204:207], v[84:87]
	v_mfma_f32_16x16x32_bf16 v[64:67], v[172:175], v[204:207], v[64:67]
	s_setprio 0
	s_setprio 1
	v_mfma_f32_16x16x32_bf16 v[100:103], v[168:171], v[184:187], v[100:103]
	v_mfma_f32_16x16x32_bf16 v[76:79], v[176:179], v[184:187], v[76:79]
	v_mfma_f32_16x16x32_bf16 v[96:99], v[168:171], v[192:195], v[96:99]
	v_mfma_f32_16x16x32_bf16 v[72:75], v[176:179], v[192:195], v[72:75]
	v_mfma_f32_16x16x32_bf16 v[88:91], v[168:171], v[200:203], v[88:91]
	v_mfma_f32_16x16x32_bf16 v[68:71], v[176:179], v[200:203], v[68:71]
	v_mfma_f32_16x16x32_bf16 v[84:87], v[168:171], v[208:211], v[84:87]
	v_mfma_f32_16x16x32_bf16 v[64:67], v[176:179], v[208:211], v[64:67]
	s_setprio 0
	s_barrier
; #define PG8_STAGE(bufoff, gbase, voff) do { _Pragma("unroll") for (int _i = 0; _i < 2; ++_i) \
;         __builtin_amdgcn_global_load_lds((const unsigned*)((const char*)(gbase) + (voff)[_i]), (PG8_LAS unsigned*)(lds + (bufoff) + ldsw + _i * 8192), 16, 0, 0); } while (0)
; #define PG8_LDA(dst, b, h) do { _Pragma("unroll") for (int m = 0; m < 4; ++m) _Pragma("unroll") for (int k = 0; k < 2; ++k) dst[m][k] = *(const PG8_LAS bf16x8*)(lds + PG8_SA(b, h) + aoff + m * 2048 + k * 1024); } while (0)
; #define PG8_MMA(ai, bj, At, Bt) do { __builtin_amdgcn_s_setprio(1); _Pragma("unroll") for (int m = 0; m < 4; ++m) _Pragma("unroll") for (int n = 0; n < 2; ++n) _Pragma("unroll") for (int k = 0; k < 2; ++k) \
;         acc[ai][bj][m][n] = __builtin_amdgcn_mfma_f32_16x16x32_bf16(Bt[n][k], At[m][k], acc[ai][bj][m][n], 0, 0, 0); __builtin_amdgcn_s_setprio(0); } while (0)
; #define PG8_WAIT_V(n) asm volatile("s_waitcnt vmcnt(" #n ")" ::: "memory")
; #define PG8_WAIT_L(n) asm volatile("s_waitcnt lgkmcnt(" #n ")" ::: "memory")
; #define PG8_BAR __builtin_amdgcn_s_barrier()
; #define PG8_SCHED __builtin_amdgcn_sched_barrier(0)
; template <class Epi, class Sched, bool ALIGN_EPI = false, bool SP2 = false>
; __device__ __forceinline__ void gemm_phase(PG8_LAS unsigned char* lds, const Gemm g, const Sched& S, const Epi& E) {
;     ...
;             PG8_LDA(At, 1, 1); PG8_STAGE(PG8_SB(1, 0), b3, voffB); PG8_STAGE(PG8_SB(1, 1), b3 + hstep, voffB); PG8_STAGE(PG8_SA(1, 0), a3, voffA);
;             PG8_WAIT_V(8); PG8_WAIT_L(0); PG8_BAR; PG8_MMA(1, 0, At, B0); PG8_MMA(1, 1, At, B1); PG8_BAR; PG8_SCHED;
	s_add_i32 s10, s79, s59
	v_lshl_add_u64 v[212:213], v[212:213], 0, s[46:47]
	s_mov_b32 m0, s10
	ds_read_b128 v[180:183], v222 offset:49152
	ds_read_b128 v[184:187], v222 offset:50176
	ds_read_b128 v[188:191], v222 offset:51200
	ds_read_b128 v[192:195], v222 offset:52224
	ds_read_b128 v[196:199], v222 offset:53248
	ds_read_b128 v[200:203], v222 offset:54272
	ds_read_b128 v[204:207], v222 offset:55296
	ds_read_b128 v[208:211], v222 offset:56320
	global_load_lds_dwordx4 v[212:213], off
	s_add_i32 m0, s10, 0x2000
	s_add_u32 s8, s8, 0x80080
	v_lshl_add_u64 v[212:213], v[214:215], 0, s[46:47]
	s_addc_u32 s9, s9, 0
	s_add_i32 s10, vcc_lo, s59
	global_load_lds_dwordx4 v[212:213], off
	v_lshl_add_u64 v[212:213], s[8:9], 0, v[148:149]
	s_mov_b32 m0, s10
	s_nop 0
	global_load_lds_dwordx4 v[212:213], off
	v_lshl_add_u64 v[212:213], s[8:9], 0, v[152:153]
	s_add_i32 m0, s10, 0x2000
	s_nop 0
	global_load_lds_dwordx4 v[212:213], off
	v_lshl_add_u64 v[212:213], v[226:227], 0, s[46:47]
	s_mov_b32 m0, s84
	s_nop 0
	global_load_lds_dwordx4 v[212:213], off
	v_lshl_add_u64 v[212:213], v[228:229], 0, s[46:47]
	s_mov_b32 m0, s85
	s_nop 0
	global_load_lds_dwordx4 v[212:213], off
	s_waitcnt vmcnt(8)
	s_waitcnt lgkmcnt(0)
	s_barrier
	s_setprio 1
	s_waitcnt lgkmcnt(0)
	v_mfma_f32_16x16x32_bf16 v[60:63], v[128:131], v[180:183], v[60:63]
	v_mfma_f32_16x16x32_bf16 v[44:47], v[136:139], v[180:183], v[44:47]
	v_mfma_f32_16x16x32_bf16 v[56:59], v[128:131], v[188:191], v[56:59]
	v_mfma_f32_16x16x32_bf16 v[40:43], v[136:139], v[188:191], v[40:43]
	v_mfma_f32_16x16x32_bf16 v[52:55], v[128:131], v[196:199], v[52:55]
	v_mfma_f32_16x16x32_bf16 v[36:39], v[136:139], v[196:199], v[36:39]
	v_mfma_f32_16x16x32_bf16 v[48:51], v[128:131], v[204:207], v[48:51]
	v_mfma_f32_16x16x32_bf16 v[32:35], v[136:139], v[204:207], v[32:35]
	s_setprio 0
	s_setprio 1
	v_mfma_f32_16x16x32_bf16 v[60:63], v[132:135], v[184:187], v[60:63]
	v_mfma_f32_16x16x32_bf16 v[44:47], v[140:143], v[184:187], v[44:47]
	v_mfma_f32_16x16x32_bf16 v[56:59], v[132:135], v[192:195], v[56:59]
	v_mfma_f32_16x16x32_bf16 v[40:43], v[140:143], v[192:195], v[40:43]
	v_mfma_f32_16x16x32_bf16 v[52:55], v[132:135], v[200:203], v[52:55]
	v_mfma_f32_16x16x32_bf16 v[36:39], v[140:143], v[200:203], v[36:39]
	v_mfma_f32_16x16x32_bf16 v[48:51], v[132:135], v[208:211], v[48:51]
	v_mfma_f32_16x16x32_bf16 v[32:35], v[140:143], v[208:211], v[32:35]
	s_setprio 0
	s_setprio 1
	v_mfma_f32_16x16x32_bf16 v[28:31], v[164:167], v[180:183], v[28:31]
	v_mfma_f32_16x16x32_bf16 v[12:15], v[172:175], v[180:183], v[12:15]
	v_mfma_f32_16x16x32_bf16 v[24:27], v[164:167], v[188:191], v[24:27]
	v_mfma_f32_16x16x32_bf16 v[8:11], v[172:175], v[188:191], v[8:11]
	v_mfma_f32_16x16x32_bf16 v[20:23], v[164:167], v[196:199], v[20:23]
	v_mfma_f32_16x16x32_bf16 v[4:7], v[172:175], v[196:199], v[4:7]
	v_mfma_f32_16x16x32_bf16 v[16:19], v[164:167], v[204:207], v[16:19]
	v_mfma_f32_16x16x32_bf16 v[0:3], v[172:175], v[204:207], v[0:3]
	s_setprio 0
	s_setprio 1
	v_mfma_f32_16x16x32_bf16 v[28:31], v[168:171], v[184:187], v[28:31]
	v_mfma_f32_16x16x32_bf16 v[12:15], v[176:179], v[184:187], v[12:15]
	v_mfma_f32_16x16x32_bf16 v[24:27], v[168:171], v[192:195], v[24:27]
	v_mfma_f32_16x16x32_bf16 v[8:11], v[176:179], v[192:195], v[8:11]
	v_mfma_f32_16x16x32_bf16 v[20:23], v[168:171], v[200:203], v[20:23]
	v_mfma_f32_16x16x32_bf16 v[4:7], v[176:179], v[200:203], v[4:7]
	v_mfma_f32_16x16x32_bf16 v[16:19], v[168:171], v[208:211], v[16:19]
	v_mfma_f32_16x16x32_bf16 v[0:3], v[176:179], v[208:211], v[0:3]
	s_setprio 0
	s_barrier
	s_add_i32 s73, s73, 2
	s_add_u32 s0, s0, 0x100
	s_addc_u32 s1, s1, 0
	s_add_u32 s37, s37, 0x100
	s_addc_u32 s71, s71, 0
	s_cmp_gt_u32 s73, 29
	s_cbranch_scc0 .LBB0_1701
	v_readlane_b32 s0, v244, 56
	v_readlane_b32 s1, v244, 57
	s_and_b64 vcc, exec, s[0:1]
	s_cbranch_vccz .LBB0_1704
	s_barrier

; #define PG8_STAGE(bufoff, gbase, voff) do { _Pragma("unroll") for (int _i = 0; _i < 2; ++_i) \
;         __builtin_amdgcn_global_load_lds((const unsigned*)((const char*)(gbase) + (voff)[_i]), (PG8_LAS unsigned*)(lds + (bufoff) + ldsw + _i * 8192), 16, 0, 0); } while (0)
; #define PG8_LDA(dst, b, h) do { _Pragma("unroll") for (int m = 0; m < 4; ++m) _Pragma("unroll") for (int k = 0; k < 2; ++k) dst[m][k] = *(const PG8_LAS bf16x8*)(lds + PG8_SA(b, h) + aoff + m * 2048 + k * 1024); } while (0)
; #define PG8_LDB(dst, b, h) do { _Pragma("unroll") for (int n = 0; n < 2; ++n) _Pragma("unroll") for (int k = 0; k < 2; ++k) dst[n][k] = *(const PG8_LAS bf16x8*)(lds + PG8_SB(b, h) + boff + n * 2048 + k * 1024); } while (0)
; #define PG8_MMA(ai, bj, At, Bt) do { __builtin_amdgcn_s_setprio(1); _Pragma("unroll") for (int m = 0; m < 4; ++m) _Pragma("unroll") for (int n = 0; n < 2; ++n) _Pragma("unroll") for (int k = 0; k < 2; ++k) \
;         acc[ai][bj][m][n] = __builtin_amdgcn_mfma_f32_16x16x32_bf16(Bt[n][k], At[m][k], acc[ai][bj][m][n], 0, 0, 0); __builtin_amdgcn_s_setprio(0); } while (0)
; #define PG8_WAIT_V(n) asm volatile("s_waitcnt vmcnt(" #n ")" ::: "memory")
; #define PG8_WAIT_L(n) asm volatile("s_waitcnt lgkmcnt(" #n ")" ::: "memory")
; template <class Epi, class Sched, bool ALIGN_EPI = false, bool SP2 = false>
; __device__ __forceinline__ void gemm_phase(PG8_LAS unsigned char* lds, const Gemm g, const Sched& S, const Epi& E) {
;     ...
;             const bool last = (t == nt - 2);
;             const char* a1 = cA + (size_t)(t + 1) * kstep;
;             const char* a2 = last ? nA : cA + (size_t)(t + 2) * kstep; const char* b2 = last ? nB : cB + (size_t)(t + 2) * kstep;
;             const char* a3 = a2 + kstep; const char* b3 = b2 + kstep;
;             if (last && has_next) S.a_ready(nxt);
;             if constexpr (SP2) {
;             PG8_LDB(B0, 0, 0); PG8_LDB(B1, 0, 1); PG8_SCHED; PG8_LDA(At, 0, 0); PG8_STAGE(PG8_SA(1, 1), a1 + hstep, voffA);
;             PG8_WAIT_V(8); PG8_WAIT_L(0); PG8_BAR; PG8_MMA(0, 0, At, B0); PG8_MMA(0, 1, At, B1); PG8_BAR; PG8_SCHED;
;             PG8_LDA(At, 0, 1); PG8_STAGE(PG8_SB(0, 0), b2, voffB); PG8_STAGE(PG8_SB(0, 1), b2 + hstep, voffB); PG8_STAGE(PG8_SA(0, 0), a2, voffA);
;             PG8_WAIT_V(8); PG8_WAIT_L(0); PG8_BAR; PG8_MMA(1, 0, At, B0); PG8_MMA(1, 1, At, B1); PG8_BAR; PG8_SCHED;
.LBB0_1924:
	ds_read_b128 v[146:149], v153
	ds_read_b128 v[158:161], v153 offset:1024
	ds_read_b128 v[162:165], v153 offset:2048
	ds_read_b128 v[166:169], v153 offset:3072
	ds_read_b128 v[170:173], v154
	ds_read_b128 v[174:177], v154 offset:1024
	ds_read_b128 v[178:181], v154 offset:2048
	ds_read_b128 v[182:185], v154 offset:3072
	s_add_u32 s36, s22, 0xffea0080
	s_addc_u32 s37, s23, -1
	s_cmpk_eq_i32 s63, 0x54
	s_cselect_b32 s39, s5, s37
	s_cselect_b32 s38, s4, s36
	s_cselect_b32 s37, s21, s62
	s_cselect_b32 s36, s20, s61
	v_lshl_add_u64 v[218:219], s[22:23], 0, v[136:137]
	s_add_i32 m0, s43, 0xc000
	ds_read_b128 v[186:189], v155
	ds_read_b128 v[190:193], v155 offset:1024
	ds_read_b128 v[194:197], v155 offset:2048
	ds_read_b128 v[198:201], v155 offset:3072
	ds_read_b128 v[202:205], v155 offset:4096
	ds_read_b128 v[206:209], v155 offset:5120
	ds_read_b128 v[210:213], v155 offset:6144
	ds_read_b128 v[214:217], v155 offset:7168
	global_load_lds_dwordx4 v[218:219], off
	v_lshl_add_u64 v[218:219], s[22:23], 0, v[138:139]
	s_add_i32 m0, s43, 0xe000
	s_nop 0
	global_load_lds_dwordx4 v[218:219], off
	s_waitcnt vmcnt(8)
	s_waitcnt lgkmcnt(0)
	s_barrier
	s_setprio 1
	s_waitcnt lgkmcnt(0)
	v_mfma_f32_16x16x32_bf16 v[124:127], v[146:149], v[186:189], v[124:127]
	v_mfma_f32_16x16x32_bf16 v[120:123], v[162:165], v[186:189], v[120:123]
	v_mfma_f32_16x16x32_bf16 v[108:111], v[146:149], v[194:197], v[108:111]
	v_mfma_f32_16x16x32_bf16 v[104:107], v[162:165], v[194:197], v[104:107]
	v_mfma_f32_16x16x32_bf16 v[92:95], v[146:149], v[202:205], v[92:95]
	v_mfma_f32_16x16x32_bf16 v[88:91], v[162:165], v[202:205], v[88:91]
	v_mfma_f32_16x16x32_bf16 v[76:79], v[146:149], v[210:213], v[76:79]
	v_mfma_f32_16x16x32_bf16 v[72:75], v[162:165], v[210:213], v[72:75]
	s_setprio 0
	s_setprio 1
	v_mfma_f32_16x16x32_bf16 v[124:127], v[158:161], v[190:193], v[124:127]
	v_mfma_f32_16x16x32_bf16 v[120:123], v[166:169], v[190:193], v[120:123]
	v_mfma_f32_16x16x32_bf16 v[108:111], v[158:161], v[198:201], v[108:111]
	v_mfma_f32_16x16x32_bf16 v[104:107], v[166:169], v[198:201], v[104:107]
	v_mfma_f32_16x16x32_bf16 v[92:95], v[158:161], v[206:209], v[92:95]
	v_mfma_f32_16x16x32_bf16 v[88:91], v[166:169], v[206:209], v[88:91]
	v_mfma_f32_16x16x32_bf16 v[76:79], v[158:161], v[214:217], v[76:79]
	v_mfma_f32_16x16x32_bf16 v[72:75], v[166:169], v[214:217], v[72:75]
	s_setprio 0
	s_setprio 1
	v_mfma_f32_16x16x32_bf16 v[116:119], v[170:173], v[186:189], v[116:119]
	v_mfma_f32_16x16x32_bf16 v[112:115], v[178:181], v[186:189], v[112:115]
	v_mfma_f32_16x16x32_bf16 v[100:103], v[170:173], v[194:197], v[100:103]
	v_mfma_f32_16x16x32_bf16 v[96:99], v[178:181], v[194:197], v[96:99]
	v_mfma_f32_16x16x32_bf16 v[84:87], v[170:173], v[202:205], v[84:87]
	v_mfma_f32_16x16x32_bf16 v[80:83], v[178:181], v[202:205], v[80:83]
	v_mfma_f32_16x16x32_bf16 v[68:71], v[170:173], v[210:213], v[68:71]
	v_mfma_f32_16x16x32_bf16 v[64:67], v[178:181], v[210:213], v[64:67]
	s_setprio 0
	s_setprio 1
	v_mfma_f32_16x16x32_bf16 v[116:119], v[174:177], v[190:193], v[116:119]
	v_mfma_f32_16x16x32_bf16 v[112:115], v[182:185], v[190:193], v[112:115]
	v_mfma_f32_16x16x32_bf16 v[100:103], v[174:177], v[198:201], v[100:103]
	v_mfma_f32_16x16x32_bf16 v[96:99], v[182:185], v[198:201], v[96:99]
	v_mfma_f32_16x16x32_bf16 v[84:87], v[174:177], v[206:209], v[84:87]
	v_mfma_f32_16x16x32_bf16 v[80:83], v[182:185], v[206:209], v[80:83]
	v_mfma_f32_16x16x32_bf16 v[68:71], v[174:177], v[214:217], v[68:71]
	v_mfma_f32_16x16x32_bf16 v[64:67], v[182:185], v[214:217], v[64:67]
	s_setprio 0
	s_barrier
	s_add_i32 s64, s55, s42
	v_lshl_add_u64 v[218:219], s[36:37], 0, v[130:131]
	s_mov_b32 m0, s64
	ds_read_b128 v[186:189], v155 offset:16384
	ds_read_b128 v[190:193], v155 offset:17408
	ds_read_b128 v[194:197], v155 offset:18432
	ds_read_b128 v[198:201], v155 offset:19456
	ds_read_b128 v[202:205], v155 offset:20480
	ds_read_b128 v[206:209], v155 offset:21504
	ds_read_b128 v[210:213], v155 offset:22528
	ds_read_b128 v[214:217], v155 offset:23552
	global_load_lds_dwordx4 v[218:219], off
	s_add_i32 m0, s64, 0x2000
	s_add_u32 s64, s36, 0x160000
	v_lshl_add_u64 v[220:221], s[36:37], 0, v[134:135]
	s_addc_u32 s65, s37, 0
	s_add_i32 s66, s56, s42
	global_load_lds_dwordx4 v[220:221], off
	v_lshl_add_u64 v[222:223], s[64:65], 0, v[130:131]
	s_mov_b32 m0, s66
	v_lshl_add_u64 v[224:225], s[38:39], 0, v[132:133]
	global_load_lds_dwordx4 v[222:223], off
	v_lshl_add_u64 v[222:223], s[64:65], 0, v[134:135]
	s_add_i32 m0, s66, 0x2000
	s_nop 0
	global_load_lds_dwordx4 v[222:223], off
	v_lshl_add_u64 v[222:223], s[38:39], 0, v[128:129]
	s_mov_b32 m0, s43
	s_nop 0
	global_load_lds_dwordx4 v[222:223], off
	s_mov_b32 m0, s44
	s_nop 0
	global_load_lds_dwordx4 v[224:225], off
	s_waitcnt vmcnt(8)
	s_waitcnt lgkmcnt(0)
	s_barrier
; #define PG8_STAGE(bufoff, gbase, voff) do { _Pragma("unroll") for (int _i = 0; _i < 2; ++_i) \
;         __builtin_amdgcn_global_load_lds((const unsigned*)((const char*)(gbase) + (voff)[_i]), (PG8_LAS unsigned*)(lds + (bufoff) + ldsw + _i * 8192), 16, 0, 0); } while (0)
; #define PG8_LDA(dst, b, h) do { _Pragma("unroll") for (int m = 0; m < 4; ++m) _Pragma("unroll") for (int k = 0; k < 2; ++k) dst[m][k] = *(const PG8_LAS bf16x8*)(lds + PG8_SA(b, h) + aoff + m * 2048 + k * 1024); } while (0)
; #define PG8_LDB(dst, b, h) do { _Pragma("unroll") for (int n = 0; n < 2; ++n) _Pragma("unroll") for (int k = 0; k < 2; ++k) dst[n][k] = *(const PG8_LAS bf16x8*)(lds + PG8_SB(b, h) + boff + n * 2048 + k * 1024); } while (0)
; #define PG8_MMA(ai, bj, At, Bt) do { __builtin_amdgcn_s_setprio(1); _Pragma("unroll") for (int m = 0; m < 4; ++m) _Pragma("unroll") for (int n = 0; n < 2; ++n) _Pragma("unroll") for (int k = 0; k < 2; ++k) \
;         acc[ai][bj][m][n] = __builtin_amdgcn_mfma_f32_16x16x32_bf16(Bt[n][k], At[m][k], acc[ai][bj][m][n], 0, 0, 0); __builtin_amdgcn_s_setprio(0); } while (0)
; #define PG8_WAIT_V(n) asm volatile("s_waitcnt vmcnt(" #n ")" ::: "memory")
; #define PG8_WAIT_L(n) asm volatile("s_waitcnt lgkmcnt(" #n ")" ::: "memory")
; #define PG8_BAR __builtin_amdgcn_s_barrier()
; #define PG8_SCHED __builtin_amdgcn_sched_barrier(0)
; template <class Epi, class Sched, bool ALIGN_EPI = false, bool SP2 = false>
; __device__ __forceinline__ void gemm_phase(PG8_LAS unsigned char* lds, const Gemm g, const Sched& S, const Epi& E) {
;     ...
;             PG8_WAIT_V(8); PG8_WAIT_L(0); PG8_BAR; PG8_MMA(1, 0, At, B0); PG8_MMA(1, 1, At, B1); PG8_BAR; PG8_SCHED;
;             PG8_LDB(B0, 1, 0); PG8_LDB(B1, 1, 1); PG8_SCHED; PG8_LDA(At, 1, 0); PG8_STAGE(PG8_SA(0, 1), a2 + hstep, voffA);
;             PG8_WAIT_V(8); PG8_WAIT_L(0); PG8_BAR; PG8_MMA(0, 0, At, B0); PG8_MMA(0, 1, At, B1); PG8_BAR; PG8_SCHED;
	s_setprio 1
	s_waitcnt lgkmcnt(0)
	v_mfma_f32_16x16x32_bf16 v[60:63], v[146:149], v[186:189], v[60:63]
	v_mfma_f32_16x16x32_bf16 v[56:59], v[162:165], v[186:189], v[56:59]
	v_mfma_f32_16x16x32_bf16 v[44:47], v[146:149], v[194:197], v[44:47]
	v_mfma_f32_16x16x32_bf16 v[40:43], v[162:165], v[194:197], v[40:43]
	v_mfma_f32_16x16x32_bf16 v[28:31], v[146:149], v[202:205], v[28:31]
	v_mfma_f32_16x16x32_bf16 v[24:27], v[162:165], v[202:205], v[24:27]
	v_mfma_f32_16x16x32_bf16 v[12:15], v[146:149], v[210:213], v[12:15]
	v_mfma_f32_16x16x32_bf16 v[8:11], v[162:165], v[210:213], v[8:11]
	s_setprio 0
	s_setprio 1
	v_mfma_f32_16x16x32_bf16 v[60:63], v[158:161], v[190:193], v[60:63]
	v_mfma_f32_16x16x32_bf16 v[56:59], v[166:169], v[190:193], v[56:59]
	v_mfma_f32_16x16x32_bf16 v[44:47], v[158:161], v[198:201], v[44:47]
	v_mfma_f32_16x16x32_bf16 v[40:43], v[166:169], v[198:201], v[40:43]
	v_mfma_f32_16x16x32_bf16 v[28:31], v[158:161], v[206:209], v[28:31]
	v_mfma_f32_16x16x32_bf16 v[24:27], v[166:169], v[206:209], v[24:27]
	v_mfma_f32_16x16x32_bf16 v[12:15], v[158:161], v[214:217], v[12:15]
	v_mfma_f32_16x16x32_bf16 v[8:11], v[166:169], v[214:217], v[8:11]
	s_setprio 0
	s_setprio 1
	v_mfma_f32_16x16x32_bf16 v[52:55], v[170:173], v[186:189], v[52:55]
	v_mfma_f32_16x16x32_bf16 v[48:51], v[178:181], v[186:189], v[48:51]
	v_mfma_f32_16x16x32_bf16 v[36:39], v[170:173], v[194:197], v[36:39]
	v_mfma_f32_16x16x32_bf16 v[32:35], v[178:181], v[194:197], v[32:35]
	v_mfma_f32_16x16x32_bf16 v[20:23], v[170:173], v[202:205], v[20:23]
	v_mfma_f32_16x16x32_bf16 v[16:19], v[178:181], v[202:205], v[16:19]
	v_mfma_f32_16x16x32_bf16 v[4:7], v[170:173], v[210:213], v[4:7]
	v_mfma_f32_16x16x32_bf16 v[0:3], v[178:181], v[210:213], v[0:3]
	s_setprio 0
	s_setprio 1
	v_mfma_f32_16x16x32_bf16 v[52:55], v[174:177], v[190:193], v[52:55]
	v_mfma_f32_16x16x32_bf16 v[48:51], v[182:185], v[190:193], v[48:51]
	v_mfma_f32_16x16x32_bf16 v[36:39], v[174:177], v[198:201], v[36:39]
	v_mfma_f32_16x16x32_bf16 v[32:35], v[182:185], v[198:201], v[32:35]
	v_mfma_f32_16x16x32_bf16 v[20:23], v[174:177], v[206:209], v[20:23]
	v_mfma_f32_16x16x32_bf16 v[16:19], v[182:185], v[206:209], v[16:19]
	v_mfma_f32_16x16x32_bf16 v[4:7], v[174:177], v[214:217], v[4:7]
	v_mfma_f32_16x16x32_bf16 v[0:3], v[182:185], v[214:217], v[0:3]
	s_setprio 0
	s_barrier
	s_add_i32 s64, 0, 0x18000
	v_add_u32_e32 v157, s64, v152
	s_add_i32 s65, 0, 0x1c000
	ds_read_b128 v[146:149], v157
	ds_read_b128 v[158:161], v157 offset:1024
	ds_read_b128 v[162:165], v157 offset:2048
	ds_read_b128 v[166:169], v157 offset:3072
	v_add_u32_e32 v157, s65, v152
	ds_read_b128 v[170:173], v157
	ds_read_b128 v[174:177], v157 offset:1024
	ds_read_b128 v[178:181], v157 offset:2048
	ds_read_b128 v[182:185], v157 offset:3072
	s_add_u32 s38, s38, 0x160000
	s_addc_u32 s39, s39, 0
	s_mov_b32 m0, s45
	v_lshl_add_u64 v[226:227], s[38:39], 0, v[128:129]
	ds_read_b128 v[186:189], v155 offset:32768
	ds_read_b128 v[190:193], v155 offset:33792
	ds_read_b128 v[194:197], v155 offset:34816
	ds_read_b128 v[198:201], v155 offset:35840
	ds_read_b128 v[202:205], v155 offset:36864
	ds_read_b128 v[206:209], v155 offset:37888
	ds_read_b128 v[210:213], v155 offset:38912
	ds_read_b128 v[214:217], v155 offset:39936
	global_load_lds_dwordx4 v[226:227], off
	v_lshl_add_u64 v[226:227], s[38:39], 0, v[132:133]
	s_mov_b32 m0, s46
	s_nop 0
	global_load_lds_dwordx4 v[226:227], off
	s_waitcnt vmcnt(8)
	s_waitcnt lgkmcnt(0)
	s_barrier
	s_setprio 1
	s_waitcnt lgkmcnt(0)
	v_mfma_f32_16x16x32_bf16 v[124:127], v[146:149], v[186:189], v[124:127]
	v_mfma_f32_16x16x32_bf16 v[120:123], v[162:165], v[186:189], v[120:123]
	v_mfma_f32_16x16x32_bf16 v[108:111], v[146:149], v[194:197], v[108:111]
	v_mfma_f32_16x16x32_bf16 v[104:107], v[162:165], v[194:197], v[104:107]
	v_mfma_f32_16x16x32_bf16 v[92:95], v[146:149], v[202:205], v[92:95]
	v_mfma_f32_16x16x32_bf16 v[88:91], v[162:165], v[202:205], v[88:91]
	v_mfma_f32_16x16x32_bf16 v[76:79], v[146:149], v[210:213], v[76:79]
	v_mfma_f32_16x16x32_bf16 v[72:75], v[162:165], v[210:213], v[72:75]
	s_setprio 0
	s_setprio 1
	v_mfma_f32_16x16x32_bf16 v[124:127], v[158:161], v[190:193], v[124:127]
	v_mfma_f32_16x16x32_bf16 v[120:123], v[166:169], v[190:193], v[120:123]
	v_mfma_f32_16x16x32_bf16 v[108:111], v[158:161], v[198:201], v[108:111]
	v_mfma_f32_16x16x32_bf16 v[104:107], v[166:169], v[198:201], v[104:107]
	v_mfma_f32_16x16x32_bf16 v[92:95], v[158:161], v[206:209], v[92:95]
	v_mfma_f32_16x16x32_bf16 v[88:91], v[166:169], v[206:209], v[88:91]
	v_mfma_f32_16x16x32_bf16 v[76:79], v[158:161], v[214:217], v[76:79]
	v_mfma_f32_16x16x32_bf16 v[72:75], v[166:169], v[214:217], v[72:75]
	s_setprio 0
	s_setprio 1
	v_mfma_f32_16x16x32_bf16 v[116:119], v[170:173], v[186:189], v[116:119]
	v_mfma_f32_16x16x32_bf16 v[112:115], v[178:181], v[186:189], v[112:115]
	v_mfma_f32_16x16x32_bf16 v[100:103], v[170:173], v[194:197], v[100:103]
	v_mfma_f32_16x16x32_bf16 v[96:99], v[178:181], v[194:197], v[96:99]
	v_mfma_f32_16x16x32_bf16 v[84:87], v[170:173], v[202:205], v[84:87]
	v_mfma_f32_16x16x32_bf16 v[80:83], v[178:181], v[202:205], v[80:83]
	v_mfma_f32_16x16x32_bf16 v[68:71], v[170:173], v[210:213], v[68:71]
	v_mfma_f32_16x16x32_bf16 v[64:67], v[178:181], v[210:213], v[64:67]
	s_setprio 0
	s_setprio 1
	v_mfma_f32_16x16x32_bf16 v[116:119], v[174:177], v[190:193], v[116:119]
	v_mfma_f32_16x16x32_bf16 v[112:115], v[182:185], v[190:193], v[112:115]
	v_mfma_f32_16x16x32_bf16 v[100:103], v[174:177], v[198:201], v[100:103]
	v_mfma_f32_16x16x32_bf16 v[96:99], v[182:185], v[198:201], v[96:99]
	v_mfma_f32_16x16x32_bf16 v[84:87], v[174:177], v[206:209], v[84:87]
	v_mfma_f32_16x16x32_bf16 v[80:83], v[182:185], v[206:209], v[80:83]
	v_mfma_f32_16x16x32_bf16 v[68:71], v[174:177], v[214:217], v[68:71]
	v_mfma_f32_16x16x32_bf16 v[64:67], v[182:185], v[214:217], v[64:67]
	s_setprio 0
	s_barrier
; #define PG8_STAGE(bufoff, gbase, voff) do { _Pragma("unroll") for (int _i = 0; _i < 2; ++_i) \
;         __builtin_amdgcn_global_load_lds((const unsigned*)((const char*)(gbase) + (voff)[_i]), (PG8_LAS unsigned*)(lds + (bufoff) + ldsw + _i * 8192), 16, 0, 0); } while (0)
; #define PG8_LDA(dst, b, h) do { _Pragma("unroll") for (int m = 0; m < 4; ++m) _Pragma("unroll") for (int k = 0; k < 2; ++k) dst[m][k] = *(const PG8_LAS bf16x8*)(lds + PG8_SA(b, h) + aoff + m * 2048 + k * 1024); } while (0)
; #define PG8_MMA(ai, bj, At, Bt) do { __builtin_amdgcn_s_setprio(1); _Pragma("unroll") for (int m = 0; m < 4; ++m) _Pragma("unroll") for (int n = 0; n < 2; ++n) _Pragma("unroll") for (int k = 0; k < 2; ++k) \
;         acc[ai][bj][m][n] = __builtin_amdgcn_mfma_f32_16x16x32_bf16(Bt[n][k], At[m][k], acc[ai][bj][m][n], 0, 0, 0); __builtin_amdgcn_s_setprio(0); } while (0)
; #define PG8_WAIT_V(n) asm volatile("s_waitcnt vmcnt(" #n ")" ::: "memory")
; #define PG8_WAIT_L(n) asm volatile("s_waitcnt lgkmcnt(" #n ")" ::: "memory")
; #define PG8_BAR __builtin_amdgcn_s_barrier()
; #define PG8_SCHED __builtin_amdgcn_sched_barrier(0)
; template <class Epi, class Sched, bool ALIGN_EPI = false, bool SP2 = false>
; __device__ __forceinline__ void gemm_phase(PG8_LAS unsigned char* lds, const Gemm g, const Sched& S, const Epi& E) {
;     ...
;             PG8_LDA(At, 1, 1); PG8_STAGE(PG8_SB(1, 0), b3, voffB); PG8_STAGE(PG8_SB(1, 1), b3 + hstep, voffB); PG8_STAGE(PG8_SA(1, 0), a3, voffA);
;             PG8_WAIT_V(8); PG8_WAIT_L(0); PG8_BAR; PG8_MMA(1, 0, At, B0); PG8_MMA(1, 1, At, B1); PG8_BAR; PG8_SCHED;
	s_add_i32 s38, s64, s42
	v_lshl_add_u64 v[218:219], v[218:219], 0, s[16:17]
	s_mov_b32 m0, s38
	ds_read_b128 v[186:189], v155 offset:49152
	ds_read_b128 v[190:193], v155 offset:50176
	ds_read_b128 v[194:197], v155 offset:51200
	ds_read_b128 v[198:201], v155 offset:52224
	ds_read_b128 v[202:205], v155 offset:53248
	ds_read_b128 v[206:209], v155 offset:54272
	ds_read_b128 v[210:213], v155 offset:55296
	ds_read_b128 v[214:217], v155 offset:56320
	global_load_lds_dwordx4 v[218:219], off
	s_add_i32 m0, s38, 0x2000
	s_add_u32 s36, s36, 0x160080
	v_lshl_add_u64 v[218:219], v[220:221], 0, s[16:17]
	s_addc_u32 s37, s37, 0
	s_add_i32 s38, s65, s42
	global_load_lds_dwordx4 v[218:219], off
	v_lshl_add_u64 v[218:219], s[36:37], 0, v[130:131]
	s_mov_b32 m0, s38
	s_nop 0
	global_load_lds_dwordx4 v[218:219], off
	v_lshl_add_u64 v[218:219], s[36:37], 0, v[134:135]
	s_add_i32 m0, s38, 0x2000
	s_nop 0
	global_load_lds_dwordx4 v[218:219], off
	v_lshl_add_u64 v[218:219], v[222:223], 0, s[16:17]
	s_mov_b32 m0, s52
	s_nop 0
	global_load_lds_dwordx4 v[218:219], off
	v_lshl_add_u64 v[218:219], v[224:225], 0, s[16:17]
	s_mov_b32 m0, s53
	s_nop 0
	global_load_lds_dwordx4 v[218:219], off
	s_waitcnt vmcnt(8)
	s_waitcnt lgkmcnt(0)
	s_barrier
	s_setprio 1
	s_waitcnt lgkmcnt(0)
	v_mfma_f32_16x16x32_bf16 v[60:63], v[146:149], v[186:189], v[60:63]
	v_mfma_f32_16x16x32_bf16 v[56:59], v[162:165], v[186:189], v[56:59]
	v_mfma_f32_16x16x32_bf16 v[44:47], v[146:149], v[194:197], v[44:47]
	v_mfma_f32_16x16x32_bf16 v[40:43], v[162:165], v[194:197], v[40:43]
	v_mfma_f32_16x16x32_bf16 v[28:31], v[146:149], v[202:205], v[28:31]
	v_mfma_f32_16x16x32_bf16 v[24:27], v[162:165], v[202:205], v[24:27]
	v_mfma_f32_16x16x32_bf16 v[12:15], v[146:149], v[210:213], v[12:15]
	v_mfma_f32_16x16x32_bf16 v[8:11], v[162:165], v[210:213], v[8:11]
	s_setprio 0
	s_setprio 1
	v_mfma_f32_16x16x32_bf16 v[60:63], v[158:161], v[190:193], v[60:63]
	v_mfma_f32_16x16x32_bf16 v[56:59], v[166:169], v[190:193], v[56:59]
	v_mfma_f32_16x16x32_bf16 v[44:47], v[158:161], v[198:201], v[44:47]
	v_mfma_f32_16x16x32_bf16 v[40:43], v[166:169], v[198:201], v[40:43]
	v_mfma_f32_16x16x32_bf16 v[28:31], v[158:161], v[206:209], v[28:31]
	v_mfma_f32_16x16x32_bf16 v[24:27], v[166:169], v[206:209], v[24:27]
	v_mfma_f32_16x16x32_bf16 v[12:15], v[158:161], v[214:217], v[12:15]
	v_mfma_f32_16x16x32_bf16 v[8:11], v[166:169], v[214:217], v[8:11]
	s_setprio 0
	s_setprio 1
	v_mfma_f32_16x16x32_bf16 v[52:55], v[170:173], v[186:189], v[52:55]
	v_mfma_f32_16x16x32_bf16 v[48:51], v[178:181], v[186:189], v[48:51]
	v_mfma_f32_16x16x32_bf16 v[36:39], v[170:173], v[194:197], v[36:39]
	v_mfma_f32_16x16x32_bf16 v[32:35], v[178:181], v[194:197], v[32:35]
	v_mfma_f32_16x16x32_bf16 v[20:23], v[170:173], v[202:205], v[20:23]
	v_mfma_f32_16x16x32_bf16 v[16:19], v[178:181], v[202:205], v[16:19]
	v_mfma_f32_16x16x32_bf16 v[4:7], v[170:173], v[210:213], v[4:7]
	v_mfma_f32_16x16x32_bf16 v[0:3], v[178:181], v[210:213], v[0:3]
	s_setprio 0
	s_setprio 1
	v_mfma_f32_16x16x32_bf16 v[52:55], v[174:177], v[190:193], v[52:55]
	v_mfma_f32_16x16x32_bf16 v[48:51], v[182:185], v[190:193], v[48:51]
	v_mfma_f32_16x16x32_bf16 v[36:39], v[174:177], v[198:201], v[36:39]
	v_mfma_f32_16x16x32_bf16 v[32:35], v[182:185], v[198:201], v[32:35]
	v_mfma_f32_16x16x32_bf16 v[20:23], v[174:177], v[206:209], v[20:23]
	v_mfma_f32_16x16x32_bf16 v[16:19], v[182:185], v[206:209], v[16:19]
	v_mfma_f32_16x16x32_bf16 v[4:7], v[174:177], v[214:217], v[4:7]
	v_mfma_f32_16x16x32_bf16 v[0:3], v[182:185], v[214:217], v[0:3]
	s_setprio 0
	s_barrier
	s_add_i32 s63, s63, 2
	s_add_u32 s22, s22, 0x100
	s_addc_u32 s23, s23, 0
	s_add_u32 s61, s61, 0x100
	s_addc_u32 s62, s62, 0
	s_cmpk_gt_u32 s63, 0x55
	s_cbranch_scc0 .LBB0_1924
	s_and_b64 vcc, exec, s[18:19]
	s_cbranch_vccz .LBB0_1927
	s_barrier
